# v009 + GEMM LDS-DMA loads via SGPR base + 32-bit VGPR offset (isolating this change)
# speedup vs baseline: 1.0004x; 1.0004x over previous
; #define PG8_STAGE(bufoff, gbase, voff) do { _Pragma("unroll") for (int _i = 0; _i < 2; ++_i) \
;         __builtin_amdgcn_global_load_lds((const gunsigned*)((const gchar*)(gbase) + (voff)[_i]), (LAS unsigned*)(lds + (bufoff) + ldsw + _i * 8192), 16, 0, 0); } while (0)
; #define PG8_LDA(dst, b, h) do { _Pragma("unroll") for (int m = 0; m < 4; ++m) _Pragma("unroll") for (int k = 0; k < 2; ++k) dst[m][k] = *(const LAS bf16x8*)(lds + PG8_SA(b, h) + aoff + m * 2048 + k * 1024); } while (0)
; #define PG8_LDB(dst, b, h) do { _Pragma("unroll") for (int n = 0; n < 2; ++n) _Pragma("unroll") for (int k = 0; k < 2; ++k) dst[n][k] = *(const LAS bf16x8*)(lds + PG8_SB(b, h) + boff + n * 2048 + k * 1024); } while (0)
; #define PG8_MMA(ai, bj, At, Bt) do { __builtin_amdgcn_s_setprio(1); _Pragma("unroll") for (int m = 0; m < 4; ++m) _Pragma("unroll") for (int n = 0; n < 2; ++n) _Pragma("unroll") for (int k = 0; k < 2; ++k) \
;         acc[ai][bj][m][n] = __builtin_amdgcn_mfma_f32_16x16x32_bf16(Bt[n][k], At[m][k], acc[ai][bj][m][n], 0, 0, 0); __builtin_amdgcn_s_setprio(0); } while (0)
; #define PG8_WAIT_V(n) asm volatile("s_waitcnt vmcnt(" #n ")" ::: "memory")
; #define PG8_WAIT_L(n) asm volatile("s_waitcnt lgkmcnt(" #n ")" ::: "memory")
; #define PG8_BAR __builtin_amdgcn_s_barrier()
; template <class Epi, class Sched>
; __device__ __forceinline__ void gemm_phase(LAS unsigned char* lds, const int tid, const Gemm g, const Sched& S, const Epi& E) {
;     ...
;         for (int t = 0; t < nt; t += 2) {
;             const bool last = (t == nt - 2);
;             const gchar* a1 = cA + (size_t)(t + 1) * kstep;
;             const gchar* a2 = last ? nA : cA + (size_t)(t + 2) * kstep; const gchar* b2 = last ? nB : cB + (size_t)(t + 2) * kstep;
;             const gchar* a3 = a2 + kstep; const gchar* b3 = b2 + kstep;
;             PG8_LDB(B0, 0, 0); PG8_LDB(B1, 0, 1); PG8_SCHED; PG8_LDA(At, 0, 0); PG8_STAGE(PG8_SA(1, 1), a1 + hstep, voffA);
;             PG8_WAIT_V(8); PG8_WAIT_L(0); PG8_BAR; PG8_MMA(0, 0, At, B0); PG8_MMA(0, 1, At, B1); PG8_BAR; PG8_SCHED;
;     ...
; #pragma unroll
;         for (int a = 0; a < 2; ++a)
; #pragma unroll
;             for (int b = 0; b < 2; ++b)
; #pragma unroll
;                 for (int m = 0; m < 4; ++m)
; #pragma unroll
;                     for (int n = 0; n < 2; ++n) acc[a][b][m][n] = (f32x4){0.f, 0.f, 0.f, 0.f};
;         cur = nxt; cA = nA; cB = nB; ++ui;
.LBB0_318:
	s_add_u32 s31, s72, 0x100
	v_mov_b32_e32 v2, 0
	s_addc_u32 s93, s73, 0
	s_mov_b32 s29, -2
	v_mov_b32_e32 v3, v2
	v_mov_b32_e32 v4, v2
	v_mov_b32_e32 v5, v2
	v_mov_b32_e32 v6, v2
	v_mov_b32_e32 v7, v2
	v_mov_b32_e32 v8, v2
	v_mov_b32_e32 v9, v2
	v_mov_b32_e32 v18, v2
	v_mov_b32_e32 v19, v2
	v_mov_b32_e32 v20, v2
	v_mov_b32_e32 v21, v2
	v_mov_b32_e32 v22, v2
	v_mov_b32_e32 v23, v2
	v_mov_b32_e32 v24, v2
	v_mov_b32_e32 v25, v2
	v_mov_b32_e32 v34, v2
	v_mov_b32_e32 v35, v2
	v_mov_b32_e32 v36, v2
	v_mov_b32_e32 v37, v2
	v_mov_b32_e32 v38, v2
	v_mov_b32_e32 v39, v2
	v_mov_b32_e32 v40, v2
	v_mov_b32_e32 v41, v2
	v_mov_b32_e32 v50, v2
	v_mov_b32_e32 v51, v2
	v_mov_b32_e32 v52, v2
	v_mov_b32_e32 v53, v2
	v_mov_b32_e32 v54, v2
	v_mov_b32_e32 v55, v2
	v_mov_b32_e32 v56, v2
	v_mov_b32_e32 v57, v2
	v_mov_b32_e32 v10, v2
	v_mov_b32_e32 v11, v2
	v_mov_b32_e32 v12, v2
	v_mov_b32_e32 v13, v2
	v_mov_b32_e32 v14, v2
	v_mov_b32_e32 v15, v2
	v_mov_b32_e32 v16, v2
	v_mov_b32_e32 v17, v2
	v_mov_b32_e32 v26, v2
	v_mov_b32_e32 v27, v2
	v_mov_b32_e32 v28, v2
	v_mov_b32_e32 v29, v2
	v_mov_b32_e32 v30, v2
	v_mov_b32_e32 v31, v2
	v_mov_b32_e32 v32, v2
	v_mov_b32_e32 v33, v2
	v_mov_b32_e32 v42, v2
	v_mov_b32_e32 v43, v2
	v_mov_b32_e32 v44, v2
	v_mov_b32_e32 v45, v2
	v_mov_b32_e32 v46, v2
	v_mov_b32_e32 v47, v2
	v_mov_b32_e32 v48, v2
	v_mov_b32_e32 v49, v2
	v_mov_b32_e32 v58, v2
	v_mov_b32_e32 v59, v2
	v_mov_b32_e32 v60, v2
	v_mov_b32_e32 v61, v2
	v_mov_b32_e32 v62, v2
	v_mov_b32_e32 v63, v2
	v_mov_b32_e32 v64, v2
	v_mov_b32_e32 v65, v2
	v_mov_b32_e32 v66, v2
	v_mov_b32_e32 v67, v2
	v_mov_b32_e32 v68, v2
	v_mov_b32_e32 v69, v2
	v_mov_b32_e32 v70, v2
	v_mov_b32_e32 v71, v2
	v_mov_b32_e32 v72, v2
	v_mov_b32_e32 v73, v2
	s_waitcnt vmcnt(0)
	v_mov_b32_e32 v82, v2
	v_mov_b32_e32 v83, v2
	v_mov_b32_e32 v84, v2
	v_mov_b32_e32 v85, v2
	v_mov_b32_e32 v86, v2
	v_mov_b32_e32 v87, v2
	v_mov_b32_e32 v88, v2
	v_mov_b32_e32 v89, v2
	v_mov_b32_e32 v98, v2
	v_mov_b32_e32 v99, v2
	v_mov_b32_e32 v100, v2
	v_mov_b32_e32 v101, v2
	v_mov_b32_e32 v102, v2
	v_mov_b32_e32 v103, v2
	v_mov_b32_e32 v104, v2
	v_mov_b32_e32 v105, v2
	v_mov_b32_e32 v114, v2
	v_mov_b32_e32 v115, v2
	v_mov_b32_e32 v116, v2
	v_mov_b32_e32 v117, v2
	v_mov_b32_e32 v118, v2
	v_mov_b32_e32 v119, v2
	v_mov_b32_e32 v120, v2
	v_mov_b32_e32 v121, v2
	v_mov_b32_e32 v74, v2
	v_mov_b32_e32 v75, v2
	v_mov_b32_e32 v76, v2
	v_mov_b32_e32 v77, v2
	v_mov_b32_e32 v78, v2
	v_mov_b32_e32 v79, v2
	v_mov_b32_e32 v80, v2
	v_mov_b32_e32 v81, v2
	v_mov_b32_e32 v90, v2
	v_mov_b32_e32 v91, v2
	v_mov_b32_e32 v92, v2
	v_mov_b32_e32 v93, v2
	v_mov_b32_e32 v94, v2
	v_mov_b32_e32 v95, v2
	v_mov_b32_e32 v96, v2
	v_mov_b32_e32 v97, v2
	v_mov_b32_e32 v106, v2
	v_mov_b32_e32 v107, v2
	v_mov_b32_e32 v108, v2
	v_mov_b32_e32 v109, v2
	v_mov_b32_e32 v110, v2
	v_mov_b32_e32 v111, v2
	v_mov_b32_e32 v112, v2
	v_mov_b32_e32 v113, v2
	v_mov_b32_e32 v122, v2
	v_mov_b32_e32 v123, v2
	v_mov_b32_e32 v124, v2
	v_mov_b32_e32 v125, v2
	v_mov_b32_e32 v126, v2
	v_mov_b32_e32 v127, v2
	v_mov_b32_e32 v128, v2
	v_mov_b32_e32 v129, v2
	v_add_u32_e32 v201, 0x80, v0
	v_add_u32_e32 v247, 0x80, v158
	v_add_u32_e32 v249, 0x80, v154
	v_add_u32_e32 v251, 0x80, v156
.LBB0_319:
	s_add_u32 vcc_lo, s10, 0x100
	s_addc_u32 vcc_hi, s11, 0
	s_add_i32 s39, 0, 0x10000
	s_cmp_eq_u32 s29, 40
	s_cselect_b32 s75, s21, vcc_hi
	s_cselect_b32 s74, s20, vcc_lo
	s_cselect_b32 s73, s1, s93
	s_cselect_b32 s72, s0, s31
	s_add_i32 s30, 0, 0x14000
	v_add_u32_e32 v142, s39, v174
	v_add_u32_e32 v168, s30, v174
	ds_read_b128 v[130:133], v142
	ds_read_b128 v[134:137], v142 offset:1024
	ds_read_b128 v[138:141], v142 offset:2048
	ds_read_b128 v[142:145], v142 offset:3072
	ds_read_b128 v[146:149], v168
	ds_read_b128 v[150:153], v168 offset:1024
	ds_read_b128 v[164:167], v168 offset:2048
	ds_read_b128 v[168:171], v168 offset:3072
	s_add_i32 m0, s46, 0xc000
	ds_read_b128 v[192:195], v190
	ds_read_b128 v[204:207], v190 offset:1024
	ds_read_b128 v[208:211], v190 offset:2048
	ds_read_b128 v[212:215], v190 offset:3072
	ds_read_b128 v[216:219], v190 offset:4096
	ds_read_b128 v[220:223], v190 offset:5120
	ds_read_b128 v[224:227], v190 offset:6144
	ds_read_b128 v[242:245], v190 offset:7168
	global_load_lds_dwordx4 v162, s[10:11]
	s_add_i32 m0, s46, 0xe000
	s_nop 0
	global_load_lds_dwordx4 v160, s[10:11]
	s_waitcnt vmcnt(8)
	s_waitcnt lgkmcnt(0)
	s_barrier
	s_setprio 1
	s_waitcnt lgkmcnt(0)
	v_mfma_f32_16x16x32_bf16 v[126:129], v[130:133], v[192:195], v[126:129]
	v_mfma_f32_16x16x32_bf16 v[122:125], v[138:141], v[192:195], v[122:125]
	v_mfma_f32_16x16x32_bf16 v[110:113], v[130:133], v[208:211], v[110:113]
	v_mfma_f32_16x16x32_bf16 v[106:109], v[138:141], v[208:211], v[106:109]
	v_mfma_f32_16x16x32_bf16 v[94:97], v[130:133], v[216:219], v[94:97]
	v_mfma_f32_16x16x32_bf16 v[90:93], v[138:141], v[216:219], v[90:93]
	v_mfma_f32_16x16x32_bf16 v[78:81], v[130:133], v[224:227], v[78:81]
	v_mfma_f32_16x16x32_bf16 v[74:77], v[138:141], v[224:227], v[74:77]
	v_mfma_f32_16x16x32_bf16 v[126:129], v[134:137], v[204:207], v[126:129]
	v_mfma_f32_16x16x32_bf16 v[122:125], v[142:145], v[204:207], v[122:125]
	v_mfma_f32_16x16x32_bf16 v[110:113], v[134:137], v[212:215], v[110:113]
	v_mfma_f32_16x16x32_bf16 v[106:109], v[142:145], v[212:215], v[106:109]
	v_mfma_f32_16x16x32_bf16 v[94:97], v[134:137], v[220:223], v[94:97]
	v_mfma_f32_16x16x32_bf16 v[90:93], v[142:145], v[220:223], v[90:93]
	v_mfma_f32_16x16x32_bf16 v[78:81], v[134:137], v[242:245], v[78:81]
	v_mfma_f32_16x16x32_bf16 v[74:77], v[142:145], v[242:245], v[74:77]
	s_setprio 0
	s_setprio 1
	v_mfma_f32_16x16x32_bf16 v[118:121], v[146:149], v[192:195], v[118:121]
	v_mfma_f32_16x16x32_bf16 v[114:117], v[164:167], v[192:195], v[114:117]
	v_mfma_f32_16x16x32_bf16 v[102:105], v[146:149], v[208:211], v[102:105]
	v_mfma_f32_16x16x32_bf16 v[98:101], v[164:167], v[208:211], v[98:101]
	v_mfma_f32_16x16x32_bf16 v[86:89], v[146:149], v[216:219], v[86:89]
	v_mfma_f32_16x16x32_bf16 v[82:85], v[164:167], v[216:219], v[82:85]
	v_mfma_f32_16x16x32_bf16 v[70:73], v[146:149], v[224:227], v[70:73]
	v_mfma_f32_16x16x32_bf16 v[66:69], v[164:167], v[224:227], v[66:69]
	v_mfma_f32_16x16x32_bf16 v[118:121], v[150:153], v[204:207], v[118:121]
	v_mfma_f32_16x16x32_bf16 v[114:117], v[168:171], v[204:207], v[114:117]
	v_mfma_f32_16x16x32_bf16 v[102:105], v[150:153], v[212:215], v[102:105]
	v_mfma_f32_16x16x32_bf16 v[98:101], v[168:171], v[212:215], v[98:101]
	v_mfma_f32_16x16x32_bf16 v[86:89], v[150:153], v[220:223], v[86:89]
	v_mfma_f32_16x16x32_bf16 v[82:85], v[168:171], v[220:223], v[82:85]
	v_mfma_f32_16x16x32_bf16 v[70:73], v[150:153], v[242:245], v[70:73]
	v_mfma_f32_16x16x32_bf16 v[66:69], v[168:171], v[242:245], v[66:69]
	s_setprio 0
	s_barrier
; #define PG8_STAGE(bufoff, gbase, voff) do { _Pragma("unroll") for (int _i = 0; _i < 2; ++_i) \
;         __builtin_amdgcn_global_load_lds((const gunsigned*)((const gchar*)(gbase) + (voff)[_i]), (LAS unsigned*)(lds + (bufoff) + ldsw + _i * 8192), 16, 0, 0); } while (0)
; #define PG8_LDA(dst, b, h) do { _Pragma("unroll") for (int m = 0; m < 4; ++m) _Pragma("unroll") for (int k = 0; k < 2; ++k) dst[m][k] = *(const LAS bf16x8*)(lds + PG8_SA(b, h) + aoff + m * 2048 + k * 1024); } while (0)
; #define PG8_LDB(dst, b, h) do { _Pragma("unroll") for (int n = 0; n < 2; ++n) _Pragma("unroll") for (int k = 0; k < 2; ++k) dst[n][k] = *(const LAS bf16x8*)(lds + PG8_SB(b, h) + boff + n * 2048 + k * 1024); } while (0)
; #define PG8_MMA(ai, bj, At, Bt) do { __builtin_amdgcn_s_setprio(1); _Pragma("unroll") for (int m = 0; m < 4; ++m) _Pragma("unroll") for (int n = 0; n < 2; ++n) _Pragma("unroll") for (int k = 0; k < 2; ++k) \
;         acc[ai][bj][m][n] = __builtin_amdgcn_mfma_f32_16x16x32_bf16(Bt[n][k], At[m][k], acc[ai][bj][m][n], 0, 0, 0); __builtin_amdgcn_s_setprio(0); } while (0)
; #define PG8_WAIT_V(n) asm volatile("s_waitcnt vmcnt(" #n ")" ::: "memory")
; #define PG8_WAIT_L(n) asm volatile("s_waitcnt lgkmcnt(" #n ")" ::: "memory")
; #define PG8_BAR __builtin_amdgcn_s_barrier()
; #define PG8_SCHED __builtin_amdgcn_sched_barrier(0)
; template <class Epi, class Sched>
; __device__ __forceinline__ void gemm_phase(LAS unsigned char* lds, const int tid, const Gemm g, const Sched& S, const Epi& E) {
;     ...
;             PG8_LDA(At, 0, 1); PG8_STAGE(PG8_SB(0, 0), b2, voffB); PG8_STAGE(PG8_SB(0, 1), b2 + hstep, voffB); PG8_STAGE(PG8_SA(0, 0), a2, voffA);
;             PG8_WAIT_V(8); PG8_WAIT_L(0); PG8_BAR; PG8_MMA(1, 0, At, B0); PG8_MMA(1, 1, At, B1); PG8_BAR; PG8_SCHED;
;             PG8_LDB(B0, 1, 0); PG8_LDB(B1, 1, 1); PG8_SCHED; PG8_LDA(At, 1, 0); PG8_STAGE(PG8_SA(0, 1), a2 + hstep, voffA);
;             PG8_WAIT_V(8); PG8_WAIT_L(0); PG8_BAR; PG8_MMA(0, 0, At, B0); PG8_MMA(0, 1, At, B1); PG8_BAR; PG8_SCHED;
;             PG8_LDA(At, 1, 1); PG8_STAGE(PG8_SB(1, 0), b3, voffB); PG8_STAGE(PG8_SB(1, 1), b3 + hstep, voffB); PG8_STAGE(PG8_SA(1, 0), a3, voffA);
	s_add_i32 s10, s39, s43
	s_mov_b32 m0, s10
	ds_read_b128 v[192:195], v190 offset:16384
	ds_read_b128 v[204:207], v190 offset:17408
	ds_read_b128 v[208:211], v190 offset:18432
	ds_read_b128 v[212:215], v190 offset:19456
	ds_read_b128 v[216:219], v190 offset:20480
	ds_read_b128 v[220:223], v190 offset:21504
	ds_read_b128 v[224:227], v190 offset:22528
	ds_read_b128 v[242:245], v190 offset:23552
	global_load_lds_dwordx4 v0, s[72:73]
	s_add_i32 m0, s10, 0x2000
	s_add_u32 s10, s72, 0xb0000
	s_addc_u32 s11, s73, 0
	s_add_i32 s30, s30, s43
	global_load_lds_dwordx4 v158, s[72:73]
	s_mov_b32 m0, s30
	s_nop 0
	global_load_lds_dwordx4 v0, s[10:11]
	s_add_i32 m0, s30, 0x2000
	s_nop 0
	global_load_lds_dwordx4 v158, s[10:11]
	s_mov_b32 m0, s46
	s_nop 0
	global_load_lds_dwordx4 v154, s[74:75]
	s_mov_b32 m0, s47
	s_nop 0
	global_load_lds_dwordx4 v156, s[74:75]
	s_waitcnt vmcnt(8)
	s_waitcnt lgkmcnt(0)
	s_barrier
	s_setprio 1
	s_waitcnt lgkmcnt(0)
	v_mfma_f32_16x16x32_bf16 v[62:65], v[130:133], v[192:195], v[62:65]
	v_mfma_f32_16x16x32_bf16 v[58:61], v[138:141], v[192:195], v[58:61]
	v_mfma_f32_16x16x32_bf16 v[46:49], v[130:133], v[208:211], v[46:49]
	v_mfma_f32_16x16x32_bf16 v[42:45], v[138:141], v[208:211], v[42:45]
	v_mfma_f32_16x16x32_bf16 v[30:33], v[130:133], v[216:219], v[30:33]
	v_mfma_f32_16x16x32_bf16 v[26:29], v[138:141], v[216:219], v[26:29]
	v_mfma_f32_16x16x32_bf16 v[14:17], v[130:133], v[224:227], v[14:17]
	v_mfma_f32_16x16x32_bf16 v[10:13], v[138:141], v[224:227], v[10:13]
	v_mfma_f32_16x16x32_bf16 v[62:65], v[134:137], v[204:207], v[62:65]
	v_mfma_f32_16x16x32_bf16 v[58:61], v[142:145], v[204:207], v[58:61]
	v_mfma_f32_16x16x32_bf16 v[46:49], v[134:137], v[212:215], v[46:49]
	v_mfma_f32_16x16x32_bf16 v[42:45], v[142:145], v[212:215], v[42:45]
	v_mfma_f32_16x16x32_bf16 v[30:33], v[134:137], v[220:223], v[30:33]
	v_mfma_f32_16x16x32_bf16 v[26:29], v[142:145], v[220:223], v[26:29]
	v_mfma_f32_16x16x32_bf16 v[14:17], v[134:137], v[242:245], v[14:17]
	v_mfma_f32_16x16x32_bf16 v[10:13], v[142:145], v[242:245], v[10:13]
	s_setprio 0
	s_setprio 1
	v_mfma_f32_16x16x32_bf16 v[54:57], v[146:149], v[192:195], v[54:57]
	v_mfma_f32_16x16x32_bf16 v[50:53], v[164:167], v[192:195], v[50:53]
	v_mfma_f32_16x16x32_bf16 v[38:41], v[146:149], v[208:211], v[38:41]
	v_mfma_f32_16x16x32_bf16 v[34:37], v[164:167], v[208:211], v[34:37]
	v_mfma_f32_16x16x32_bf16 v[22:25], v[146:149], v[216:219], v[22:25]
	v_mfma_f32_16x16x32_bf16 v[18:21], v[164:167], v[216:219], v[18:21]
	v_mfma_f32_16x16x32_bf16 v[6:9], v[146:149], v[224:227], v[6:9]
	v_mfma_f32_16x16x32_bf16 v[2:5], v[164:167], v[224:227], v[2:5]
	v_mfma_f32_16x16x32_bf16 v[54:57], v[150:153], v[204:207], v[54:57]
	v_mfma_f32_16x16x32_bf16 v[50:53], v[168:171], v[204:207], v[50:53]
	v_mfma_f32_16x16x32_bf16 v[38:41], v[150:153], v[212:215], v[38:41]
	v_mfma_f32_16x16x32_bf16 v[34:37], v[168:171], v[212:215], v[34:37]
	v_mfma_f32_16x16x32_bf16 v[22:25], v[150:153], v[220:223], v[22:25]
	v_mfma_f32_16x16x32_bf16 v[18:21], v[168:171], v[220:223], v[18:21]
	v_mfma_f32_16x16x32_bf16 v[6:9], v[150:153], v[242:245], v[6:9]
	v_mfma_f32_16x16x32_bf16 v[2:5], v[168:171], v[242:245], v[2:5]
	s_setprio 0
	s_barrier
	s_add_i32 s30, 0, 0x18000
	s_add_i32 s39, 0, 0x1c000
	v_add_u32_e32 v142, s30, v174
	v_add_u32_e32 v168, s39, v174
	ds_read_b128 v[130:133], v142
	ds_read_b128 v[134:137], v142 offset:1024
	ds_read_b128 v[138:141], v142 offset:2048
	ds_read_b128 v[142:145], v142 offset:3072
	ds_read_b128 v[146:149], v168
	ds_read_b128 v[150:153], v168 offset:1024
	ds_read_b128 v[164:167], v168 offset:2048
	ds_read_b128 v[168:171], v168 offset:3072
	s_add_u32 s10, s74, 0xb0000
	s_addc_u32 s11, s75, 0
	s_mov_b32 m0, s48
	ds_read_b128 v[192:195], v190 offset:32768
	ds_read_b128 v[204:207], v190 offset:33792
	ds_read_b128 v[208:211], v190 offset:34816
	ds_read_b128 v[212:215], v190 offset:35840
	ds_read_b128 v[216:219], v190 offset:36864
	ds_read_b128 v[220:223], v190 offset:37888
	ds_read_b128 v[224:227], v190 offset:38912
	ds_read_b128 v[242:245], v190 offset:39936
	global_load_lds_dwordx4 v154, s[10:11]
	s_mov_b32 m0, s49
	s_nop 0
	global_load_lds_dwordx4 v156, s[10:11]
	s_waitcnt vmcnt(8)
	s_waitcnt lgkmcnt(0)
	s_barrier
; #define PG8_STAGE(bufoff, gbase, voff) do { _Pragma("unroll") for (int _i = 0; _i < 2; ++_i) \
;         __builtin_amdgcn_global_load_lds((const gunsigned*)((const gchar*)(gbase) + (voff)[_i]), (LAS unsigned*)(lds + (bufoff) + ldsw + _i * 8192), 16, 0, 0); } while (0)
; #define PG8_LDA(dst, b, h) do { _Pragma("unroll") for (int m = 0; m < 4; ++m) _Pragma("unroll") for (int k = 0; k < 2; ++k) dst[m][k] = *(const LAS bf16x8*)(lds + PG8_SA(b, h) + aoff + m * 2048 + k * 1024); } while (0)
; #define PG8_MMA(ai, bj, At, Bt) do { __builtin_amdgcn_s_setprio(1); _Pragma("unroll") for (int m = 0; m < 4; ++m) _Pragma("unroll") for (int n = 0; n < 2; ++n) _Pragma("unroll") for (int k = 0; k < 2; ++k) \
;         acc[ai][bj][m][n] = __builtin_amdgcn_mfma_f32_16x16x32_bf16(Bt[n][k], At[m][k], acc[ai][bj][m][n], 0, 0, 0); __builtin_amdgcn_s_setprio(0); } while (0)
; #define PG8_WAIT_V(n) asm volatile("s_waitcnt vmcnt(" #n ")" ::: "memory")
; #define PG8_WAIT_L(n) asm volatile("s_waitcnt lgkmcnt(" #n ")" ::: "memory")
; #define PG8_BAR __builtin_amdgcn_s_barrier()
; #define PG8_SCHED __builtin_amdgcn_sched_barrier(0)
; template <class Epi, class Sched>
; __device__ __forceinline__ void gemm_phase(LAS unsigned char* lds, const int tid, const Gemm g, const Sched& S, const Epi& E) {
;     ...
;             PG8_WAIT_V(8); PG8_WAIT_L(0); PG8_BAR; PG8_MMA(0, 0, At, B0); PG8_MMA(0, 1, At, B1); PG8_BAR; PG8_SCHED;
;             PG8_LDA(At, 1, 1); PG8_STAGE(PG8_SB(1, 0), b3, voffB); PG8_STAGE(PG8_SB(1, 1), b3 + hstep, voffB); PG8_STAGE(PG8_SA(1, 0), a3, voffA);
;             PG8_WAIT_V(8); PG8_WAIT_L(0); PG8_BAR; PG8_MMA(1, 0, At, B0); PG8_MMA(1, 1, At, B1); PG8_BAR; PG8_SCHED;
;         }
	s_setprio 1
	s_waitcnt lgkmcnt(0)
	v_mfma_f32_16x16x32_bf16 v[126:129], v[130:133], v[192:195], v[126:129]
	v_mfma_f32_16x16x32_bf16 v[122:125], v[138:141], v[192:195], v[122:125]
	v_mfma_f32_16x16x32_bf16 v[110:113], v[130:133], v[208:211], v[110:113]
	v_mfma_f32_16x16x32_bf16 v[106:109], v[138:141], v[208:211], v[106:109]
	v_mfma_f32_16x16x32_bf16 v[94:97], v[130:133], v[216:219], v[94:97]
	v_mfma_f32_16x16x32_bf16 v[90:93], v[138:141], v[216:219], v[90:93]
	v_mfma_f32_16x16x32_bf16 v[78:81], v[130:133], v[224:227], v[78:81]
	v_mfma_f32_16x16x32_bf16 v[74:77], v[138:141], v[224:227], v[74:77]
	v_mfma_f32_16x16x32_bf16 v[126:129], v[134:137], v[204:207], v[126:129]
	v_mfma_f32_16x16x32_bf16 v[122:125], v[142:145], v[204:207], v[122:125]
	v_mfma_f32_16x16x32_bf16 v[110:113], v[134:137], v[212:215], v[110:113]
	v_mfma_f32_16x16x32_bf16 v[106:109], v[142:145], v[212:215], v[106:109]
	v_mfma_f32_16x16x32_bf16 v[94:97], v[134:137], v[220:223], v[94:97]
	v_mfma_f32_16x16x32_bf16 v[90:93], v[142:145], v[220:223], v[90:93]
	v_mfma_f32_16x16x32_bf16 v[78:81], v[134:137], v[242:245], v[78:81]
	v_mfma_f32_16x16x32_bf16 v[74:77], v[142:145], v[242:245], v[74:77]
	s_setprio 0
	s_setprio 1
	v_mfma_f32_16x16x32_bf16 v[118:121], v[146:149], v[192:195], v[118:121]
	v_mfma_f32_16x16x32_bf16 v[114:117], v[164:167], v[192:195], v[114:117]
	v_mfma_f32_16x16x32_bf16 v[102:105], v[146:149], v[208:211], v[102:105]
	v_mfma_f32_16x16x32_bf16 v[98:101], v[164:167], v[208:211], v[98:101]
	v_mfma_f32_16x16x32_bf16 v[86:89], v[146:149], v[216:219], v[86:89]
	v_mfma_f32_16x16x32_bf16 v[82:85], v[164:167], v[216:219], v[82:85]
	v_mfma_f32_16x16x32_bf16 v[70:73], v[146:149], v[224:227], v[70:73]
	v_mfma_f32_16x16x32_bf16 v[66:69], v[164:167], v[224:227], v[66:69]
	v_mfma_f32_16x16x32_bf16 v[118:121], v[150:153], v[204:207], v[118:121]
	v_mfma_f32_16x16x32_bf16 v[114:117], v[168:171], v[204:207], v[114:117]
	v_mfma_f32_16x16x32_bf16 v[102:105], v[150:153], v[212:215], v[102:105]
	v_mfma_f32_16x16x32_bf16 v[98:101], v[168:171], v[212:215], v[98:101]
	v_mfma_f32_16x16x32_bf16 v[86:89], v[150:153], v[220:223], v[86:89]
	v_mfma_f32_16x16x32_bf16 v[82:85], v[168:171], v[220:223], v[82:85]
	v_mfma_f32_16x16x32_bf16 v[70:73], v[150:153], v[242:245], v[70:73]
	v_mfma_f32_16x16x32_bf16 v[66:69], v[168:171], v[242:245], v[66:69]
	s_setprio 0
	s_barrier
	s_add_i32 s10, s30, s43
	s_mov_b32 m0, s10
	ds_read_b128 v[192:195], v190 offset:49152
	ds_read_b128 v[204:207], v190 offset:50176
	ds_read_b128 v[208:211], v190 offset:51200
	ds_read_b128 v[212:215], v190 offset:52224
	ds_read_b128 v[216:219], v190 offset:53248
	ds_read_b128 v[220:223], v190 offset:54272
	ds_read_b128 v[224:227], v190 offset:55296
	ds_read_b128 v[242:245], v190 offset:56320
	global_load_lds_dwordx4 v201, s[72:73]
	s_add_i32 m0, s10, 0x2000
	s_add_u32 s10, s72, 0xb0080
	s_addc_u32 s11, s73, 0
	s_add_i32 s30, s39, s43
	global_load_lds_dwordx4 v247, s[72:73]
	s_mov_b32 m0, s30
	s_nop 0
	global_load_lds_dwordx4 v0, s[10:11]
	s_add_i32 m0, s30, 0x2000
	s_nop 0
	global_load_lds_dwordx4 v158, s[10:11]
	s_mov_b32 m0, s53
	s_nop 0
	global_load_lds_dwordx4 v249, s[74:75]
	s_mov_b32 m0, s54
	s_nop 0
	global_load_lds_dwordx4 v251, s[74:75]
	s_waitcnt vmcnt(8)
	s_waitcnt lgkmcnt(0)
	s_barrier
	s_setprio 1
	s_waitcnt lgkmcnt(0)
	v_mfma_f32_16x16x32_bf16 v[62:65], v[130:133], v[192:195], v[62:65]
	v_mfma_f32_16x16x32_bf16 v[58:61], v[138:141], v[192:195], v[58:61]
	v_mfma_f32_16x16x32_bf16 v[46:49], v[130:133], v[208:211], v[46:49]
	v_mfma_f32_16x16x32_bf16 v[42:45], v[138:141], v[208:211], v[42:45]
	v_mfma_f32_16x16x32_bf16 v[30:33], v[130:133], v[216:219], v[30:33]
	v_mfma_f32_16x16x32_bf16 v[26:29], v[138:141], v[216:219], v[26:29]
	v_mfma_f32_16x16x32_bf16 v[14:17], v[130:133], v[224:227], v[14:17]
	v_mfma_f32_16x16x32_bf16 v[10:13], v[138:141], v[224:227], v[10:13]
	v_mfma_f32_16x16x32_bf16 v[62:65], v[134:137], v[204:207], v[62:65]
	v_mfma_f32_16x16x32_bf16 v[58:61], v[142:145], v[204:207], v[58:61]
	v_mfma_f32_16x16x32_bf16 v[46:49], v[134:137], v[212:215], v[46:49]
	v_mfma_f32_16x16x32_bf16 v[42:45], v[142:145], v[212:215], v[42:45]
	v_mfma_f32_16x16x32_bf16 v[30:33], v[134:137], v[220:223], v[30:33]
	v_mfma_f32_16x16x32_bf16 v[26:29], v[142:145], v[220:223], v[26:29]
	v_mfma_f32_16x16x32_bf16 v[14:17], v[134:137], v[242:245], v[14:17]
	v_mfma_f32_16x16x32_bf16 v[10:13], v[142:145], v[242:245], v[10:13]
	s_setprio 0
	s_setprio 1
	v_mfma_f32_16x16x32_bf16 v[54:57], v[146:149], v[192:195], v[54:57]
	v_mfma_f32_16x16x32_bf16 v[50:53], v[164:167], v[192:195], v[50:53]
	v_mfma_f32_16x16x32_bf16 v[38:41], v[146:149], v[208:211], v[38:41]
	v_mfma_f32_16x16x32_bf16 v[34:37], v[164:167], v[208:211], v[34:37]
	v_mfma_f32_16x16x32_bf16 v[22:25], v[146:149], v[216:219], v[22:25]
	v_mfma_f32_16x16x32_bf16 v[18:21], v[164:167], v[216:219], v[18:21]
	v_mfma_f32_16x16x32_bf16 v[6:9], v[146:149], v[224:227], v[6:9]
	v_mfma_f32_16x16x32_bf16 v[2:5], v[164:167], v[224:227], v[2:5]
	v_mfma_f32_16x16x32_bf16 v[54:57], v[150:153], v[204:207], v[54:57]
	v_mfma_f32_16x16x32_bf16 v[50:53], v[168:171], v[204:207], v[50:53]
	v_mfma_f32_16x16x32_bf16 v[38:41], v[150:153], v[212:215], v[38:41]
	v_mfma_f32_16x16x32_bf16 v[34:37], v[168:171], v[212:215], v[34:37]
	v_mfma_f32_16x16x32_bf16 v[22:25], v[150:153], v[220:223], v[22:25]
	v_mfma_f32_16x16x32_bf16 v[18:21], v[168:171], v[220:223], v[18:21]
	v_mfma_f32_16x16x32_bf16 v[6:9], v[150:153], v[242:245], v[6:9]
	v_mfma_f32_16x16x32_bf16 v[2:5], v[168:171], v[242:245], v[2:5]
	s_setprio 0
	s_barrier
	s_add_i32 s29, s29, 2
	s_add_u32 s31, s31, 0x100
	s_addc_u32 s93, s93, 0
	s_cmp_gt_u32 s29, 41
	s_mov_b64 s[10:11], vcc
	s_cbranch_scc0 .LBB0_319
	s_and_b64 vcc, exec, s[16:17]
	s_cbranch_vccz .LBB0_322
	s_barrier

;     __device__ bool next(int i, Unit& u) const { if (!b.next(i / 3, u)) return false; u.pz = i % 3; return true; }
; #define PG8_STAGE(bufoff, gbase, voff) do { _Pragma("unroll") for (int _i = 0; _i < 2; ++_i) \
;         __builtin_amdgcn_global_load_lds((const gunsigned*)((const gchar*)(gbase) + (voff)[_i]), (LAS unsigned*)(lds + (bufoff) + ldsw + _i * 8192), 16, 0, 0); } while (0)
; #define PG8_LDA(dst, b, h) do { _Pragma("unroll") for (int m = 0; m < 4; ++m) _Pragma("unroll") for (int k = 0; k < 2; ++k) dst[m][k] = *(const LAS bf16x8*)(lds + PG8_SA(b, h) + aoff + m * 2048 + k * 1024); } while (0)
; #define PG8_LDB(dst, b, h) do { _Pragma("unroll") for (int n = 0; n < 2; ++n) _Pragma("unroll") for (int k = 0; k < 2; ++k) dst[n][k] = *(const LAS bf16x8*)(lds + PG8_SB(b, h) + boff + n * 2048 + k * 1024); } while (0)
; #define PG8_WAIT_V(n) asm volatile("s_waitcnt vmcnt(" #n ")" ::: "memory")
; #define PG8_WAIT_L(n) asm volatile("s_waitcnt lgkmcnt(" #n ")" ::: "memory")
; template <class Epi, class Sched>
; __device__ __forceinline__ void gemm_phase(LAS unsigned char* lds, const int tid, const Gemm g, const Sched& S, const Epi& E) {
;     ...
;         const bool has_next = S.next(ui + 1, nxt);
;         const gchar* nA = has_next ? (const gchar*)g.A + (size_t)nxt.pm * tstep + (size_t)nxt.pz * g.zA : cA;
;         const gchar* nB = has_next ? (const gchar*)g.Bt + (size_t)nxt.pn * tstep + (size_t)nxt.pz * g.zB : cB;
;         for (int t = 0; t < nt; t += 2) {
;             const bool last = (t == nt - 2);
;             const gchar* a1 = cA + (size_t)(t + 1) * kstep;
;             const gchar* a2 = last ? nA : cA + (size_t)(t + 2) * kstep; const gchar* b2 = last ? nB : cB + (size_t)(t + 2) * kstep;
;             const gchar* a3 = a2 + kstep; const gchar* b3 = b2 + kstep;
;             PG8_LDB(B0, 0, 0); PG8_LDB(B1, 0, 1); PG8_SCHED; PG8_LDA(At, 0, 0); PG8_STAGE(PG8_SA(1, 1), a1 + hstep, voffA);
;             PG8_WAIT_V(8); PG8_WAIT_L(0); PG8_BAR; PG8_MMA(0, 0, At, B0); PG8_MMA(0, 1, At, B1); PG8_BAR; PG8_SCHED;
;     ...
; #pragma unroll
;         for (int a = 0; a < 2; ++a)
; #pragma unroll
;             for (int b = 0; b < 2; ++b)
; #pragma unroll
;                 for (int m = 0; m < 4; ++m)
; #pragma unroll
;                     for (int n = 0; n < 2; ++n) acc[a][b][m][n] = (f32x4){0.f, 0.f, 0.f, 0.f};
;         cur = nxt; cA = nA; cB = nB; ++ui;
.LBB0_368:
	s_ashr_i32 s11, s10, 31
	s_lshl_b64 s[46:47], s[10:11], 19
	s_add_u32 s60, s86, s46
	s_addc_u32 s61, s87, s47
	s_and_b64 s[46:47], s[2:3], exec
	s_cselect_b32 s11, s61, s21
	s_cselect_b32 s12, s60, s20
	s_ashr_i32 s9, s8, 31
	s_lshl_b64 s[46:47], s[8:9], 19
	s_add_u32 s62, s58, s46
	s_addc_u32 s63, s59, s47
	s_and_b64 s[46:47], s[2:3], exec
	s_cselect_b32 s9, s63, s17
	s_cselect_b32 s15, s62, s16
	s_add_u32 s23, s16, 0x100
	s_addc_u32 s24, s17, 0
	s_add_u32 s16, s20, 0x40080
	v_mov_b32_e32 v2, 0
	s_addc_u32 s17, s21, 0
	s_mov_b32 s31, -2
	v_mov_b32_e32 v3, v2
	v_mov_b32_e32 v4, v2
	v_mov_b32_e32 v5, v2
	v_mov_b32_e32 v10, v2
	v_mov_b32_e32 v11, v2
	v_mov_b32_e32 v12, v2
	v_mov_b32_e32 v13, v2
	v_mov_b32_e32 v18, v2
	v_mov_b32_e32 v19, v2
	v_mov_b32_e32 v20, v2
	v_mov_b32_e32 v21, v2
	v_mov_b32_e32 v26, v2
	v_mov_b32_e32 v27, v2
	v_mov_b32_e32 v28, v2
	v_mov_b32_e32 v29, v2
	v_mov_b32_e32 v34, v2
	v_mov_b32_e32 v35, v2
	v_mov_b32_e32 v36, v2
	v_mov_b32_e32 v37, v2
	v_mov_b32_e32 v42, v2
	v_mov_b32_e32 v43, v2
	v_mov_b32_e32 v44, v2
	v_mov_b32_e32 v45, v2
	v_mov_b32_e32 v50, v2
	v_mov_b32_e32 v51, v2
	v_mov_b32_e32 v52, v2
	v_mov_b32_e32 v53, v2
	v_mov_b32_e32 v58, v2
	v_mov_b32_e32 v59, v2
	v_mov_b32_e32 v60, v2
	v_mov_b32_e32 v61, v2
	v_mov_b32_e32 v6, v2
	v_mov_b32_e32 v7, v2
	v_mov_b32_e32 v8, v2
	v_mov_b32_e32 v9, v2
	v_mov_b32_e32 v14, v2
	v_mov_b32_e32 v15, v2
	v_mov_b32_e32 v16, v2
	v_mov_b32_e32 v17, v2
	v_mov_b32_e32 v22, v2
	v_mov_b32_e32 v23, v2
	v_mov_b32_e32 v24, v2
	v_mov_b32_e32 v25, v2
	v_mov_b32_e32 v30, v2
	v_mov_b32_e32 v31, v2
	v_mov_b32_e32 v32, v2
	v_mov_b32_e32 v33, v2
	v_mov_b32_e32 v38, v2
	v_mov_b32_e32 v39, v2
	v_mov_b32_e32 v40, v2
	v_mov_b32_e32 v41, v2
	v_mov_b32_e32 v46, v2
	v_mov_b32_e32 v47, v2
	v_mov_b32_e32 v48, v2
	v_mov_b32_e32 v49, v2
	v_mov_b32_e32 v54, v2
	v_mov_b32_e32 v55, v2
	v_mov_b32_e32 v56, v2
	v_mov_b32_e32 v57, v2
	v_mov_b32_e32 v62, v2
	v_mov_b32_e32 v63, v2
	v_mov_b32_e32 v64, v2
	v_mov_b32_e32 v65, v2
	v_mov_b32_e32 v66, v2
	v_mov_b32_e32 v67, v2
	v_mov_b32_e32 v68, v2
	v_mov_b32_e32 v69, v2
	v_mov_b32_e32 v74, v2
	v_mov_b32_e32 v75, v2
	v_mov_b32_e32 v76, v2
	v_mov_b32_e32 v77, v2
	s_waitcnt vmcnt(0)
	v_mov_b32_e32 v82, v2
	v_mov_b32_e32 v83, v2
	v_mov_b32_e32 v84, v2
	v_mov_b32_e32 v85, v2
	v_mov_b32_e32 v90, v2
	v_mov_b32_e32 v91, v2
	v_mov_b32_e32 v92, v2
	v_mov_b32_e32 v93, v2
	v_mov_b32_e32 v98, v2
	v_mov_b32_e32 v99, v2
	v_mov_b32_e32 v100, v2
	v_mov_b32_e32 v101, v2
	v_mov_b32_e32 v106, v2
	v_mov_b32_e32 v107, v2
	v_mov_b32_e32 v108, v2
	v_mov_b32_e32 v109, v2
	v_mov_b32_e32 v114, v2
	v_mov_b32_e32 v115, v2
	v_mov_b32_e32 v116, v2
	v_mov_b32_e32 v117, v2
	v_mov_b32_e32 v122, v2
	v_mov_b32_e32 v123, v2
	v_mov_b32_e32 v124, v2
	v_mov_b32_e32 v125, v2
	v_mov_b32_e32 v70, v2
	v_mov_b32_e32 v71, v2
	v_mov_b32_e32 v72, v2
	v_mov_b32_e32 v73, v2
	v_mov_b32_e32 v78, v2
	v_mov_b32_e32 v79, v2
	v_mov_b32_e32 v80, v2
	v_mov_b32_e32 v81, v2
	v_mov_b32_e32 v86, v2
	v_mov_b32_e32 v87, v2
	v_mov_b32_e32 v88, v2
	v_mov_b32_e32 v89, v2
	v_mov_b32_e32 v94, v2
	v_mov_b32_e32 v95, v2
	v_mov_b32_e32 v96, v2
	v_mov_b32_e32 v97, v2
	v_mov_b32_e32 v102, v2
	v_mov_b32_e32 v103, v2
	v_mov_b32_e32 v104, v2
	v_mov_b32_e32 v105, v2
	v_mov_b32_e32 v110, v2
	v_mov_b32_e32 v111, v2
	v_mov_b32_e32 v112, v2
	v_mov_b32_e32 v113, v2
	v_mov_b32_e32 v118, v2
	v_mov_b32_e32 v119, v2
	v_mov_b32_e32 v120, v2
	v_mov_b32_e32 v121, v2
	v_mov_b32_e32 v126, v2
	v_mov_b32_e32 v127, v2
	v_mov_b32_e32 v128, v2
	v_mov_b32_e32 v129, v2
	v_add_u32_e32 v141, 0x80, v0
	v_add_u32_e32 v153, 0x80, v130
	v_add_u32_e32 v201, 0x80, v134
	v_add_u32_e32 v225, 0x80, v132
.LBB0_369:
	s_add_u32 s20, s16, 0xfffc0080
	s_addc_u32 s21, s17, -1
	s_add_i32 s29, 0, 0x10000
	s_cmp_eq_u32 s31, 12
	s_cselect_b32 s57, s11, s21
	s_cselect_b32 s56, s12, s20
	v_add_u32_e32 v140, s29, v145
	s_cselect_b32 s21, s9, s24
	s_cselect_b32 s20, s15, s23
	s_add_i32 s30, 0, 0x14000
	ds_read_b128 v[146:149], v140
	ds_read_b128 v[156:159], v140 offset:1024
	ds_read_b128 v[160:163], v140 offset:2048
	ds_read_b128 v[164:167], v140 offset:3072
	v_add_u32_e32 v140, s30, v145
	ds_read_b128 v[168:171], v140
	ds_read_b128 v[172:175], v140 offset:1024
	ds_read_b128 v[176:179], v140 offset:2048
	ds_read_b128 v[180:183], v140 offset:3072
	s_add_i32 m0, s73, 0xc000
	ds_read_b128 v[184:187], v155
	ds_read_b128 v[188:191], v155 offset:1024
	ds_read_b128 v[192:195], v155 offset:2048
	ds_read_b128 v[204:207], v155 offset:3072
	ds_read_b128 v[208:211], v155 offset:4096
	ds_read_b128 v[212:215], v155 offset:5120
	ds_read_b128 v[216:219], v155 offset:6144
	ds_read_b128 v[220:223], v155 offset:7168
	global_load_lds_dwordx4 v138, s[16:17]
	s_add_i32 m0, s73, 0xe000
	s_nop 0
	global_load_lds_dwordx4 v136, s[16:17]
	s_waitcnt vmcnt(8)
	s_waitcnt lgkmcnt(0)
	s_barrier
; #define PG8_STAGE(bufoff, gbase, voff) do { _Pragma("unroll") for (int _i = 0; _i < 2; ++_i) \
;         __builtin_amdgcn_global_load_lds((const gunsigned*)((const gchar*)(gbase) + (voff)[_i]), (LAS unsigned*)(lds + (bufoff) + ldsw + _i * 8192), 16, 0, 0); } while (0)
; #define PG8_LDA(dst, b, h) do { _Pragma("unroll") for (int m = 0; m < 4; ++m) _Pragma("unroll") for (int k = 0; k < 2; ++k) dst[m][k] = *(const LAS bf16x8*)(lds + PG8_SA(b, h) + aoff + m * 2048 + k * 1024); } while (0)
; #define PG8_LDB(dst, b, h) do { _Pragma("unroll") for (int n = 0; n < 2; ++n) _Pragma("unroll") for (int k = 0; k < 2; ++k) dst[n][k] = *(const LAS bf16x8*)(lds + PG8_SB(b, h) + boff + n * 2048 + k * 1024); } while (0)
; #define PG8_MMA(ai, bj, At, Bt) do { __builtin_amdgcn_s_setprio(1); _Pragma("unroll") for (int m = 0; m < 4; ++m) _Pragma("unroll") for (int n = 0; n < 2; ++n) _Pragma("unroll") for (int k = 0; k < 2; ++k) \
;         acc[ai][bj][m][n] = __builtin_amdgcn_mfma_f32_16x16x32_bf16(Bt[n][k], At[m][k], acc[ai][bj][m][n], 0, 0, 0); __builtin_amdgcn_s_setprio(0); } while (0)
; #define PG8_WAIT_V(n) asm volatile("s_waitcnt vmcnt(" #n ")" ::: "memory")
; #define PG8_WAIT_L(n) asm volatile("s_waitcnt lgkmcnt(" #n ")" ::: "memory")
; #define PG8_BAR __builtin_amdgcn_s_barrier()
; #define PG8_SCHED __builtin_amdgcn_sched_barrier(0)
; template <class Epi, class Sched>
; __device__ __forceinline__ void gemm_phase(LAS unsigned char* lds, const int tid, const Gemm g, const Sched& S, const Epi& E) {
;     ...
;             PG8_WAIT_V(8); PG8_WAIT_L(0); PG8_BAR; PG8_MMA(0, 0, At, B0); PG8_MMA(0, 1, At, B1); PG8_BAR; PG8_SCHED;
;             PG8_LDA(At, 0, 1); PG8_STAGE(PG8_SB(0, 0), b2, voffB); PG8_STAGE(PG8_SB(0, 1), b2 + hstep, voffB); PG8_STAGE(PG8_SA(0, 0), a2, voffA);
;             PG8_WAIT_V(8); PG8_WAIT_L(0); PG8_BAR; PG8_MMA(1, 0, At, B0); PG8_MMA(1, 1, At, B1); PG8_BAR; PG8_SCHED;
;             PG8_LDB(B0, 1, 0); PG8_LDB(B1, 1, 1); PG8_SCHED; PG8_LDA(At, 1, 0); PG8_STAGE(PG8_SA(0, 1), a2 + hstep, voffA);
	s_setprio 1
	s_waitcnt lgkmcnt(0)
	v_mfma_f32_16x16x32_bf16 v[126:129], v[146:149], v[184:187], v[126:129]
	v_mfma_f32_16x16x32_bf16 v[118:121], v[160:163], v[184:187], v[118:121]
	v_mfma_f32_16x16x32_bf16 v[110:113], v[146:149], v[192:195], v[110:113]
	v_mfma_f32_16x16x32_bf16 v[102:105], v[160:163], v[192:195], v[102:105]
	v_mfma_f32_16x16x32_bf16 v[94:97], v[146:149], v[208:211], v[94:97]
	v_mfma_f32_16x16x32_bf16 v[86:89], v[160:163], v[208:211], v[86:89]
	v_mfma_f32_16x16x32_bf16 v[78:81], v[146:149], v[216:219], v[78:81]
	v_mfma_f32_16x16x32_bf16 v[70:73], v[160:163], v[216:219], v[70:73]
	v_mfma_f32_16x16x32_bf16 v[126:129], v[156:159], v[188:191], v[126:129]
	v_mfma_f32_16x16x32_bf16 v[118:121], v[164:167], v[188:191], v[118:121]
	v_mfma_f32_16x16x32_bf16 v[110:113], v[156:159], v[204:207], v[110:113]
	v_mfma_f32_16x16x32_bf16 v[102:105], v[164:167], v[204:207], v[102:105]
	v_mfma_f32_16x16x32_bf16 v[94:97], v[156:159], v[212:215], v[94:97]
	v_mfma_f32_16x16x32_bf16 v[86:89], v[164:167], v[212:215], v[86:89]
	v_mfma_f32_16x16x32_bf16 v[78:81], v[156:159], v[220:223], v[78:81]
	v_mfma_f32_16x16x32_bf16 v[70:73], v[164:167], v[220:223], v[70:73]
	s_setprio 0
	s_setprio 1
	v_mfma_f32_16x16x32_bf16 v[122:125], v[168:171], v[184:187], v[122:125]
	v_mfma_f32_16x16x32_bf16 v[114:117], v[176:179], v[184:187], v[114:117]
	v_mfma_f32_16x16x32_bf16 v[106:109], v[168:171], v[192:195], v[106:109]
	v_mfma_f32_16x16x32_bf16 v[98:101], v[176:179], v[192:195], v[98:101]
	v_mfma_f32_16x16x32_bf16 v[90:93], v[168:171], v[208:211], v[90:93]
	v_mfma_f32_16x16x32_bf16 v[82:85], v[176:179], v[208:211], v[82:85]
	v_mfma_f32_16x16x32_bf16 v[74:77], v[168:171], v[216:219], v[74:77]
	v_mfma_f32_16x16x32_bf16 v[66:69], v[176:179], v[216:219], v[66:69]
	v_mfma_f32_16x16x32_bf16 v[122:125], v[172:175], v[188:191], v[122:125]
	v_mfma_f32_16x16x32_bf16 v[114:117], v[180:183], v[188:191], v[114:117]
	v_mfma_f32_16x16x32_bf16 v[106:109], v[172:175], v[204:207], v[106:109]
	v_mfma_f32_16x16x32_bf16 v[98:101], v[180:183], v[204:207], v[98:101]
	v_mfma_f32_16x16x32_bf16 v[90:93], v[172:175], v[212:215], v[90:93]
	v_mfma_f32_16x16x32_bf16 v[82:85], v[180:183], v[212:215], v[82:85]
	v_mfma_f32_16x16x32_bf16 v[74:77], v[172:175], v[220:223], v[74:77]
	v_mfma_f32_16x16x32_bf16 v[66:69], v[180:183], v[220:223], v[66:69]
	s_setprio 0
	s_barrier
	s_add_i32 s29, s29, s43
	s_mov_b32 m0, s29
	ds_read_b128 v[184:187], v155 offset:16384
	ds_read_b128 v[188:191], v155 offset:17408
	ds_read_b128 v[192:195], v155 offset:18432
	ds_read_b128 v[204:207], v155 offset:19456
	ds_read_b128 v[208:211], v155 offset:20480
	ds_read_b128 v[212:215], v155 offset:21504
	ds_read_b128 v[216:219], v155 offset:22528
	ds_read_b128 v[220:223], v155 offset:23552
	global_load_lds_dwordx4 v0, s[20:21]
	s_add_i32 m0, s29, 0x2000
	s_add_u32 s46, s20, 0x40000
	s_addc_u32 s47, s21, 0
	s_add_i32 s29, s30, s43
	global_load_lds_dwordx4 v130, s[20:21]
	s_mov_b32 m0, s29
	s_nop 0
	global_load_lds_dwordx4 v0, s[46:47]
	s_add_i32 m0, s29, 0x2000
	s_nop 0
	global_load_lds_dwordx4 v130, s[46:47]
	s_mov_b32 m0, s73
	s_nop 0
	global_load_lds_dwordx4 v134, s[56:57]
	s_mov_b32 m0, s74
	s_nop 0
	global_load_lds_dwordx4 v132, s[56:57]
	s_waitcnt vmcnt(8)
	s_waitcnt lgkmcnt(0)
	s_barrier
	s_setprio 1
	s_waitcnt lgkmcnt(0)
	v_mfma_f32_16x16x32_bf16 v[62:65], v[146:149], v[184:187], v[62:65]
	v_mfma_f32_16x16x32_bf16 v[54:57], v[160:163], v[184:187], v[54:57]
	v_mfma_f32_16x16x32_bf16 v[46:49], v[146:149], v[192:195], v[46:49]
	v_mfma_f32_16x16x32_bf16 v[38:41], v[160:163], v[192:195], v[38:41]
	v_mfma_f32_16x16x32_bf16 v[30:33], v[146:149], v[208:211], v[30:33]
	v_mfma_f32_16x16x32_bf16 v[22:25], v[160:163], v[208:211], v[22:25]
	v_mfma_f32_16x16x32_bf16 v[14:17], v[146:149], v[216:219], v[14:17]
	v_mfma_f32_16x16x32_bf16 v[6:9], v[160:163], v[216:219], v[6:9]
	v_mfma_f32_16x16x32_bf16 v[62:65], v[156:159], v[188:191], v[62:65]
	v_mfma_f32_16x16x32_bf16 v[54:57], v[164:167], v[188:191], v[54:57]
	v_mfma_f32_16x16x32_bf16 v[46:49], v[156:159], v[204:207], v[46:49]
	v_mfma_f32_16x16x32_bf16 v[38:41], v[164:167], v[204:207], v[38:41]
	v_mfma_f32_16x16x32_bf16 v[30:33], v[156:159], v[212:215], v[30:33]
	v_mfma_f32_16x16x32_bf16 v[22:25], v[164:167], v[212:215], v[22:25]
	v_mfma_f32_16x16x32_bf16 v[14:17], v[156:159], v[220:223], v[14:17]
	v_mfma_f32_16x16x32_bf16 v[6:9], v[164:167], v[220:223], v[6:9]
	s_setprio 0
	s_setprio 1
	v_mfma_f32_16x16x32_bf16 v[58:61], v[168:171], v[184:187], v[58:61]
	v_mfma_f32_16x16x32_bf16 v[50:53], v[176:179], v[184:187], v[50:53]
	v_mfma_f32_16x16x32_bf16 v[42:45], v[168:171], v[192:195], v[42:45]
	v_mfma_f32_16x16x32_bf16 v[34:37], v[176:179], v[192:195], v[34:37]
	v_mfma_f32_16x16x32_bf16 v[26:29], v[168:171], v[208:211], v[26:29]
	v_mfma_f32_16x16x32_bf16 v[18:21], v[176:179], v[208:211], v[18:21]
	v_mfma_f32_16x16x32_bf16 v[10:13], v[168:171], v[216:219], v[10:13]
	v_mfma_f32_16x16x32_bf16 v[2:5], v[176:179], v[216:219], v[2:5]
	v_mfma_f32_16x16x32_bf16 v[58:61], v[172:175], v[188:191], v[58:61]
	v_mfma_f32_16x16x32_bf16 v[50:53], v[180:183], v[188:191], v[50:53]
	v_mfma_f32_16x16x32_bf16 v[42:45], v[172:175], v[204:207], v[42:45]
	v_mfma_f32_16x16x32_bf16 v[34:37], v[180:183], v[204:207], v[34:37]
	v_mfma_f32_16x16x32_bf16 v[26:29], v[172:175], v[212:215], v[26:29]
	v_mfma_f32_16x16x32_bf16 v[18:21], v[180:183], v[212:215], v[18:21]
	v_mfma_f32_16x16x32_bf16 v[10:13], v[172:175], v[220:223], v[10:13]
	v_mfma_f32_16x16x32_bf16 v[2:5], v[180:183], v[220:223], v[2:5]
	s_setprio 0
	s_barrier
; #define PG8_STAGE(bufoff, gbase, voff) do { _Pragma("unroll") for (int _i = 0; _i < 2; ++_i) \
;         __builtin_amdgcn_global_load_lds((const gunsigned*)((const gchar*)(gbase) + (voff)[_i]), (LAS unsigned*)(lds + (bufoff) + ldsw + _i * 8192), 16, 0, 0); } while (0)
; #define PG8_LDA(dst, b, h) do { _Pragma("unroll") for (int m = 0; m < 4; ++m) _Pragma("unroll") for (int k = 0; k < 2; ++k) dst[m][k] = *(const LAS bf16x8*)(lds + PG8_SA(b, h) + aoff + m * 2048 + k * 1024); } while (0)
; #define PG8_LDB(dst, b, h) do { _Pragma("unroll") for (int n = 0; n < 2; ++n) _Pragma("unroll") for (int k = 0; k < 2; ++k) dst[n][k] = *(const LAS bf16x8*)(lds + PG8_SB(b, h) + boff + n * 2048 + k * 1024); } while (0)
; #define PG8_MMA(ai, bj, At, Bt) do { __builtin_amdgcn_s_setprio(1); _Pragma("unroll") for (int m = 0; m < 4; ++m) _Pragma("unroll") for (int n = 0; n < 2; ++n) _Pragma("unroll") for (int k = 0; k < 2; ++k) \
;         acc[ai][bj][m][n] = __builtin_amdgcn_mfma_f32_16x16x32_bf16(Bt[n][k], At[m][k], acc[ai][bj][m][n], 0, 0, 0); __builtin_amdgcn_s_setprio(0); } while (0)
; #define PG8_WAIT_V(n) asm volatile("s_waitcnt vmcnt(" #n ")" ::: "memory")
; #define PG8_WAIT_L(n) asm volatile("s_waitcnt lgkmcnt(" #n ")" ::: "memory")
; #define PG8_BAR __builtin_amdgcn_s_barrier()
; #define PG8_SCHED __builtin_amdgcn_sched_barrier(0)
; template <class Epi, class Sched>
; __device__ __forceinline__ void gemm_phase(LAS unsigned char* lds, const int tid, const Gemm g, const Sched& S, const Epi& E) {
;     ...
;             PG8_LDB(B0, 1, 0); PG8_LDB(B1, 1, 1); PG8_SCHED; PG8_LDA(At, 1, 0); PG8_STAGE(PG8_SA(0, 1), a2 + hstep, voffA);
;             PG8_WAIT_V(8); PG8_WAIT_L(0); PG8_BAR; PG8_MMA(0, 0, At, B0); PG8_MMA(0, 1, At, B1); PG8_BAR; PG8_SCHED;
;             PG8_LDA(At, 1, 1); PG8_STAGE(PG8_SB(1, 0), b3, voffB); PG8_STAGE(PG8_SB(1, 1), b3 + hstep, voffB); PG8_STAGE(PG8_SA(1, 0), a3, voffA);
;             PG8_WAIT_V(8); PG8_WAIT_L(0); PG8_BAR; PG8_MMA(1, 0, At, B0); PG8_MMA(1, 1, At, B1); PG8_BAR; PG8_SCHED;
;         }
	s_add_i32 s29, 0, 0x18000
	v_add_u32_e32 v142, s29, v145
	s_add_i32 s30, 0, 0x1c000
	ds_read_b128 v[146:149], v142
	ds_read_b128 v[156:159], v142 offset:1024
	ds_read_b128 v[160:163], v142 offset:2048
	ds_read_b128 v[164:167], v142 offset:3072
	v_add_u32_e32 v142, s30, v145
	ds_read_b128 v[168:171], v142
	ds_read_b128 v[172:175], v142 offset:1024
	ds_read_b128 v[176:179], v142 offset:2048
	ds_read_b128 v[180:183], v142 offset:3072
	s_add_u32 s46, s56, 0x40000
	s_addc_u32 s47, s57, 0
	s_mov_b32 m0, s75
	ds_read_b128 v[184:187], v155 offset:32768
	ds_read_b128 v[188:191], v155 offset:33792
	ds_read_b128 v[192:195], v155 offset:34816
	ds_read_b128 v[204:207], v155 offset:35840
	ds_read_b128 v[208:211], v155 offset:36864
	ds_read_b128 v[212:215], v155 offset:37888
	ds_read_b128 v[216:219], v155 offset:38912
	ds_read_b128 v[220:223], v155 offset:39936
	global_load_lds_dwordx4 v134, s[46:47]
	s_mov_b32 m0, s92
	s_nop 0
	global_load_lds_dwordx4 v132, s[46:47]
	s_waitcnt vmcnt(8)
	s_waitcnt lgkmcnt(0)
	s_barrier
	s_setprio 1
	s_waitcnt lgkmcnt(0)
	v_mfma_f32_16x16x32_bf16 v[126:129], v[146:149], v[184:187], v[126:129]
	v_mfma_f32_16x16x32_bf16 v[118:121], v[160:163], v[184:187], v[118:121]
	v_mfma_f32_16x16x32_bf16 v[110:113], v[146:149], v[192:195], v[110:113]
	v_mfma_f32_16x16x32_bf16 v[102:105], v[160:163], v[192:195], v[102:105]
	v_mfma_f32_16x16x32_bf16 v[94:97], v[146:149], v[208:211], v[94:97]
	v_mfma_f32_16x16x32_bf16 v[86:89], v[160:163], v[208:211], v[86:89]
	v_mfma_f32_16x16x32_bf16 v[78:81], v[146:149], v[216:219], v[78:81]
	v_mfma_f32_16x16x32_bf16 v[70:73], v[160:163], v[216:219], v[70:73]
	v_mfma_f32_16x16x32_bf16 v[126:129], v[156:159], v[188:191], v[126:129]
	v_mfma_f32_16x16x32_bf16 v[118:121], v[164:167], v[188:191], v[118:121]
	v_mfma_f32_16x16x32_bf16 v[110:113], v[156:159], v[204:207], v[110:113]
	v_mfma_f32_16x16x32_bf16 v[102:105], v[164:167], v[204:207], v[102:105]
	v_mfma_f32_16x16x32_bf16 v[94:97], v[156:159], v[212:215], v[94:97]
	v_mfma_f32_16x16x32_bf16 v[86:89], v[164:167], v[212:215], v[86:89]
	v_mfma_f32_16x16x32_bf16 v[78:81], v[156:159], v[220:223], v[78:81]
	v_mfma_f32_16x16x32_bf16 v[70:73], v[164:167], v[220:223], v[70:73]
	s_setprio 0
	s_setprio 1
	v_mfma_f32_16x16x32_bf16 v[122:125], v[168:171], v[184:187], v[122:125]
	v_mfma_f32_16x16x32_bf16 v[114:117], v[176:179], v[184:187], v[114:117]
	v_mfma_f32_16x16x32_bf16 v[106:109], v[168:171], v[192:195], v[106:109]
	v_mfma_f32_16x16x32_bf16 v[98:101], v[176:179], v[192:195], v[98:101]
	v_mfma_f32_16x16x32_bf16 v[90:93], v[168:171], v[208:211], v[90:93]
	v_mfma_f32_16x16x32_bf16 v[82:85], v[176:179], v[208:211], v[82:85]
	v_mfma_f32_16x16x32_bf16 v[74:77], v[168:171], v[216:219], v[74:77]
	v_mfma_f32_16x16x32_bf16 v[66:69], v[176:179], v[216:219], v[66:69]
	v_mfma_f32_16x16x32_bf16 v[122:125], v[172:175], v[188:191], v[122:125]
	v_mfma_f32_16x16x32_bf16 v[114:117], v[180:183], v[188:191], v[114:117]
	v_mfma_f32_16x16x32_bf16 v[106:109], v[172:175], v[204:207], v[106:109]
	v_mfma_f32_16x16x32_bf16 v[98:101], v[180:183], v[204:207], v[98:101]
	v_mfma_f32_16x16x32_bf16 v[90:93], v[172:175], v[212:215], v[90:93]
	v_mfma_f32_16x16x32_bf16 v[82:85], v[180:183], v[212:215], v[82:85]
	v_mfma_f32_16x16x32_bf16 v[74:77], v[172:175], v[220:223], v[74:77]
	v_mfma_f32_16x16x32_bf16 v[66:69], v[180:183], v[220:223], v[66:69]
	s_setprio 0
	s_barrier
	s_add_i32 s29, s29, s43
	s_mov_b32 m0, s29
	ds_read_b128 v[184:187], v155 offset:49152
	ds_read_b128 v[188:191], v155 offset:50176
	ds_read_b128 v[192:195], v155 offset:51200
	ds_read_b128 v[204:207], v155 offset:52224
	ds_read_b128 v[208:211], v155 offset:53248
	ds_read_b128 v[212:215], v155 offset:54272
	ds_read_b128 v[216:219], v155 offset:55296
	ds_read_b128 v[220:223], v155 offset:56320
	global_load_lds_dwordx4 v141, s[20:21]
	s_add_i32 m0, s29, 0x2000
	s_add_i32 s29, s30, s43
	global_load_lds_dwordx4 v153, s[20:21]
	s_add_u32 s20, s20, 0x40080
	s_addc_u32 s21, s21, 0
	s_mov_b32 m0, s29
	s_nop 0
	global_load_lds_dwordx4 v0, s[20:21]
	s_add_i32 m0, s29, 0x2000
	s_nop 0
	global_load_lds_dwordx4 v130, s[20:21]
	s_mov_b32 m0, s93
	s_nop 0
	global_load_lds_dwordx4 v201, s[56:57]
	s_mov_b32 m0, s44
	s_nop 0
	global_load_lds_dwordx4 v225, s[56:57]
	s_waitcnt vmcnt(8)
	s_waitcnt lgkmcnt(0)
	s_barrier
	s_setprio 1
	s_waitcnt lgkmcnt(0)
	v_mfma_f32_16x16x32_bf16 v[62:65], v[146:149], v[184:187], v[62:65]
	v_mfma_f32_16x16x32_bf16 v[54:57], v[160:163], v[184:187], v[54:57]
	v_mfma_f32_16x16x32_bf16 v[46:49], v[146:149], v[192:195], v[46:49]
	v_mfma_f32_16x16x32_bf16 v[38:41], v[160:163], v[192:195], v[38:41]
	v_mfma_f32_16x16x32_bf16 v[30:33], v[146:149], v[208:211], v[30:33]
	v_mfma_f32_16x16x32_bf16 v[22:25], v[160:163], v[208:211], v[22:25]
	v_mfma_f32_16x16x32_bf16 v[14:17], v[146:149], v[216:219], v[14:17]
	v_mfma_f32_16x16x32_bf16 v[6:9], v[160:163], v[216:219], v[6:9]
	v_mfma_f32_16x16x32_bf16 v[62:65], v[156:159], v[188:191], v[62:65]
	v_mfma_f32_16x16x32_bf16 v[54:57], v[164:167], v[188:191], v[54:57]
	v_mfma_f32_16x16x32_bf16 v[46:49], v[156:159], v[204:207], v[46:49]
	v_mfma_f32_16x16x32_bf16 v[38:41], v[164:167], v[204:207], v[38:41]
	v_mfma_f32_16x16x32_bf16 v[30:33], v[156:159], v[212:215], v[30:33]
	v_mfma_f32_16x16x32_bf16 v[22:25], v[164:167], v[212:215], v[22:25]
	v_mfma_f32_16x16x32_bf16 v[14:17], v[156:159], v[220:223], v[14:17]
	v_mfma_f32_16x16x32_bf16 v[6:9], v[164:167], v[220:223], v[6:9]
	s_setprio 0
	s_setprio 1
	v_mfma_f32_16x16x32_bf16 v[58:61], v[168:171], v[184:187], v[58:61]
	v_mfma_f32_16x16x32_bf16 v[50:53], v[176:179], v[184:187], v[50:53]
	v_mfma_f32_16x16x32_bf16 v[42:45], v[168:171], v[192:195], v[42:45]
	v_mfma_f32_16x16x32_bf16 v[34:37], v[176:179], v[192:195], v[34:37]
	v_mfma_f32_16x16x32_bf16 v[26:29], v[168:171], v[208:211], v[26:29]
	v_mfma_f32_16x16x32_bf16 v[18:21], v[176:179], v[208:211], v[18:21]
	v_mfma_f32_16x16x32_bf16 v[10:13], v[168:171], v[216:219], v[10:13]
	v_mfma_f32_16x16x32_bf16 v[2:5], v[176:179], v[216:219], v[2:5]
	v_mfma_f32_16x16x32_bf16 v[58:61], v[172:175], v[188:191], v[58:61]
	v_mfma_f32_16x16x32_bf16 v[50:53], v[180:183], v[188:191], v[50:53]
	v_mfma_f32_16x16x32_bf16 v[42:45], v[172:175], v[204:207], v[42:45]
	v_mfma_f32_16x16x32_bf16 v[34:37], v[180:183], v[204:207], v[34:37]
	v_mfma_f32_16x16x32_bf16 v[26:29], v[172:175], v[212:215], v[26:29]
	v_mfma_f32_16x16x32_bf16 v[18:21], v[180:183], v[212:215], v[18:21]
	v_mfma_f32_16x16x32_bf16 v[10:13], v[172:175], v[220:223], v[10:13]
	v_mfma_f32_16x16x32_bf16 v[2:5], v[180:183], v[220:223], v[2:5]
	s_setprio 0
	s_barrier
	s_add_i32 s31, s31, 2
	s_add_u32 s23, s23, 0x100
	s_addc_u32 s24, s24, 0
	s_add_u32 s16, s16, 0x100
	s_addc_u32 s17, s17, 0
	s_cmp_gt_u32 s31, 13
	s_cbranch_scc0 .LBB0_369
	s_and_b64 vcc, exec, s[6:7]
	s_cbranch_vccz .LBB0_372
	s_barrier

;     __device__ bool next(int i, Unit& u) const { if (!b.next(i / 3, u)) return false; u.pz = i % 3; return true; }
; #define PG8_STAGE(bufoff, gbase, voff) do { _Pragma("unroll") for (int _i = 0; _i < 2; ++_i) \
;         __builtin_amdgcn_global_load_lds((const gunsigned*)((const gchar*)(gbase) + (voff)[_i]), (LAS unsigned*)(lds + (bufoff) + ldsw + _i * 8192), 16, 0, 0); } while (0)
; #define PG8_LDA(dst, b, h) do { _Pragma("unroll") for (int m = 0; m < 4; ++m) _Pragma("unroll") for (int k = 0; k < 2; ++k) dst[m][k] = *(const LAS bf16x8*)(lds + PG8_SA(b, h) + aoff + m * 2048 + k * 1024); } while (0)
; #define PG8_LDB(dst, b, h) do { _Pragma("unroll") for (int n = 0; n < 2; ++n) _Pragma("unroll") for (int k = 0; k < 2; ++k) dst[n][k] = *(const LAS bf16x8*)(lds + PG8_SB(b, h) + boff + n * 2048 + k * 1024); } while (0)
; #define PG8_WAIT_V(n) asm volatile("s_waitcnt vmcnt(" #n ")" ::: "memory")
; #define PG8_WAIT_L(n) asm volatile("s_waitcnt lgkmcnt(" #n ")" ::: "memory")
; template <class Epi, class Sched>
; __device__ __forceinline__ void gemm_phase(LAS unsigned char* lds, const int tid, const Gemm g, const Sched& S, const Epi& E) {
;     ...
;         const bool has_next = S.next(ui + 1, nxt);
;         const gchar* nA = has_next ? (const gchar*)g.A + (size_t)nxt.pm * tstep + (size_t)nxt.pz * g.zA : cA;
;         const gchar* nB = has_next ? (const gchar*)g.Bt + (size_t)nxt.pn * tstep + (size_t)nxt.pz * g.zB : cB;
;         for (int t = 0; t < nt; t += 2) {
;             const bool last = (t == nt - 2);
;             const gchar* a1 = cA + (size_t)(t + 1) * kstep;
;             const gchar* a2 = last ? nA : cA + (size_t)(t + 2) * kstep; const gchar* b2 = last ? nB : cB + (size_t)(t + 2) * kstep;
;             const gchar* a3 = a2 + kstep; const gchar* b3 = b2 + kstep;
;             PG8_LDB(B0, 0, 0); PG8_LDB(B1, 0, 1); PG8_SCHED; PG8_LDA(At, 0, 0); PG8_STAGE(PG8_SA(1, 1), a1 + hstep, voffA);
;             PG8_WAIT_V(8); PG8_WAIT_L(0); PG8_BAR; PG8_MMA(0, 0, At, B0); PG8_MMA(0, 1, At, B1); PG8_BAR; PG8_SCHED;
;     ...
; #pragma unroll
;         for (int a = 0; a < 2; ++a)
; #pragma unroll
;             for (int b = 0; b < 2; ++b)
; #pragma unroll
;                 for (int m = 0; m < 4; ++m)
; #pragma unroll
;                     for (int n = 0; n < 2; ++n) acc[a][b][m][n] = (f32x4){0.f, 0.f, 0.f, 0.f};
;         cur = nxt; cA = nA; cB = nB; ++ui;
.LBB0_396:
	s_ashr_i32 s57, s56, 31
	s_lshl_b64 s[50:51], s[56:57], 19
	s_add_u32 s58, s64, s50
	s_addc_u32 s59, s41, s51
	s_and_b64 s[50:51], s[6:7], exec
	s_cselect_b32 s1, s59, s93
	s_cselect_b32 s31, s58, s92
	s_ashr_i32 s17, s16, 31
	s_lshl_b64 s[50:51], s[16:17], 19
	s_add_u32 s60, s23, s50
	s_addc_u32 s61, s24, s51
	s_and_b64 s[50:51], s[6:7], exec
	s_cselect_b32 s17, s61, s21
	s_cselect_b32 s50, s60, s20
	s_add_u32 s51, s20, 0x100
	s_addc_u32 s52, s21, 0
	s_add_u32 s92, s92, 0x40080
	v_mov_b32_e32 v2, 0
	s_addc_u32 s93, s93, 0
	s_mov_b32 s53, -2
	s_waitcnt lgkmcnt(0)
	v_mov_b32_e32 v3, v2
	v_mov_b32_e32 v4, v2
	v_mov_b32_e32 v5, v2
	v_mov_b32_e32 v6, v2
	v_mov_b32_e32 v7, v2
	v_mov_b32_e32 v8, v2
	v_mov_b32_e32 v9, v2
	v_mov_b32_e32 v18, v2
	v_mov_b32_e32 v19, v2
	v_mov_b32_e32 v20, v2
	v_mov_b32_e32 v21, v2
	v_mov_b32_e32 v22, v2
	v_mov_b32_e32 v23, v2
	v_mov_b32_e32 v24, v2
	v_mov_b32_e32 v25, v2
	v_mov_b32_e32 v34, v2
	v_mov_b32_e32 v35, v2
	v_mov_b32_e32 v36, v2
	v_mov_b32_e32 v37, v2
	v_mov_b32_e32 v38, v2
	v_mov_b32_e32 v39, v2
	v_mov_b32_e32 v40, v2
	v_mov_b32_e32 v41, v2
	v_mov_b32_e32 v50, v2
	v_mov_b32_e32 v51, v2
	v_mov_b32_e32 v52, v2
	v_mov_b32_e32 v53, v2
	v_mov_b32_e32 v54, v2
	v_mov_b32_e32 v55, v2
	v_mov_b32_e32 v56, v2
	v_mov_b32_e32 v57, v2
	v_mov_b32_e32 v10, v2
	v_mov_b32_e32 v11, v2
	v_mov_b32_e32 v12, v2
	v_mov_b32_e32 v13, v2
	v_mov_b32_e32 v14, v2
	v_mov_b32_e32 v15, v2
	v_mov_b32_e32 v16, v2
	v_mov_b32_e32 v17, v2
	v_mov_b32_e32 v26, v2
	v_mov_b32_e32 v27, v2
	v_mov_b32_e32 v28, v2
	v_mov_b32_e32 v29, v2
	v_mov_b32_e32 v30, v2
	v_mov_b32_e32 v31, v2
	v_mov_b32_e32 v32, v2
	v_mov_b32_e32 v33, v2
	v_mov_b32_e32 v42, v2
	v_mov_b32_e32 v43, v2
	v_mov_b32_e32 v44, v2
	v_mov_b32_e32 v45, v2
	v_mov_b32_e32 v46, v2
	v_mov_b32_e32 v47, v2
	v_mov_b32_e32 v48, v2
	v_mov_b32_e32 v49, v2
	v_mov_b32_e32 v58, v2
	v_mov_b32_e32 v59, v2
	v_mov_b32_e32 v60, v2
	v_mov_b32_e32 v61, v2
	v_mov_b32_e32 v62, v2
	v_mov_b32_e32 v63, v2
	v_mov_b32_e32 v64, v2
	v_mov_b32_e32 v65, v2
	v_mov_b32_e32 v66, v2
	v_mov_b32_e32 v67, v2
	v_mov_b32_e32 v68, v2
	v_mov_b32_e32 v69, v2
	v_mov_b32_e32 v70, v2
	v_mov_b32_e32 v71, v2
	v_mov_b32_e32 v72, v2
	v_mov_b32_e32 v73, v2
	s_waitcnt vmcnt(0)
	v_mov_b32_e32 v82, v2
	v_mov_b32_e32 v83, v2
	v_mov_b32_e32 v84, v2
	v_mov_b32_e32 v85, v2
	v_mov_b32_e32 v86, v2
	v_mov_b32_e32 v87, v2
	v_mov_b32_e32 v88, v2
	v_mov_b32_e32 v89, v2
	v_mov_b32_e32 v98, v2
	v_mov_b32_e32 v99, v2
	v_mov_b32_e32 v100, v2
	v_mov_b32_e32 v101, v2
	v_mov_b32_e32 v102, v2
	v_mov_b32_e32 v103, v2
	v_mov_b32_e32 v104, v2
	v_mov_b32_e32 v105, v2
	v_mov_b32_e32 v114, v2
	v_mov_b32_e32 v115, v2
	v_mov_b32_e32 v116, v2
	v_mov_b32_e32 v117, v2
	v_mov_b32_e32 v118, v2
	v_mov_b32_e32 v119, v2
	v_mov_b32_e32 v120, v2
	v_mov_b32_e32 v121, v2
	v_mov_b32_e32 v74, v2
	v_mov_b32_e32 v75, v2
	v_mov_b32_e32 v76, v2
	v_mov_b32_e32 v77, v2
	v_mov_b32_e32 v78, v2
	v_mov_b32_e32 v79, v2
	v_mov_b32_e32 v80, v2
	v_mov_b32_e32 v81, v2
	v_mov_b32_e32 v90, v2
	v_mov_b32_e32 v91, v2
	v_mov_b32_e32 v92, v2
	v_mov_b32_e32 v93, v2
	v_mov_b32_e32 v94, v2
	v_mov_b32_e32 v95, v2
	v_mov_b32_e32 v96, v2
	v_mov_b32_e32 v97, v2
	v_mov_b32_e32 v106, v2
	v_mov_b32_e32 v107, v2
	v_mov_b32_e32 v108, v2
	v_mov_b32_e32 v109, v2
	v_mov_b32_e32 v110, v2
	v_mov_b32_e32 v111, v2
	v_mov_b32_e32 v112, v2
	v_mov_b32_e32 v113, v2
	v_mov_b32_e32 v122, v2
	v_mov_b32_e32 v123, v2
	v_mov_b32_e32 v124, v2
	v_mov_b32_e32 v125, v2
	v_mov_b32_e32 v126, v2
	v_mov_b32_e32 v127, v2
	v_mov_b32_e32 v128, v2
	v_mov_b32_e32 v129, v2
	v_add_u32_e32 v195, 0x80, v0
	v_add_u32_e32 v201, 0x80, v158
	v_add_u32_e32 v221, 0x80, v154
	v_add_u32_e32 v223, 0x80, v156
.LBB0_397:
	s_add_u32 s20, s92, 0xfffc0080
	s_addc_u32 s21, s93, -1
	s_add_i32 s29, 0, 0x10000
	s_cmp_eq_u32 s53, 12
	s_cselect_b32 s73, s1, s21
	s_cselect_b32 s72, s31, s20
	s_cselect_b32 s21, s17, s52
	s_cselect_b32 s20, s50, s51
	s_add_i32 s30, 0, 0x14000
	v_add_u32_e32 v142, s29, v177
	v_add_u32_e32 v168, s30, v177
	ds_read_b128 v[130:133], v142
	ds_read_b128 v[134:137], v142 offset:1024
	ds_read_b128 v[138:141], v142 offset:2048
	ds_read_b128 v[142:145], v142 offset:3072
	ds_read_b128 v[146:149], v168
	ds_read_b128 v[150:153], v168 offset:1024
	ds_read_b128 v[164:167], v168 offset:2048
	ds_read_b128 v[168:171], v168 offset:3072
	s_add_i32 m0, s43, 0xc000
	ds_read_b128 v[172:175], v181
	ds_read_b128 v[182:185], v181 offset:1024
	ds_read_b128 v[186:189], v181 offset:2048
	ds_read_b128 v[190:193], v181 offset:3072
	ds_read_b128 v[204:207], v181 offset:4096
	ds_read_b128 v[208:211], v181 offset:5120
	ds_read_b128 v[212:215], v181 offset:6144
	ds_read_b128 v[216:219], v181 offset:7168
	global_load_lds_dwordx4 v162, s[92:93]
	s_add_i32 m0, s43, 0xe000
	s_nop 0
	global_load_lds_dwordx4 v160, s[92:93]
	s_waitcnt vmcnt(8)
	s_waitcnt lgkmcnt(0)
	s_barrier
; #define PG8_STAGE(bufoff, gbase, voff) do { _Pragma("unroll") for (int _i = 0; _i < 2; ++_i) \
;         __builtin_amdgcn_global_load_lds((const gunsigned*)((const gchar*)(gbase) + (voff)[_i]), (LAS unsigned*)(lds + (bufoff) + ldsw + _i * 8192), 16, 0, 0); } while (0)
; #define PG8_LDA(dst, b, h) do { _Pragma("unroll") for (int m = 0; m < 4; ++m) _Pragma("unroll") for (int k = 0; k < 2; ++k) dst[m][k] = *(const LAS bf16x8*)(lds + PG8_SA(b, h) + aoff + m * 2048 + k * 1024); } while (0)
; #define PG8_LDB(dst, b, h) do { _Pragma("unroll") for (int n = 0; n < 2; ++n) _Pragma("unroll") for (int k = 0; k < 2; ++k) dst[n][k] = *(const LAS bf16x8*)(lds + PG8_SB(b, h) + boff + n * 2048 + k * 1024); } while (0)
; #define PG8_MMA(ai, bj, At, Bt) do { __builtin_amdgcn_s_setprio(1); _Pragma("unroll") for (int m = 0; m < 4; ++m) _Pragma("unroll") for (int n = 0; n < 2; ++n) _Pragma("unroll") for (int k = 0; k < 2; ++k) \
;         acc[ai][bj][m][n] = __builtin_amdgcn_mfma_f32_16x16x32_bf16(Bt[n][k], At[m][k], acc[ai][bj][m][n], 0, 0, 0); __builtin_amdgcn_s_setprio(0); } while (0)
; #define PG8_WAIT_V(n) asm volatile("s_waitcnt vmcnt(" #n ")" ::: "memory")
; #define PG8_WAIT_L(n) asm volatile("s_waitcnt lgkmcnt(" #n ")" ::: "memory")
; #define PG8_BAR __builtin_amdgcn_s_barrier()
; #define PG8_SCHED __builtin_amdgcn_sched_barrier(0)
; template <class Epi, class Sched>
; __device__ __forceinline__ void gemm_phase(LAS unsigned char* lds, const int tid, const Gemm g, const Sched& S, const Epi& E) {
;     ...
;             PG8_WAIT_V(8); PG8_WAIT_L(0); PG8_BAR; PG8_MMA(0, 0, At, B0); PG8_MMA(0, 1, At, B1); PG8_BAR; PG8_SCHED;
;             PG8_LDA(At, 0, 1); PG8_STAGE(PG8_SB(0, 0), b2, voffB); PG8_STAGE(PG8_SB(0, 1), b2 + hstep, voffB); PG8_STAGE(PG8_SA(0, 0), a2, voffA);
;             PG8_WAIT_V(8); PG8_WAIT_L(0); PG8_BAR; PG8_MMA(1, 0, At, B0); PG8_MMA(1, 1, At, B1); PG8_BAR; PG8_SCHED;
;             PG8_LDB(B0, 1, 0); PG8_LDB(B1, 1, 1); PG8_SCHED; PG8_LDA(At, 1, 0); PG8_STAGE(PG8_SA(0, 1), a2 + hstep, voffA);
	s_setprio 1
	s_waitcnt lgkmcnt(0)
	v_mfma_f32_16x16x32_bf16 v[126:129], v[130:133], v[172:175], v[126:129]
	v_mfma_f32_16x16x32_bf16 v[122:125], v[138:141], v[172:175], v[122:125]
	v_mfma_f32_16x16x32_bf16 v[110:113], v[130:133], v[186:189], v[110:113]
	v_mfma_f32_16x16x32_bf16 v[106:109], v[138:141], v[186:189], v[106:109]
	v_mfma_f32_16x16x32_bf16 v[94:97], v[130:133], v[204:207], v[94:97]
	v_mfma_f32_16x16x32_bf16 v[90:93], v[138:141], v[204:207], v[90:93]
	v_mfma_f32_16x16x32_bf16 v[78:81], v[130:133], v[212:215], v[78:81]
	v_mfma_f32_16x16x32_bf16 v[74:77], v[138:141], v[212:215], v[74:77]
	v_mfma_f32_16x16x32_bf16 v[126:129], v[134:137], v[182:185], v[126:129]
	v_mfma_f32_16x16x32_bf16 v[122:125], v[142:145], v[182:185], v[122:125]
	v_mfma_f32_16x16x32_bf16 v[110:113], v[134:137], v[190:193], v[110:113]
	v_mfma_f32_16x16x32_bf16 v[106:109], v[142:145], v[190:193], v[106:109]
	v_mfma_f32_16x16x32_bf16 v[94:97], v[134:137], v[208:211], v[94:97]
	v_mfma_f32_16x16x32_bf16 v[90:93], v[142:145], v[208:211], v[90:93]
	v_mfma_f32_16x16x32_bf16 v[78:81], v[134:137], v[216:219], v[78:81]
	v_mfma_f32_16x16x32_bf16 v[74:77], v[142:145], v[216:219], v[74:77]
	s_setprio 0
	s_setprio 1
	v_mfma_f32_16x16x32_bf16 v[118:121], v[146:149], v[172:175], v[118:121]
	v_mfma_f32_16x16x32_bf16 v[114:117], v[164:167], v[172:175], v[114:117]
	v_mfma_f32_16x16x32_bf16 v[102:105], v[146:149], v[186:189], v[102:105]
	v_mfma_f32_16x16x32_bf16 v[98:101], v[164:167], v[186:189], v[98:101]
	v_mfma_f32_16x16x32_bf16 v[86:89], v[146:149], v[204:207], v[86:89]
	v_mfma_f32_16x16x32_bf16 v[82:85], v[164:167], v[204:207], v[82:85]
	v_mfma_f32_16x16x32_bf16 v[70:73], v[146:149], v[212:215], v[70:73]
	v_mfma_f32_16x16x32_bf16 v[66:69], v[164:167], v[212:215], v[66:69]
	v_mfma_f32_16x16x32_bf16 v[118:121], v[150:153], v[182:185], v[118:121]
	v_mfma_f32_16x16x32_bf16 v[114:117], v[168:171], v[182:185], v[114:117]
	v_mfma_f32_16x16x32_bf16 v[102:105], v[150:153], v[190:193], v[102:105]
	v_mfma_f32_16x16x32_bf16 v[98:101], v[168:171], v[190:193], v[98:101]
	v_mfma_f32_16x16x32_bf16 v[86:89], v[150:153], v[208:211], v[86:89]
	v_mfma_f32_16x16x32_bf16 v[82:85], v[168:171], v[208:211], v[82:85]
	v_mfma_f32_16x16x32_bf16 v[70:73], v[150:153], v[216:219], v[70:73]
	v_mfma_f32_16x16x32_bf16 v[66:69], v[168:171], v[216:219], v[66:69]
	s_setprio 0
	s_barrier
	s_add_i32 s29, s29, s15
	s_mov_b32 m0, s29
	ds_read_b128 v[172:175], v181 offset:16384
	ds_read_b128 v[182:185], v181 offset:17408
	ds_read_b128 v[186:189], v181 offset:18432
	ds_read_b128 v[190:193], v181 offset:19456
	ds_read_b128 v[204:207], v181 offset:20480
	ds_read_b128 v[208:211], v181 offset:21504
	ds_read_b128 v[212:215], v181 offset:22528
	ds_read_b128 v[216:219], v181 offset:23552
	global_load_lds_dwordx4 v0, s[20:21]
	s_add_i32 m0, s29, 0x2000
	s_add_u32 s54, s20, 0x40000
	s_addc_u32 s55, s21, 0
	s_add_i32 s29, s30, s15
	global_load_lds_dwordx4 v158, s[20:21]
	s_mov_b32 m0, s29
	s_nop 0
	global_load_lds_dwordx4 v0, s[54:55]
	s_add_i32 m0, s29, 0x2000
	s_nop 0
	global_load_lds_dwordx4 v158, s[54:55]
	s_mov_b32 m0, s43
	s_nop 0
	global_load_lds_dwordx4 v154, s[72:73]
	s_mov_b32 m0, s44
	s_nop 0
	global_load_lds_dwordx4 v156, s[72:73]
	s_waitcnt vmcnt(8)
	s_waitcnt lgkmcnt(0)
	s_barrier
	s_setprio 1
	s_waitcnt lgkmcnt(0)
	v_mfma_f32_16x16x32_bf16 v[62:65], v[130:133], v[172:175], v[62:65]
	v_mfma_f32_16x16x32_bf16 v[58:61], v[138:141], v[172:175], v[58:61]
	v_mfma_f32_16x16x32_bf16 v[46:49], v[130:133], v[186:189], v[46:49]
	v_mfma_f32_16x16x32_bf16 v[42:45], v[138:141], v[186:189], v[42:45]
	v_mfma_f32_16x16x32_bf16 v[30:33], v[130:133], v[204:207], v[30:33]
	v_mfma_f32_16x16x32_bf16 v[26:29], v[138:141], v[204:207], v[26:29]
	v_mfma_f32_16x16x32_bf16 v[14:17], v[130:133], v[212:215], v[14:17]
	v_mfma_f32_16x16x32_bf16 v[10:13], v[138:141], v[212:215], v[10:13]
	v_mfma_f32_16x16x32_bf16 v[62:65], v[134:137], v[182:185], v[62:65]
	v_mfma_f32_16x16x32_bf16 v[58:61], v[142:145], v[182:185], v[58:61]
	v_mfma_f32_16x16x32_bf16 v[46:49], v[134:137], v[190:193], v[46:49]
	v_mfma_f32_16x16x32_bf16 v[42:45], v[142:145], v[190:193], v[42:45]
	v_mfma_f32_16x16x32_bf16 v[30:33], v[134:137], v[208:211], v[30:33]
	v_mfma_f32_16x16x32_bf16 v[26:29], v[142:145], v[208:211], v[26:29]
	v_mfma_f32_16x16x32_bf16 v[14:17], v[134:137], v[216:219], v[14:17]
	v_mfma_f32_16x16x32_bf16 v[10:13], v[142:145], v[216:219], v[10:13]
	s_setprio 0
	s_setprio 1
	v_mfma_f32_16x16x32_bf16 v[54:57], v[146:149], v[172:175], v[54:57]
	v_mfma_f32_16x16x32_bf16 v[50:53], v[164:167], v[172:175], v[50:53]
	v_mfma_f32_16x16x32_bf16 v[38:41], v[146:149], v[186:189], v[38:41]
	v_mfma_f32_16x16x32_bf16 v[34:37], v[164:167], v[186:189], v[34:37]
	v_mfma_f32_16x16x32_bf16 v[22:25], v[146:149], v[204:207], v[22:25]
	v_mfma_f32_16x16x32_bf16 v[18:21], v[164:167], v[204:207], v[18:21]
	v_mfma_f32_16x16x32_bf16 v[6:9], v[146:149], v[212:215], v[6:9]
	v_mfma_f32_16x16x32_bf16 v[2:5], v[164:167], v[212:215], v[2:5]
	v_mfma_f32_16x16x32_bf16 v[54:57], v[150:153], v[182:185], v[54:57]
	v_mfma_f32_16x16x32_bf16 v[50:53], v[168:171], v[182:185], v[50:53]
	v_mfma_f32_16x16x32_bf16 v[38:41], v[150:153], v[190:193], v[38:41]
	v_mfma_f32_16x16x32_bf16 v[34:37], v[168:171], v[190:193], v[34:37]
	v_mfma_f32_16x16x32_bf16 v[22:25], v[150:153], v[208:211], v[22:25]
	v_mfma_f32_16x16x32_bf16 v[18:21], v[168:171], v[208:211], v[18:21]
	v_mfma_f32_16x16x32_bf16 v[6:9], v[150:153], v[216:219], v[6:9]
	v_mfma_f32_16x16x32_bf16 v[2:5], v[168:171], v[216:219], v[2:5]
	s_setprio 0
	s_barrier
; #define PG8_STAGE(bufoff, gbase, voff) do { _Pragma("unroll") for (int _i = 0; _i < 2; ++_i) \
;         __builtin_amdgcn_global_load_lds((const gunsigned*)((const gchar*)(gbase) + (voff)[_i]), (LAS unsigned*)(lds + (bufoff) + ldsw + _i * 8192), 16, 0, 0); } while (0)
; #define PG8_LDA(dst, b, h) do { _Pragma("unroll") for (int m = 0; m < 4; ++m) _Pragma("unroll") for (int k = 0; k < 2; ++k) dst[m][k] = *(const LAS bf16x8*)(lds + PG8_SA(b, h) + aoff + m * 2048 + k * 1024); } while (0)
; #define PG8_LDB(dst, b, h) do { _Pragma("unroll") for (int n = 0; n < 2; ++n) _Pragma("unroll") for (int k = 0; k < 2; ++k) dst[n][k] = *(const LAS bf16x8*)(lds + PG8_SB(b, h) + boff + n * 2048 + k * 1024); } while (0)
; #define PG8_MMA(ai, bj, At, Bt) do { __builtin_amdgcn_s_setprio(1); _Pragma("unroll") for (int m = 0; m < 4; ++m) _Pragma("unroll") for (int n = 0; n < 2; ++n) _Pragma("unroll") for (int k = 0; k < 2; ++k) \
;         acc[ai][bj][m][n] = __builtin_amdgcn_mfma_f32_16x16x32_bf16(Bt[n][k], At[m][k], acc[ai][bj][m][n], 0, 0, 0); __builtin_amdgcn_s_setprio(0); } while (0)
; #define PG8_WAIT_V(n) asm volatile("s_waitcnt vmcnt(" #n ")" ::: "memory")
; #define PG8_WAIT_L(n) asm volatile("s_waitcnt lgkmcnt(" #n ")" ::: "memory")
; #define PG8_BAR __builtin_amdgcn_s_barrier()
; #define PG8_SCHED __builtin_amdgcn_sched_barrier(0)
; template <class Epi, class Sched>
; __device__ __forceinline__ void gemm_phase(LAS unsigned char* lds, const int tid, const Gemm g, const Sched& S, const Epi& E) {
;     ...
;             PG8_LDB(B0, 1, 0); PG8_LDB(B1, 1, 1); PG8_SCHED; PG8_LDA(At, 1, 0); PG8_STAGE(PG8_SA(0, 1), a2 + hstep, voffA);
;             PG8_WAIT_V(8); PG8_WAIT_L(0); PG8_BAR; PG8_MMA(0, 0, At, B0); PG8_MMA(0, 1, At, B1); PG8_BAR; PG8_SCHED;
;             PG8_LDA(At, 1, 1); PG8_STAGE(PG8_SB(1, 0), b3, voffB); PG8_STAGE(PG8_SB(1, 1), b3 + hstep, voffB); PG8_STAGE(PG8_SA(1, 0), a3, voffA);
;             PG8_WAIT_V(8); PG8_WAIT_L(0); PG8_BAR; PG8_MMA(1, 0, At, B0); PG8_MMA(1, 1, At, B1); PG8_BAR; PG8_SCHED;
;         }
	s_add_i32 s29, 0, 0x18000
	s_add_i32 s30, 0, 0x1c000
	v_add_u32_e32 v142, s29, v177
	v_add_u32_e32 v168, s30, v177
	ds_read_b128 v[130:133], v142
	ds_read_b128 v[134:137], v142 offset:1024
	ds_read_b128 v[138:141], v142 offset:2048
	ds_read_b128 v[142:145], v142 offset:3072
	ds_read_b128 v[146:149], v168
	ds_read_b128 v[150:153], v168 offset:1024
	ds_read_b128 v[164:167], v168 offset:2048
	ds_read_b128 v[168:171], v168 offset:3072
	s_add_u32 s54, s72, 0x40000
	s_addc_u32 s55, s73, 0
	s_mov_b32 m0, s45
	ds_read_b128 v[172:175], v181 offset:32768
	ds_read_b128 v[182:185], v181 offset:33792
	ds_read_b128 v[186:189], v181 offset:34816
	ds_read_b128 v[190:193], v181 offset:35840
	ds_read_b128 v[204:207], v181 offset:36864
	ds_read_b128 v[208:211], v181 offset:37888
	ds_read_b128 v[212:215], v181 offset:38912
	ds_read_b128 v[216:219], v181 offset:39936
	global_load_lds_dwordx4 v154, s[54:55]
	s_mov_b32 m0, s46
	s_nop 0
	global_load_lds_dwordx4 v156, s[54:55]
	s_waitcnt vmcnt(8)
	s_waitcnt lgkmcnt(0)
	s_barrier
	s_setprio 1
	s_waitcnt lgkmcnt(0)
	v_mfma_f32_16x16x32_bf16 v[126:129], v[130:133], v[172:175], v[126:129]
	v_mfma_f32_16x16x32_bf16 v[122:125], v[138:141], v[172:175], v[122:125]
	v_mfma_f32_16x16x32_bf16 v[110:113], v[130:133], v[186:189], v[110:113]
	v_mfma_f32_16x16x32_bf16 v[106:109], v[138:141], v[186:189], v[106:109]
	v_mfma_f32_16x16x32_bf16 v[94:97], v[130:133], v[204:207], v[94:97]
	v_mfma_f32_16x16x32_bf16 v[90:93], v[138:141], v[204:207], v[90:93]
	v_mfma_f32_16x16x32_bf16 v[78:81], v[130:133], v[212:215], v[78:81]
	v_mfma_f32_16x16x32_bf16 v[74:77], v[138:141], v[212:215], v[74:77]
	v_mfma_f32_16x16x32_bf16 v[126:129], v[134:137], v[182:185], v[126:129]
	v_mfma_f32_16x16x32_bf16 v[122:125], v[142:145], v[182:185], v[122:125]
	v_mfma_f32_16x16x32_bf16 v[110:113], v[134:137], v[190:193], v[110:113]
	v_mfma_f32_16x16x32_bf16 v[106:109], v[142:145], v[190:193], v[106:109]
	v_mfma_f32_16x16x32_bf16 v[94:97], v[134:137], v[208:211], v[94:97]
	v_mfma_f32_16x16x32_bf16 v[90:93], v[142:145], v[208:211], v[90:93]
	v_mfma_f32_16x16x32_bf16 v[78:81], v[134:137], v[216:219], v[78:81]
	v_mfma_f32_16x16x32_bf16 v[74:77], v[142:145], v[216:219], v[74:77]
	s_setprio 0
	s_setprio 1
	v_mfma_f32_16x16x32_bf16 v[118:121], v[146:149], v[172:175], v[118:121]
	v_mfma_f32_16x16x32_bf16 v[114:117], v[164:167], v[172:175], v[114:117]
	v_mfma_f32_16x16x32_bf16 v[102:105], v[146:149], v[186:189], v[102:105]
	v_mfma_f32_16x16x32_bf16 v[98:101], v[164:167], v[186:189], v[98:101]
	v_mfma_f32_16x16x32_bf16 v[86:89], v[146:149], v[204:207], v[86:89]
	v_mfma_f32_16x16x32_bf16 v[82:85], v[164:167], v[204:207], v[82:85]
	v_mfma_f32_16x16x32_bf16 v[70:73], v[146:149], v[212:215], v[70:73]
	v_mfma_f32_16x16x32_bf16 v[66:69], v[164:167], v[212:215], v[66:69]
	v_mfma_f32_16x16x32_bf16 v[118:121], v[150:153], v[182:185], v[118:121]
	v_mfma_f32_16x16x32_bf16 v[114:117], v[168:171], v[182:185], v[114:117]
	v_mfma_f32_16x16x32_bf16 v[102:105], v[150:153], v[190:193], v[102:105]
	v_mfma_f32_16x16x32_bf16 v[98:101], v[168:171], v[190:193], v[98:101]
	v_mfma_f32_16x16x32_bf16 v[86:89], v[150:153], v[208:211], v[86:89]
	v_mfma_f32_16x16x32_bf16 v[82:85], v[168:171], v[208:211], v[82:85]
	v_mfma_f32_16x16x32_bf16 v[70:73], v[150:153], v[216:219], v[70:73]
	v_mfma_f32_16x16x32_bf16 v[66:69], v[168:171], v[216:219], v[66:69]
	s_setprio 0
	s_barrier
	s_add_i32 s29, s29, s15
	s_mov_b32 m0, s29
	ds_read_b128 v[172:175], v181 offset:49152
	ds_read_b128 v[182:185], v181 offset:50176
	ds_read_b128 v[186:189], v181 offset:51200
	ds_read_b128 v[190:193], v181 offset:52224
	ds_read_b128 v[204:207], v181 offset:53248
	ds_read_b128 v[208:211], v181 offset:54272
	ds_read_b128 v[212:215], v181 offset:55296
	ds_read_b128 v[216:219], v181 offset:56320
	global_load_lds_dwordx4 v195, s[20:21]
	s_add_i32 m0, s29, 0x2000
	s_add_i32 s29, s30, s15
	global_load_lds_dwordx4 v201, s[20:21]
	s_add_u32 s20, s20, 0x40080
	s_addc_u32 s21, s21, 0
	s_mov_b32 m0, s29
	s_nop 0
	global_load_lds_dwordx4 v0, s[20:21]
	s_add_i32 m0, s29, 0x2000
	s_nop 0
	global_load_lds_dwordx4 v158, s[20:21]
	s_mov_b32 m0, s12
	s_nop 0
	global_load_lds_dwordx4 v221, s[72:73]
	s_mov_b32 m0, s47
	s_nop 0
	global_load_lds_dwordx4 v223, s[72:73]
	s_waitcnt vmcnt(8)
	s_waitcnt lgkmcnt(0)
	s_barrier
	s_setprio 1
	s_waitcnt lgkmcnt(0)
	v_mfma_f32_16x16x32_bf16 v[62:65], v[130:133], v[172:175], v[62:65]
	v_mfma_f32_16x16x32_bf16 v[58:61], v[138:141], v[172:175], v[58:61]
	v_mfma_f32_16x16x32_bf16 v[46:49], v[130:133], v[186:189], v[46:49]
	v_mfma_f32_16x16x32_bf16 v[42:45], v[138:141], v[186:189], v[42:45]
	v_mfma_f32_16x16x32_bf16 v[30:33], v[130:133], v[204:207], v[30:33]
	v_mfma_f32_16x16x32_bf16 v[26:29], v[138:141], v[204:207], v[26:29]
	v_mfma_f32_16x16x32_bf16 v[14:17], v[130:133], v[212:215], v[14:17]
	v_mfma_f32_16x16x32_bf16 v[10:13], v[138:141], v[212:215], v[10:13]
	v_mfma_f32_16x16x32_bf16 v[62:65], v[134:137], v[182:185], v[62:65]
	v_mfma_f32_16x16x32_bf16 v[58:61], v[142:145], v[182:185], v[58:61]
	v_mfma_f32_16x16x32_bf16 v[46:49], v[134:137], v[190:193], v[46:49]
	v_mfma_f32_16x16x32_bf16 v[42:45], v[142:145], v[190:193], v[42:45]
	v_mfma_f32_16x16x32_bf16 v[30:33], v[134:137], v[208:211], v[30:33]
	v_mfma_f32_16x16x32_bf16 v[26:29], v[142:145], v[208:211], v[26:29]
	v_mfma_f32_16x16x32_bf16 v[14:17], v[134:137], v[216:219], v[14:17]
	v_mfma_f32_16x16x32_bf16 v[10:13], v[142:145], v[216:219], v[10:13]
	s_setprio 0
	s_setprio 1
	v_mfma_f32_16x16x32_bf16 v[54:57], v[146:149], v[172:175], v[54:57]
	v_mfma_f32_16x16x32_bf16 v[50:53], v[164:167], v[172:175], v[50:53]
	v_mfma_f32_16x16x32_bf16 v[38:41], v[146:149], v[186:189], v[38:41]
	v_mfma_f32_16x16x32_bf16 v[34:37], v[164:167], v[186:189], v[34:37]
	v_mfma_f32_16x16x32_bf16 v[22:25], v[146:149], v[204:207], v[22:25]
	v_mfma_f32_16x16x32_bf16 v[18:21], v[164:167], v[204:207], v[18:21]
	v_mfma_f32_16x16x32_bf16 v[6:9], v[146:149], v[212:215], v[6:9]
	v_mfma_f32_16x16x32_bf16 v[2:5], v[164:167], v[212:215], v[2:5]
	v_mfma_f32_16x16x32_bf16 v[54:57], v[150:153], v[182:185], v[54:57]
	v_mfma_f32_16x16x32_bf16 v[50:53], v[168:171], v[182:185], v[50:53]
	v_mfma_f32_16x16x32_bf16 v[38:41], v[150:153], v[190:193], v[38:41]
	v_mfma_f32_16x16x32_bf16 v[34:37], v[168:171], v[190:193], v[34:37]
	v_mfma_f32_16x16x32_bf16 v[22:25], v[150:153], v[208:211], v[22:25]
	v_mfma_f32_16x16x32_bf16 v[18:21], v[168:171], v[208:211], v[18:21]
	v_mfma_f32_16x16x32_bf16 v[6:9], v[150:153], v[216:219], v[6:9]
	v_mfma_f32_16x16x32_bf16 v[2:5], v[168:171], v[216:219], v[2:5]
	s_setprio 0
	s_barrier
	s_add_i32 s53, s53, 2
	s_add_u32 s51, s51, 0x100
	s_addc_u32 s52, s52, 0
	s_add_u32 s92, s92, 0x100
	s_addc_u32 s93, s93, 0
	s_cmp_gt_u32 s53, 13
	s_cbranch_scc0 .LBB0_397
	s_and_b64 vcc, exec, s[10:11]
	s_cbranch_vccz .LBB0_400
	s_barrier

;     __device__ bool next(int i, Unit& u) const { if (!b.next(i / 3, u)) return false; u.pz = i % 3; return true; }
; #define PG8_STAGE(bufoff, gbase, voff) do { _Pragma("unroll") for (int _i = 0; _i < 2; ++_i) \
;         __builtin_amdgcn_global_load_lds((const gunsigned*)((const gchar*)(gbase) + (voff)[_i]), (LAS unsigned*)(lds + (bufoff) + ldsw + _i * 8192), 16, 0, 0); } while (0)
; #define PG8_LDA(dst, b, h) do { _Pragma("unroll") for (int m = 0; m < 4; ++m) _Pragma("unroll") for (int k = 0; k < 2; ++k) dst[m][k] = *(const LAS bf16x8*)(lds + PG8_SA(b, h) + aoff + m * 2048 + k * 1024); } while (0)
; #define PG8_LDB(dst, b, h) do { _Pragma("unroll") for (int n = 0; n < 2; ++n) _Pragma("unroll") for (int k = 0; k < 2; ++k) dst[n][k] = *(const LAS bf16x8*)(lds + PG8_SB(b, h) + boff + n * 2048 + k * 1024); } while (0)
; #define PG8_WAIT_V(n) asm volatile("s_waitcnt vmcnt(" #n ")" ::: "memory")
; #define PG8_WAIT_L(n) asm volatile("s_waitcnt lgkmcnt(" #n ")" ::: "memory")
; template <class Epi, class Sched>
; __device__ __forceinline__ void gemm_phase(LAS unsigned char* lds, const int tid, const Gemm g, const Sched& S, const Epi& E) {
;     ...
;         const bool has_next = S.next(ui + 1, nxt);
;         const gchar* nA = has_next ? (const gchar*)g.A + (size_t)nxt.pm * tstep + (size_t)nxt.pz * g.zA : cA;
;         const gchar* nB = has_next ? (const gchar*)g.Bt + (size_t)nxt.pn * tstep + (size_t)nxt.pz * g.zB : cB;
;         for (int t = 0; t < nt; t += 2) {
;             const bool last = (t == nt - 2);
;             const gchar* a1 = cA + (size_t)(t + 1) * kstep;
;             const gchar* a2 = last ? nA : cA + (size_t)(t + 2) * kstep; const gchar* b2 = last ? nB : cB + (size_t)(t + 2) * kstep;
;             const gchar* a3 = a2 + kstep; const gchar* b3 = b2 + kstep;
;             PG8_LDB(B0, 0, 0); PG8_LDB(B1, 0, 1); PG8_SCHED; PG8_LDA(At, 0, 0); PG8_STAGE(PG8_SA(1, 1), a1 + hstep, voffA);
;             PG8_WAIT_V(8); PG8_WAIT_L(0); PG8_BAR; PG8_MMA(0, 0, At, B0); PG8_MMA(0, 1, At, B1); PG8_BAR; PG8_SCHED;
;     ...
; #pragma unroll
;         for (int a = 0; a < 2; ++a)
; #pragma unroll
;             for (int b = 0; b < 2; ++b)
; #pragma unroll
;                 for (int m = 0; m < 4; ++m)
; #pragma unroll
;                     for (int n = 0; n < 2; ++n) acc[a][b][m][n] = (f32x4){0.f, 0.f, 0.f, 0.f};
;         cur = nxt; cA = nA; cB = nB; ++ui;
.LBB0_443:
	s_ashr_i32 s71, s70, 31
	s_lshl_b64 s[52:53], s[70:71], 18
	s_add_u32 s1, s74, s52
	s_addc_u32 s5, s75, s53
	s_ashr_i32 s63, s62, 31
	s_lshl_b64 s[52:53], s[62:63], 25
	s_add_u32 s56, s1, s52
	s_addc_u32 s57, s5, s53
	s_and_b64 s[52:53], s[2:3], exec
	s_cselect_b32 s1, s57, s21
	s_cselect_b32 s5, s56, s20
	s_ashr_i32 s61, s60, 31
	s_lshl_b64 s[52:53], s[60:61], 18
	s_add_u32 s15, s43, s52
	s_addc_u32 s23, s92, s53
	s_lshl_b64 s[52:53], s[62:63], 20
	s_add_u32 s58, s15, s52
	s_addc_u32 s59, s23, s53
	s_and_b64 s[52:53], s[2:3], exec
	s_cselect_b32 s15, s59, s17
	s_cselect_b32 s23, s58, s16
	s_add_u32 s24, s16, 0x100
	s_addc_u32 s31, s17, 0
	s_add_u32 s16, s20, 0x20080
	v_mov_b32_e32 v2, 0
	s_addc_u32 s17, s21, 0
	s_mov_b32 s51, -2
	v_mov_b32_e32 v3, v2
	v_mov_b32_e32 v4, v2
	v_mov_b32_e32 v5, v2
	v_mov_b32_e32 v6, v2
	v_mov_b32_e32 v7, v2
	v_mov_b32_e32 v8, v2
	v_mov_b32_e32 v9, v2
	v_mov_b32_e32 v18, v2
	v_mov_b32_e32 v19, v2
	v_mov_b32_e32 v20, v2
	v_mov_b32_e32 v21, v2
	v_mov_b32_e32 v22, v2
	v_mov_b32_e32 v23, v2
	v_mov_b32_e32 v24, v2
	v_mov_b32_e32 v25, v2
	v_mov_b32_e32 v34, v2
	v_mov_b32_e32 v35, v2
	v_mov_b32_e32 v36, v2
	v_mov_b32_e32 v37, v2
	v_mov_b32_e32 v38, v2
	v_mov_b32_e32 v39, v2
	v_mov_b32_e32 v40, v2
	v_mov_b32_e32 v41, v2
	v_mov_b32_e32 v50, v2
	v_mov_b32_e32 v51, v2
	v_mov_b32_e32 v52, v2
	v_mov_b32_e32 v53, v2
	v_mov_b32_e32 v54, v2
	v_mov_b32_e32 v55, v2
	v_mov_b32_e32 v56, v2
	v_mov_b32_e32 v57, v2
	v_mov_b32_e32 v10, v2
	v_mov_b32_e32 v11, v2
	v_mov_b32_e32 v12, v2
	v_mov_b32_e32 v13, v2
	v_mov_b32_e32 v14, v2
	v_mov_b32_e32 v15, v2
	v_mov_b32_e32 v16, v2
	v_mov_b32_e32 v17, v2
	v_mov_b32_e32 v26, v2
	v_mov_b32_e32 v27, v2
	v_mov_b32_e32 v28, v2
	v_mov_b32_e32 v29, v2
	v_mov_b32_e32 v30, v2
	v_mov_b32_e32 v31, v2
	v_mov_b32_e32 v32, v2
	v_mov_b32_e32 v33, v2
	v_mov_b32_e32 v42, v2
	v_mov_b32_e32 v43, v2
	v_mov_b32_e32 v44, v2
	v_mov_b32_e32 v45, v2
	v_mov_b32_e32 v46, v2
	v_mov_b32_e32 v47, v2
	v_mov_b32_e32 v48, v2
	v_mov_b32_e32 v49, v2
	v_mov_b32_e32 v58, v2
	v_mov_b32_e32 v59, v2
	v_mov_b32_e32 v60, v2
	v_mov_b32_e32 v61, v2
	v_mov_b32_e32 v62, v2
	v_mov_b32_e32 v63, v2
	v_mov_b32_e32 v64, v2
	v_mov_b32_e32 v65, v2
	v_mov_b32_e32 v66, v2
	v_mov_b32_e32 v67, v2
	v_mov_b32_e32 v68, v2
	v_mov_b32_e32 v69, v2
	v_mov_b32_e32 v70, v2
	v_mov_b32_e32 v71, v2
	v_mov_b32_e32 v72, v2
	v_mov_b32_e32 v73, v2
	s_waitcnt vmcnt(0)
	v_mov_b32_e32 v82, v2
	v_mov_b32_e32 v83, v2
	v_mov_b32_e32 v84, v2
	v_mov_b32_e32 v85, v2
	v_mov_b32_e32 v86, v2
	v_mov_b32_e32 v87, v2
	v_mov_b32_e32 v88, v2
	v_mov_b32_e32 v89, v2
	v_mov_b32_e32 v98, v2
	v_mov_b32_e32 v99, v2
	v_mov_b32_e32 v100, v2
	v_mov_b32_e32 v101, v2
	v_mov_b32_e32 v102, v2
	v_mov_b32_e32 v103, v2
	v_mov_b32_e32 v104, v2
	v_mov_b32_e32 v105, v2
	v_mov_b32_e32 v114, v2
	v_mov_b32_e32 v115, v2
	v_mov_b32_e32 v116, v2
	v_mov_b32_e32 v117, v2
	v_mov_b32_e32 v118, v2
	v_mov_b32_e32 v119, v2
	v_mov_b32_e32 v120, v2
	v_mov_b32_e32 v121, v2
	v_mov_b32_e32 v74, v2
	v_mov_b32_e32 v75, v2
	v_mov_b32_e32 v76, v2
	v_mov_b32_e32 v77, v2
	v_mov_b32_e32 v78, v2
	v_mov_b32_e32 v79, v2
	v_mov_b32_e32 v80, v2
	v_mov_b32_e32 v81, v2
	v_mov_b32_e32 v90, v2
	v_mov_b32_e32 v91, v2
	v_mov_b32_e32 v92, v2
	v_mov_b32_e32 v93, v2
	v_mov_b32_e32 v94, v2
	v_mov_b32_e32 v95, v2
	v_mov_b32_e32 v96, v2
	v_mov_b32_e32 v97, v2
	v_mov_b32_e32 v106, v2
	v_mov_b32_e32 v107, v2
	v_mov_b32_e32 v108, v2
	v_mov_b32_e32 v109, v2
	v_mov_b32_e32 v110, v2
	v_mov_b32_e32 v111, v2
	v_mov_b32_e32 v112, v2
	v_mov_b32_e32 v113, v2
	v_mov_b32_e32 v124, v2
	v_mov_b32_e32 v125, v2
	v_mov_b32_e32 v126, v2
	v_mov_b32_e32 v127, v2
	v_mov_b32_e32 v128, v2
	v_mov_b32_e32 v129, v2
	v_mov_b32_e32 v130, v2
	v_mov_b32_e32 v131, v2
	v_add_u32_e32 v201, 0x80, v0
	v_add_u32_e32 v215, 0x80, v208
	v_add_u32_e32 v217, 0x80, v204
	v_add_u32_e32 v219, 0x80, v206
.LBB0_444:
	s_add_u32 s20, s16, 0xfffe0080
	s_addc_u32 s21, s17, -1
	s_add_i32 s29, 0, 0x10000
	s_cmp_eq_u32 s51, 4
	s_cselect_b32 s73, s1, s21
	s_cselect_b32 s72, s5, s20
	v_add_u32_e32 v122, s29, v242
	s_cselect_b32 s21, s15, s31
	s_cselect_b32 s20, s23, s24
	s_add_i32 s30, 0, 0x14000
	ds_read_b128 v[132:135], v122
	ds_read_b128 v[136:139], v122 offset:1024
	ds_read_b128 v[140:143], v122 offset:2048
	ds_read_b128 v[144:147], v122 offset:3072
	v_add_u32_e32 v122, s30, v242
	ds_read_b128 v[148:151], v122
	ds_read_b128 v[152:155], v122 offset:1024
	ds_read_b128 v[156:159], v122 offset:2048
	ds_read_b128 v[160:163], v122 offset:3072
	s_add_i32 m0, s93, 0xc000
	ds_read_b128 v[164:167], v244
	ds_read_b128 v[168:171], v244 offset:1024
	ds_read_b128 v[172:175], v244 offset:2048
	ds_read_b128 v[176:179], v244 offset:3072
	ds_read_b128 v[180:183], v244 offset:4096
	ds_read_b128 v[184:187], v244 offset:5120
	ds_read_b128 v[188:191], v244 offset:6144
	ds_read_b128 v[192:195], v244 offset:7168
	global_load_lds_dwordx4 v212, s[16:17]
	s_add_i32 m0, s93, 0xe000
	s_nop 0
	global_load_lds_dwordx4 v210, s[16:17]
	s_waitcnt vmcnt(8)
	s_waitcnt lgkmcnt(0)
	s_barrier
; #define PG8_STAGE(bufoff, gbase, voff) do { _Pragma("unroll") for (int _i = 0; _i < 2; ++_i) \
;         __builtin_amdgcn_global_load_lds((const gunsigned*)((const gchar*)(gbase) + (voff)[_i]), (LAS unsigned*)(lds + (bufoff) + ldsw + _i * 8192), 16, 0, 0); } while (0)
; #define PG8_LDA(dst, b, h) do { _Pragma("unroll") for (int m = 0; m < 4; ++m) _Pragma("unroll") for (int k = 0; k < 2; ++k) dst[m][k] = *(const LAS bf16x8*)(lds + PG8_SA(b, h) + aoff + m * 2048 + k * 1024); } while (0)
; #define PG8_LDB(dst, b, h) do { _Pragma("unroll") for (int n = 0; n < 2; ++n) _Pragma("unroll") for (int k = 0; k < 2; ++k) dst[n][k] = *(const LAS bf16x8*)(lds + PG8_SB(b, h) + boff + n * 2048 + k * 1024); } while (0)
; #define PG8_MMA(ai, bj, At, Bt) do { __builtin_amdgcn_s_setprio(1); _Pragma("unroll") for (int m = 0; m < 4; ++m) _Pragma("unroll") for (int n = 0; n < 2; ++n) _Pragma("unroll") for (int k = 0; k < 2; ++k) \
;         acc[ai][bj][m][n] = __builtin_amdgcn_mfma_f32_16x16x32_bf16(Bt[n][k], At[m][k], acc[ai][bj][m][n], 0, 0, 0); __builtin_amdgcn_s_setprio(0); } while (0)
; #define PG8_WAIT_V(n) asm volatile("s_waitcnt vmcnt(" #n ")" ::: "memory")
; #define PG8_WAIT_L(n) asm volatile("s_waitcnt lgkmcnt(" #n ")" ::: "memory")
; #define PG8_BAR __builtin_amdgcn_s_barrier()
; #define PG8_SCHED __builtin_amdgcn_sched_barrier(0)
; template <class Epi, class Sched>
; __device__ __forceinline__ void gemm_phase(LAS unsigned char* lds, const int tid, const Gemm g, const Sched& S, const Epi& E) {
;     ...
;             PG8_WAIT_V(8); PG8_WAIT_L(0); PG8_BAR; PG8_MMA(0, 0, At, B0); PG8_MMA(0, 1, At, B1); PG8_BAR; PG8_SCHED;
;             PG8_LDA(At, 0, 1); PG8_STAGE(PG8_SB(0, 0), b2, voffB); PG8_STAGE(PG8_SB(0, 1), b2 + hstep, voffB); PG8_STAGE(PG8_SA(0, 0), a2, voffA);
;             PG8_WAIT_V(8); PG8_WAIT_L(0); PG8_BAR; PG8_MMA(1, 0, At, B0); PG8_MMA(1, 1, At, B1); PG8_BAR; PG8_SCHED;
;             PG8_LDB(B0, 1, 0); PG8_LDB(B1, 1, 1); PG8_SCHED; PG8_LDA(At, 1, 0); PG8_STAGE(PG8_SA(0, 1), a2 + hstep, voffA);
	s_setprio 1
	s_waitcnt lgkmcnt(0)
	v_mfma_f32_16x16x32_bf16 v[128:131], v[132:135], v[164:167], v[128:131]
	v_mfma_f32_16x16x32_bf16 v[122:125], v[140:143], v[164:167], v[124:127]
	v_mfma_f32_16x16x32_bf16 v[110:113], v[132:135], v[172:175], v[110:113]
	v_mfma_f32_16x16x32_bf16 v[106:109], v[140:143], v[172:175], v[106:109]
	v_mfma_f32_16x16x32_bf16 v[94:97], v[132:135], v[180:183], v[94:97]
	v_mfma_f32_16x16x32_bf16 v[90:93], v[140:143], v[180:183], v[90:93]
	v_mfma_f32_16x16x32_bf16 v[78:81], v[132:135], v[188:191], v[78:81]
	v_mfma_f32_16x16x32_bf16 v[74:77], v[140:143], v[188:191], v[74:77]
	v_mfma_f32_16x16x32_bf16 v[128:131], v[136:139], v[168:171], v[128:131]
	v_mfma_f32_16x16x32_bf16 v[122:125], v[144:147], v[168:171], v[122:125]
	v_mfma_f32_16x16x32_bf16 v[110:113], v[136:139], v[176:179], v[110:113]
	v_mfma_f32_16x16x32_bf16 v[106:109], v[144:147], v[176:179], v[106:109]
	v_mfma_f32_16x16x32_bf16 v[94:97], v[136:139], v[184:187], v[94:97]
	v_mfma_f32_16x16x32_bf16 v[90:93], v[144:147], v[184:187], v[90:93]
	v_mfma_f32_16x16x32_bf16 v[78:81], v[136:139], v[192:195], v[78:81]
	v_mfma_f32_16x16x32_bf16 v[74:77], v[144:147], v[192:195], v[74:77]
	s_setprio 0
	s_setprio 1
	v_mfma_f32_16x16x32_bf16 v[118:121], v[148:151], v[164:167], v[118:121]
	v_mfma_f32_16x16x32_bf16 v[114:117], v[156:159], v[164:167], v[114:117]
	v_mfma_f32_16x16x32_bf16 v[102:105], v[148:151], v[172:175], v[102:105]
	v_mfma_f32_16x16x32_bf16 v[98:101], v[156:159], v[172:175], v[98:101]
	v_mfma_f32_16x16x32_bf16 v[86:89], v[148:151], v[180:183], v[86:89]
	v_mfma_f32_16x16x32_bf16 v[82:85], v[156:159], v[180:183], v[82:85]
	v_mfma_f32_16x16x32_bf16 v[70:73], v[148:151], v[188:191], v[70:73]
	v_mfma_f32_16x16x32_bf16 v[66:69], v[156:159], v[188:191], v[66:69]
	v_mfma_f32_16x16x32_bf16 v[118:121], v[152:155], v[168:171], v[118:121]
	v_mfma_f32_16x16x32_bf16 v[114:117], v[160:163], v[168:171], v[114:117]
	v_mfma_f32_16x16x32_bf16 v[102:105], v[152:155], v[176:179], v[102:105]
	v_mfma_f32_16x16x32_bf16 v[98:101], v[160:163], v[176:179], v[98:101]
	v_mfma_f32_16x16x32_bf16 v[86:89], v[152:155], v[184:187], v[86:89]
	v_mfma_f32_16x16x32_bf16 v[82:85], v[160:163], v[184:187], v[82:85]
	v_mfma_f32_16x16x32_bf16 v[70:73], v[152:155], v[192:195], v[70:73]
	v_mfma_f32_16x16x32_bf16 v[66:69], v[160:163], v[192:195], v[66:69]
	s_setprio 0
	s_barrier
	s_add_i32 s29, s29, s42
	s_mov_b32 m0, s29
	ds_read_b128 v[164:167], v244 offset:16384
	ds_read_b128 v[168:171], v244 offset:17408
	ds_read_b128 v[172:175], v244 offset:18432
	ds_read_b128 v[176:179], v244 offset:19456
	ds_read_b128 v[180:183], v244 offset:20480
	ds_read_b128 v[184:187], v244 offset:21504
	ds_read_b128 v[188:191], v244 offset:22528
	ds_read_b128 v[192:195], v244 offset:23552
	global_load_lds_dwordx4 v0, s[20:21]
	s_add_i32 m0, s29, 0x2000
	s_add_u32 s52, s20, 0x20000
	s_addc_u32 s53, s21, 0
	s_add_i32 s29, s30, s42
	global_load_lds_dwordx4 v208, s[20:21]
	s_mov_b32 m0, s29
	s_nop 0
	global_load_lds_dwordx4 v0, s[52:53]
	s_add_i32 m0, s29, 0x2000
	s_nop 0
	global_load_lds_dwordx4 v208, s[52:53]
	s_mov_b32 m0, s93
	s_nop 0
	global_load_lds_dwordx4 v204, s[72:73]
	s_mov_b32 m0, s44
	s_nop 0
	global_load_lds_dwordx4 v206, s[72:73]
	s_waitcnt vmcnt(8)
	s_waitcnt lgkmcnt(0)
	s_barrier
	s_setprio 1
	s_waitcnt lgkmcnt(0)
	v_mfma_f32_16x16x32_bf16 v[62:65], v[132:135], v[164:167], v[62:65]
	v_mfma_f32_16x16x32_bf16 v[58:61], v[140:143], v[164:167], v[58:61]
	v_mfma_f32_16x16x32_bf16 v[46:49], v[132:135], v[172:175], v[46:49]
	v_mfma_f32_16x16x32_bf16 v[42:45], v[140:143], v[172:175], v[42:45]
	v_mfma_f32_16x16x32_bf16 v[30:33], v[132:135], v[180:183], v[30:33]
	v_mfma_f32_16x16x32_bf16 v[26:29], v[140:143], v[180:183], v[26:29]
	v_mfma_f32_16x16x32_bf16 v[14:17], v[132:135], v[188:191], v[14:17]
	v_mfma_f32_16x16x32_bf16 v[10:13], v[140:143], v[188:191], v[10:13]
	v_mfma_f32_16x16x32_bf16 v[62:65], v[136:139], v[168:171], v[62:65]
	v_mfma_f32_16x16x32_bf16 v[58:61], v[144:147], v[168:171], v[58:61]
	v_mfma_f32_16x16x32_bf16 v[46:49], v[136:139], v[176:179], v[46:49]
	v_mfma_f32_16x16x32_bf16 v[42:45], v[144:147], v[176:179], v[42:45]
	v_mfma_f32_16x16x32_bf16 v[30:33], v[136:139], v[184:187], v[30:33]
	v_mfma_f32_16x16x32_bf16 v[26:29], v[144:147], v[184:187], v[26:29]
	v_mfma_f32_16x16x32_bf16 v[14:17], v[136:139], v[192:195], v[14:17]
	v_mfma_f32_16x16x32_bf16 v[10:13], v[144:147], v[192:195], v[10:13]
	s_setprio 0
	s_setprio 1
	v_mfma_f32_16x16x32_bf16 v[54:57], v[148:151], v[164:167], v[54:57]
	v_mfma_f32_16x16x32_bf16 v[50:53], v[156:159], v[164:167], v[50:53]
	v_mfma_f32_16x16x32_bf16 v[38:41], v[148:151], v[172:175], v[38:41]
	v_mfma_f32_16x16x32_bf16 v[34:37], v[156:159], v[172:175], v[34:37]
	v_mfma_f32_16x16x32_bf16 v[22:25], v[148:151], v[180:183], v[22:25]
	v_mfma_f32_16x16x32_bf16 v[18:21], v[156:159], v[180:183], v[18:21]
	v_mfma_f32_16x16x32_bf16 v[6:9], v[148:151], v[188:191], v[6:9]
	v_mfma_f32_16x16x32_bf16 v[2:5], v[156:159], v[188:191], v[2:5]
	v_mfma_f32_16x16x32_bf16 v[54:57], v[152:155], v[168:171], v[54:57]
	v_mfma_f32_16x16x32_bf16 v[50:53], v[160:163], v[168:171], v[50:53]
	v_mfma_f32_16x16x32_bf16 v[38:41], v[152:155], v[176:179], v[38:41]
	v_mfma_f32_16x16x32_bf16 v[34:37], v[160:163], v[176:179], v[34:37]
	v_mfma_f32_16x16x32_bf16 v[22:25], v[152:155], v[184:187], v[22:25]
	v_mfma_f32_16x16x32_bf16 v[18:21], v[160:163], v[184:187], v[18:21]
	v_mfma_f32_16x16x32_bf16 v[6:9], v[152:155], v[192:195], v[6:9]
	v_mfma_f32_16x16x32_bf16 v[2:5], v[160:163], v[192:195], v[2:5]
	s_setprio 0
	s_barrier
; #define PG8_STAGE(bufoff, gbase, voff) do { _Pragma("unroll") for (int _i = 0; _i < 2; ++_i) \
;         __builtin_amdgcn_global_load_lds((const gunsigned*)((const gchar*)(gbase) + (voff)[_i]), (LAS unsigned*)(lds + (bufoff) + ldsw + _i * 8192), 16, 0, 0); } while (0)
; #define PG8_LDA(dst, b, h) do { _Pragma("unroll") for (int m = 0; m < 4; ++m) _Pragma("unroll") for (int k = 0; k < 2; ++k) dst[m][k] = *(const LAS bf16x8*)(lds + PG8_SA(b, h) + aoff + m * 2048 + k * 1024); } while (0)
; #define PG8_LDB(dst, b, h) do { _Pragma("unroll") for (int n = 0; n < 2; ++n) _Pragma("unroll") for (int k = 0; k < 2; ++k) dst[n][k] = *(const LAS bf16x8*)(lds + PG8_SB(b, h) + boff + n * 2048 + k * 1024); } while (0)
; #define PG8_MMA(ai, bj, At, Bt) do { __builtin_amdgcn_s_setprio(1); _Pragma("unroll") for (int m = 0; m < 4; ++m) _Pragma("unroll") for (int n = 0; n < 2; ++n) _Pragma("unroll") for (int k = 0; k < 2; ++k) \
;         acc[ai][bj][m][n] = __builtin_amdgcn_mfma_f32_16x16x32_bf16(Bt[n][k], At[m][k], acc[ai][bj][m][n], 0, 0, 0); __builtin_amdgcn_s_setprio(0); } while (0)
; #define PG8_WAIT_V(n) asm volatile("s_waitcnt vmcnt(" #n ")" ::: "memory")
; #define PG8_WAIT_L(n) asm volatile("s_waitcnt lgkmcnt(" #n ")" ::: "memory")
; #define PG8_BAR __builtin_amdgcn_s_barrier()
; #define PG8_SCHED __builtin_amdgcn_sched_barrier(0)
; template <class Epi, class Sched>
; __device__ __forceinline__ void gemm_phase(LAS unsigned char* lds, const int tid, const Gemm g, const Sched& S, const Epi& E) {
;     ...
;             PG8_LDB(B0, 1, 0); PG8_LDB(B1, 1, 1); PG8_SCHED; PG8_LDA(At, 1, 0); PG8_STAGE(PG8_SA(0, 1), a2 + hstep, voffA);
;             PG8_WAIT_V(8); PG8_WAIT_L(0); PG8_BAR; PG8_MMA(0, 0, At, B0); PG8_MMA(0, 1, At, B1); PG8_BAR; PG8_SCHED;
;             PG8_LDA(At, 1, 1); PG8_STAGE(PG8_SB(1, 0), b3, voffB); PG8_STAGE(PG8_SB(1, 1), b3 + hstep, voffB); PG8_STAGE(PG8_SA(1, 0), a3, voffA);
;             PG8_WAIT_V(8); PG8_WAIT_L(0); PG8_BAR; PG8_MMA(1, 0, At, B0); PG8_MMA(1, 1, At, B1); PG8_BAR; PG8_SCHED;
;         }
	s_add_i32 s29, 0, 0x18000
	v_add_u32_e32 v126, s29, v242
	s_add_i32 s30, 0, 0x1c000
	ds_read_b128 v[132:135], v126
	ds_read_b128 v[136:139], v126 offset:1024
	ds_read_b128 v[140:143], v126 offset:2048
	ds_read_b128 v[144:147], v126 offset:3072
	v_add_u32_e32 v126, s30, v242
	ds_read_b128 v[148:151], v126
	ds_read_b128 v[152:155], v126 offset:1024
	ds_read_b128 v[156:159], v126 offset:2048
	ds_read_b128 v[160:163], v126 offset:3072
	s_add_u32 s52, s72, 0x20000
	s_addc_u32 s53, s73, 0
	s_mov_b32 m0, s45
	ds_read_b128 v[164:167], v244 offset:32768
	ds_read_b128 v[168:171], v244 offset:33792
	ds_read_b128 v[172:175], v244 offset:34816
	ds_read_b128 v[176:179], v244 offset:35840
	ds_read_b128 v[180:183], v244 offset:36864
	ds_read_b128 v[184:187], v244 offset:37888
	ds_read_b128 v[188:191], v244 offset:38912
	ds_read_b128 v[192:195], v244 offset:39936
	global_load_lds_dwordx4 v204, s[52:53]
	s_mov_b32 m0, s46
	s_nop 0
	global_load_lds_dwordx4 v206, s[52:53]
	s_waitcnt vmcnt(8)
	s_waitcnt lgkmcnt(0)
	s_barrier
	s_setprio 1
	s_waitcnt lgkmcnt(0)
	v_mfma_f32_16x16x32_bf16 v[126:129], v[132:135], v[164:167], v[128:131]
	v_mfma_f32_16x16x32_bf16 v[122:125], v[140:143], v[164:167], v[122:125]
	v_mfma_f32_16x16x32_bf16 v[110:113], v[132:135], v[172:175], v[110:113]
	v_mfma_f32_16x16x32_bf16 v[106:109], v[140:143], v[172:175], v[106:109]
	v_mfma_f32_16x16x32_bf16 v[94:97], v[132:135], v[180:183], v[94:97]
	v_mfma_f32_16x16x32_bf16 v[90:93], v[140:143], v[180:183], v[90:93]
	v_mfma_f32_16x16x32_bf16 v[78:81], v[132:135], v[188:191], v[78:81]
	v_mfma_f32_16x16x32_bf16 v[74:77], v[140:143], v[188:191], v[74:77]
	v_mfma_f32_16x16x32_bf16 v[128:131], v[136:139], v[168:171], v[126:129]
	v_mfma_f32_16x16x32_bf16 v[124:127], v[144:147], v[168:171], v[122:125]
	v_mfma_f32_16x16x32_bf16 v[110:113], v[136:139], v[176:179], v[110:113]
	v_mfma_f32_16x16x32_bf16 v[106:109], v[144:147], v[176:179], v[106:109]
	v_mfma_f32_16x16x32_bf16 v[94:97], v[136:139], v[184:187], v[94:97]
	v_mfma_f32_16x16x32_bf16 v[90:93], v[144:147], v[184:187], v[90:93]
	v_mfma_f32_16x16x32_bf16 v[78:81], v[136:139], v[192:195], v[78:81]
	v_mfma_f32_16x16x32_bf16 v[74:77], v[144:147], v[192:195], v[74:77]
	s_setprio 0
	s_setprio 1
	v_mfma_f32_16x16x32_bf16 v[118:121], v[148:151], v[164:167], v[118:121]
	v_mfma_f32_16x16x32_bf16 v[114:117], v[156:159], v[164:167], v[114:117]
	v_mfma_f32_16x16x32_bf16 v[102:105], v[148:151], v[172:175], v[102:105]
	v_mfma_f32_16x16x32_bf16 v[98:101], v[156:159], v[172:175], v[98:101]
	v_mfma_f32_16x16x32_bf16 v[86:89], v[148:151], v[180:183], v[86:89]
	v_mfma_f32_16x16x32_bf16 v[82:85], v[156:159], v[180:183], v[82:85]
	v_mfma_f32_16x16x32_bf16 v[70:73], v[148:151], v[188:191], v[70:73]
	v_mfma_f32_16x16x32_bf16 v[66:69], v[156:159], v[188:191], v[66:69]
	v_mfma_f32_16x16x32_bf16 v[118:121], v[152:155], v[168:171], v[118:121]
	v_mfma_f32_16x16x32_bf16 v[114:117], v[160:163], v[168:171], v[114:117]
	v_mfma_f32_16x16x32_bf16 v[102:105], v[152:155], v[176:179], v[102:105]
	v_mfma_f32_16x16x32_bf16 v[98:101], v[160:163], v[176:179], v[98:101]
	v_mfma_f32_16x16x32_bf16 v[86:89], v[152:155], v[184:187], v[86:89]
	v_mfma_f32_16x16x32_bf16 v[82:85], v[160:163], v[184:187], v[82:85]
	v_mfma_f32_16x16x32_bf16 v[70:73], v[152:155], v[192:195], v[70:73]
	v_mfma_f32_16x16x32_bf16 v[66:69], v[160:163], v[192:195], v[66:69]
	s_setprio 0
	s_barrier
	s_add_i32 s29, s29, s42
	s_mov_b32 m0, s29
	ds_read_b128 v[164:167], v244 offset:49152
	ds_read_b128 v[168:171], v244 offset:50176
	ds_read_b128 v[172:175], v244 offset:51200
	ds_read_b128 v[176:179], v244 offset:52224
	ds_read_b128 v[180:183], v244 offset:53248
	ds_read_b128 v[184:187], v244 offset:54272
	ds_read_b128 v[188:191], v244 offset:55296
	ds_read_b128 v[192:195], v244 offset:56320
	global_load_lds_dwordx4 v201, s[20:21]
	s_add_i32 m0, s29, 0x2000
	s_add_i32 s29, s30, s42
	global_load_lds_dwordx4 v215, s[20:21]
	s_add_u32 s20, s20, 0x20080
	s_addc_u32 s21, s21, 0
	s_mov_b32 m0, s29
	s_nop 0
	global_load_lds_dwordx4 v0, s[20:21]
	s_add_i32 m0, s29, 0x2000
	s_nop 0
	global_load_lds_dwordx4 v208, s[20:21]
	s_mov_b32 m0, s47
	s_nop 0
	global_load_lds_dwordx4 v217, s[72:73]
	s_mov_b32 m0, s48
	s_nop 0
	global_load_lds_dwordx4 v219, s[72:73]
	s_waitcnt vmcnt(8)
	s_waitcnt lgkmcnt(0)
	s_barrier
	s_setprio 1
	s_waitcnt lgkmcnt(0)
	v_mfma_f32_16x16x32_bf16 v[62:65], v[132:135], v[164:167], v[62:65]
	v_mfma_f32_16x16x32_bf16 v[58:61], v[140:143], v[164:167], v[58:61]
	v_mfma_f32_16x16x32_bf16 v[46:49], v[132:135], v[172:175], v[46:49]
	v_mfma_f32_16x16x32_bf16 v[42:45], v[140:143], v[172:175], v[42:45]
	v_mfma_f32_16x16x32_bf16 v[30:33], v[132:135], v[180:183], v[30:33]
	v_mfma_f32_16x16x32_bf16 v[26:29], v[140:143], v[180:183], v[26:29]
	v_mfma_f32_16x16x32_bf16 v[14:17], v[132:135], v[188:191], v[14:17]
	v_mfma_f32_16x16x32_bf16 v[10:13], v[140:143], v[188:191], v[10:13]
	v_mfma_f32_16x16x32_bf16 v[62:65], v[136:139], v[168:171], v[62:65]
	v_mfma_f32_16x16x32_bf16 v[58:61], v[144:147], v[168:171], v[58:61]
	v_mfma_f32_16x16x32_bf16 v[46:49], v[136:139], v[176:179], v[46:49]
	v_mfma_f32_16x16x32_bf16 v[42:45], v[144:147], v[176:179], v[42:45]
	v_mfma_f32_16x16x32_bf16 v[30:33], v[136:139], v[184:187], v[30:33]
	v_mfma_f32_16x16x32_bf16 v[26:29], v[144:147], v[184:187], v[26:29]
	v_mfma_f32_16x16x32_bf16 v[14:17], v[136:139], v[192:195], v[14:17]
	v_mfma_f32_16x16x32_bf16 v[10:13], v[144:147], v[192:195], v[10:13]
	s_setprio 0
	s_setprio 1
	v_mfma_f32_16x16x32_bf16 v[54:57], v[148:151], v[164:167], v[54:57]
	v_mfma_f32_16x16x32_bf16 v[50:53], v[156:159], v[164:167], v[50:53]
	v_mfma_f32_16x16x32_bf16 v[38:41], v[148:151], v[172:175], v[38:41]
	v_mfma_f32_16x16x32_bf16 v[34:37], v[156:159], v[172:175], v[34:37]
	v_mfma_f32_16x16x32_bf16 v[22:25], v[148:151], v[180:183], v[22:25]
	v_mfma_f32_16x16x32_bf16 v[18:21], v[156:159], v[180:183], v[18:21]
	v_mfma_f32_16x16x32_bf16 v[6:9], v[148:151], v[188:191], v[6:9]
	v_mfma_f32_16x16x32_bf16 v[2:5], v[156:159], v[188:191], v[2:5]
	v_mfma_f32_16x16x32_bf16 v[54:57], v[152:155], v[168:171], v[54:57]
	v_mfma_f32_16x16x32_bf16 v[50:53], v[160:163], v[168:171], v[50:53]
	v_mfma_f32_16x16x32_bf16 v[38:41], v[152:155], v[176:179], v[38:41]
	v_mfma_f32_16x16x32_bf16 v[34:37], v[160:163], v[176:179], v[34:37]
	v_mfma_f32_16x16x32_bf16 v[22:25], v[152:155], v[184:187], v[22:25]
	v_mfma_f32_16x16x32_bf16 v[18:21], v[160:163], v[184:187], v[18:21]
	v_mfma_f32_16x16x32_bf16 v[6:9], v[152:155], v[192:195], v[6:9]
	v_mfma_f32_16x16x32_bf16 v[2:5], v[160:163], v[192:195], v[2:5]
	s_setprio 0
	s_barrier
	s_add_i32 s51, s51, 2
	s_add_u32 s24, s24, 0x100
	s_addc_u32 s31, s31, 0
	s_add_u32 s16, s16, 0x100
	s_addc_u32 s17, s17, 0
	s_cmp_gt_u32 s51, 5
	s_cbranch_scc0 .LBB0_444
	s_and_b64 vcc, exec, s[10:11]
	s_cbranch_vccz .LBB0_447
	s_barrier

;     __device__ bool next(int i, Unit& u) const { if (!b.next(i / 3, u)) return false; u.pz = i % 3; return true; }
; #define PG8_STAGE(bufoff, gbase, voff) do { _Pragma("unroll") for (int _i = 0; _i < 2; ++_i) \
;         __builtin_amdgcn_global_load_lds((const gunsigned*)((const gchar*)(gbase) + (voff)[_i]), (LAS unsigned*)(lds + (bufoff) + ldsw + _i * 8192), 16, 0, 0); } while (0)
; #define PG8_LDA(dst, b, h) do { _Pragma("unroll") for (int m = 0; m < 4; ++m) _Pragma("unroll") for (int k = 0; k < 2; ++k) dst[m][k] = *(const LAS bf16x8*)(lds + PG8_SA(b, h) + aoff + m * 2048 + k * 1024); } while (0)
; #define PG8_LDB(dst, b, h) do { _Pragma("unroll") for (int n = 0; n < 2; ++n) _Pragma("unroll") for (int k = 0; k < 2; ++k) dst[n][k] = *(const LAS bf16x8*)(lds + PG8_SB(b, h) + boff + n * 2048 + k * 1024); } while (0)
; #define PG8_WAIT_V(n) asm volatile("s_waitcnt vmcnt(" #n ")" ::: "memory")
; #define PG8_WAIT_L(n) asm volatile("s_waitcnt lgkmcnt(" #n ")" ::: "memory")
; template <class Epi, class Sched>
; __device__ __forceinline__ void gemm_phase(LAS unsigned char* lds, const int tid, const Gemm g, const Sched& S, const Epi& E) {
;     ...
;         const bool has_next = S.next(ui + 1, nxt);
;         const gchar* nA = has_next ? (const gchar*)g.A + (size_t)nxt.pm * tstep + (size_t)nxt.pz * g.zA : cA;
;         const gchar* nB = has_next ? (const gchar*)g.Bt + (size_t)nxt.pn * tstep + (size_t)nxt.pz * g.zB : cB;
;         for (int t = 0; t < nt; t += 2) {
;             const bool last = (t == nt - 2);
;             const gchar* a1 = cA + (size_t)(t + 1) * kstep;
;             const gchar* a2 = last ? nA : cA + (size_t)(t + 2) * kstep; const gchar* b2 = last ? nB : cB + (size_t)(t + 2) * kstep;
;             const gchar* a3 = a2 + kstep; const gchar* b3 = b2 + kstep;
;             PG8_LDB(B0, 0, 0); PG8_LDB(B1, 0, 1); PG8_SCHED; PG8_LDA(At, 0, 0); PG8_STAGE(PG8_SA(1, 1), a1 + hstep, voffA);
;             PG8_WAIT_V(8); PG8_WAIT_L(0); PG8_BAR; PG8_MMA(0, 0, At, B0); PG8_MMA(0, 1, At, B1); PG8_BAR; PG8_SCHED;
;     ...
; #pragma unroll
;         for (int a = 0; a < 2; ++a)
; #pragma unroll
;             for (int b = 0; b < 2; ++b)
; #pragma unroll
;                 for (int m = 0; m < 4; ++m)
; #pragma unroll
;                     for (int n = 0; n < 2; ++n) acc[a][b][m][n] = (f32x4){0.f, 0.f, 0.f, 0.f};
;         cur = nxt; cA = nA; cB = nB; ++ui;
.LBB0_558:
	s_ashr_i32 s9, s8, 31
	s_lshl_b64 s[16:17], s[8:9], 19
	s_add_u32 s16, s86, s16
	s_addc_u32 s17, s87, s17
	s_and_b64 s[42:43], s[2:3], exec
	s_cselect_b32 s9, s17, s61
	s_cselect_b32 s42, s16, s60
	s_ashr_i32 s7, s6, 31
	s_lshl_b64 s[44:45], s[6:7], 19
	s_add_u32 s56, s15, s44
	s_addc_u32 s57, s23, s45
	s_and_b64 s[44:45], s[2:3], exec
	s_cselect_b32 s7, s57, s21
	s_cselect_b32 s43, s56, s20
	s_add_u32 s44, s20, 0x100
	s_addc_u32 s45, s21, 0
	s_add_u32 s60, s60, 0x40080
	v_mov_b32_e32 v2, 0
	s_addc_u32 s61, s61, 0
	s_mov_b32 s46, -2
	v_mov_b32_e32 v3, v2
	v_mov_b32_e32 v4, v2
	v_mov_b32_e32 v5, v2
	v_mov_b32_e32 v6, v2
	v_mov_b32_e32 v7, v2
	v_mov_b32_e32 v8, v2
	v_mov_b32_e32 v9, v2
	v_mov_b32_e32 v10, v2
	v_mov_b32_e32 v11, v2
	v_mov_b32_e32 v12, v2
	v_mov_b32_e32 v13, v2
	v_mov_b32_e32 v18, v2
	v_mov_b32_e32 v19, v2
	v_mov_b32_e32 v20, v2
	v_mov_b32_e32 v21, v2
	v_mov_b32_e32 v26, v2
	v_mov_b32_e32 v27, v2
	v_mov_b32_e32 v28, v2
	v_mov_b32_e32 v29, v2
	v_mov_b32_e32 v34, v2
	v_mov_b32_e32 v35, v2
	v_mov_b32_e32 v36, v2
	v_mov_b32_e32 v37, v2
	v_mov_b32_e32 v42, v2
	v_mov_b32_e32 v43, v2
	v_mov_b32_e32 v44, v2
	v_mov_b32_e32 v45, v2
	v_mov_b32_e32 v50, v2
	v_mov_b32_e32 v51, v2
	v_mov_b32_e32 v52, v2
	v_mov_b32_e32 v53, v2
	v_mov_b32_e32 v14, v2
	v_mov_b32_e32 v15, v2
	v_mov_b32_e32 v16, v2
	v_mov_b32_e32 v17, v2
	v_mov_b32_e32 v22, v2
	v_mov_b32_e32 v23, v2
	v_mov_b32_e32 v24, v2
	v_mov_b32_e32 v25, v2
	v_mov_b32_e32 v30, v2
	v_mov_b32_e32 v31, v2
	v_mov_b32_e32 v32, v2
	v_mov_b32_e32 v33, v2
	v_mov_b32_e32 v38, v2
	v_mov_b32_e32 v39, v2
	v_mov_b32_e32 v40, v2
	v_mov_b32_e32 v41, v2
	v_mov_b32_e32 v46, v2
	v_mov_b32_e32 v47, v2
	v_mov_b32_e32 v48, v2
	v_mov_b32_e32 v49, v2
	v_mov_b32_e32 v54, v2
	v_mov_b32_e32 v55, v2
	v_mov_b32_e32 v56, v2
	v_mov_b32_e32 v57, v2
	v_mov_b32_e32 v58, v2
	v_mov_b32_e32 v59, v2
	v_mov_b32_e32 v60, v2
	v_mov_b32_e32 v61, v2
	v_mov_b32_e32 v62, v2
	v_mov_b32_e32 v63, v2
	v_mov_b32_e32 v64, v2
	v_mov_b32_e32 v65, v2
	v_mov_b32_e32 v66, v2
	v_mov_b32_e32 v67, v2
	v_mov_b32_e32 v68, v2
	v_mov_b32_e32 v69, v2
	v_mov_b32_e32 v70, v2
	v_mov_b32_e32 v71, v2
	v_mov_b32_e32 v72, v2
	v_mov_b32_e32 v73, v2
	v_mov_b32_e32 v74, v2
	v_mov_b32_e32 v75, v2
	v_mov_b32_e32 v76, v2
	v_mov_b32_e32 v77, v2
	s_waitcnt vmcnt(0)
	v_mov_b32_e32 v82, v2
	v_mov_b32_e32 v83, v2
	v_mov_b32_e32 v84, v2
	v_mov_b32_e32 v85, v2
	v_mov_b32_e32 v90, v2
	v_mov_b32_e32 v91, v2
	v_mov_b32_e32 v92, v2
	v_mov_b32_e32 v93, v2
	v_mov_b32_e32 v98, v2
	v_mov_b32_e32 v99, v2
	v_mov_b32_e32 v100, v2
	v_mov_b32_e32 v101, v2
	v_mov_b32_e32 v106, v2
	v_mov_b32_e32 v107, v2
	v_mov_b32_e32 v108, v2
	v_mov_b32_e32 v109, v2
	v_mov_b32_e32 v114, v2
	v_mov_b32_e32 v115, v2
	v_mov_b32_e32 v116, v2
	v_mov_b32_e32 v117, v2
	v_mov_b32_e32 v78, v2
	v_mov_b32_e32 v79, v2
	v_mov_b32_e32 v80, v2
	v_mov_b32_e32 v81, v2
	v_mov_b32_e32 v86, v2
	v_mov_b32_e32 v87, v2
	v_mov_b32_e32 v88, v2
	v_mov_b32_e32 v89, v2
	v_mov_b32_e32 v94, v2
	v_mov_b32_e32 v95, v2
	v_mov_b32_e32 v96, v2
	v_mov_b32_e32 v97, v2
	v_mov_b32_e32 v102, v2
	v_mov_b32_e32 v103, v2
	v_mov_b32_e32 v104, v2
	v_mov_b32_e32 v105, v2
	v_mov_b32_e32 v110, v2
	v_mov_b32_e32 v111, v2
	v_mov_b32_e32 v112, v2
	v_mov_b32_e32 v113, v2
	v_mov_b32_e32 v118, v2
	v_mov_b32_e32 v119, v2
	v_mov_b32_e32 v120, v2
	v_mov_b32_e32 v121, v2
	v_mov_b32_e32 v122, v2
	v_mov_b32_e32 v123, v2
	v_mov_b32_e32 v124, v2
	v_mov_b32_e32 v125, v2
	v_mov_b32_e32 v126, v2
	v_mov_b32_e32 v127, v2
	v_mov_b32_e32 v128, v2
	v_mov_b32_e32 v129, v2
	v_add_u32_e32 v161, 0x80, v0
	v_add_u32_e32 v195, 0x80, v134
	v_add_u32_e32 v201, 0x80, v138
	v_add_u32_e32 v227, 0x80, v136
.LBB0_559:
	s_add_u32 s20, s60, 0xfffc0080
	s_addc_u32 s21, s61, -1
	s_add_i32 s29, 0, 0x10000
	s_cmp_eq_u32 s46, 12
	s_cselect_b32 s63, s9, s21
	s_cselect_b32 s62, s42, s20
	s_cselect_b32 s21, s7, s45
	s_cselect_b32 s20, s43, s44
	s_add_i32 s30, 0, 0x14000
	v_add_u32_e32 v152, s29, v165
	v_add_u32_e32 v160, s30, v165
	ds_read_b128 v[130:133], v152
	ds_read_b128 v[144:147], v152 offset:1024
	ds_read_b128 v[148:151], v152 offset:2048
	ds_read_b128 v[152:155], v152 offset:3072
	ds_read_b128 v[156:159], v160
	ds_read_b128 v[170:173], v160 offset:1024
	ds_read_b128 v[174:177], v160 offset:2048
	ds_read_b128 v[178:181], v160 offset:3072
	s_add_i32 m0, s34, 0xc000
	ds_read_b128 v[182:185], v169
	ds_read_b128 v[186:189], v169 offset:1024
	ds_read_b128 v[190:193], v169 offset:2048
	ds_read_b128 v[204:207], v169 offset:3072
	ds_read_b128 v[210:213], v169 offset:4096
	ds_read_b128 v[214:217], v169 offset:5120
	ds_read_b128 v[218:221], v169 offset:6144
	ds_read_b128 v[222:225], v169 offset:7168
	global_load_lds_dwordx4 v142, s[60:61]
	s_add_i32 m0, s34, 0xe000
	s_nop 0
	global_load_lds_dwordx4 v140, s[60:61]
	s_waitcnt vmcnt(8)
	s_waitcnt lgkmcnt(0)
	s_barrier
; #define PG8_STAGE(bufoff, gbase, voff) do { _Pragma("unroll") for (int _i = 0; _i < 2; ++_i) \
;         __builtin_amdgcn_global_load_lds((const gunsigned*)((const gchar*)(gbase) + (voff)[_i]), (LAS unsigned*)(lds + (bufoff) + ldsw + _i * 8192), 16, 0, 0); } while (0)
; #define PG8_LDA(dst, b, h) do { _Pragma("unroll") for (int m = 0; m < 4; ++m) _Pragma("unroll") for (int k = 0; k < 2; ++k) dst[m][k] = *(const LAS bf16x8*)(lds + PG8_SA(b, h) + aoff + m * 2048 + k * 1024); } while (0)
; #define PG8_LDB(dst, b, h) do { _Pragma("unroll") for (int n = 0; n < 2; ++n) _Pragma("unroll") for (int k = 0; k < 2; ++k) dst[n][k] = *(const LAS bf16x8*)(lds + PG8_SB(b, h) + boff + n * 2048 + k * 1024); } while (0)
; #define PG8_MMA(ai, bj, At, Bt) do { __builtin_amdgcn_s_setprio(1); _Pragma("unroll") for (int m = 0; m < 4; ++m) _Pragma("unroll") for (int n = 0; n < 2; ++n) _Pragma("unroll") for (int k = 0; k < 2; ++k) \
;         acc[ai][bj][m][n] = __builtin_amdgcn_mfma_f32_16x16x32_bf16(Bt[n][k], At[m][k], acc[ai][bj][m][n], 0, 0, 0); __builtin_amdgcn_s_setprio(0); } while (0)
; #define PG8_WAIT_V(n) asm volatile("s_waitcnt vmcnt(" #n ")" ::: "memory")
; #define PG8_WAIT_L(n) asm volatile("s_waitcnt lgkmcnt(" #n ")" ::: "memory")
; #define PG8_BAR __builtin_amdgcn_s_barrier()
; #define PG8_SCHED __builtin_amdgcn_sched_barrier(0)
; template <class Epi, class Sched>
; __device__ __forceinline__ void gemm_phase(LAS unsigned char* lds, const int tid, const Gemm g, const Sched& S, const Epi& E) {
;     ...
;             PG8_WAIT_V(8); PG8_WAIT_L(0); PG8_BAR; PG8_MMA(0, 0, At, B0); PG8_MMA(0, 1, At, B1); PG8_BAR; PG8_SCHED;
;             PG8_LDA(At, 0, 1); PG8_STAGE(PG8_SB(0, 0), b2, voffB); PG8_STAGE(PG8_SB(0, 1), b2 + hstep, voffB); PG8_STAGE(PG8_SA(0, 0), a2, voffA);
;             PG8_WAIT_V(8); PG8_WAIT_L(0); PG8_BAR; PG8_MMA(1, 0, At, B0); PG8_MMA(1, 1, At, B1); PG8_BAR; PG8_SCHED;
;             PG8_LDB(B0, 1, 0); PG8_LDB(B1, 1, 1); PG8_SCHED; PG8_LDA(At, 1, 0); PG8_STAGE(PG8_SA(0, 1), a2 + hstep, voffA);
	s_setprio 1
	s_waitcnt lgkmcnt(0)
	v_mfma_f32_16x16x32_bf16 v[126:129], v[130:133], v[182:185], v[126:129]
	v_mfma_f32_16x16x32_bf16 v[122:125], v[148:151], v[182:185], v[122:125]
	v_mfma_f32_16x16x32_bf16 v[118:121], v[130:133], v[190:193], v[118:121]
	v_mfma_f32_16x16x32_bf16 v[110:113], v[148:151], v[190:193], v[110:113]
	v_mfma_f32_16x16x32_bf16 v[102:105], v[130:133], v[210:213], v[102:105]
	v_mfma_f32_16x16x32_bf16 v[94:97], v[148:151], v[210:213], v[94:97]
	v_mfma_f32_16x16x32_bf16 v[86:89], v[130:133], v[218:221], v[86:89]
	v_mfma_f32_16x16x32_bf16 v[78:81], v[148:151], v[218:221], v[78:81]
	v_mfma_f32_16x16x32_bf16 v[126:129], v[144:147], v[186:189], v[126:129]
	v_mfma_f32_16x16x32_bf16 v[122:125], v[152:155], v[186:189], v[122:125]
	v_mfma_f32_16x16x32_bf16 v[118:121], v[144:147], v[204:207], v[118:121]
	v_mfma_f32_16x16x32_bf16 v[110:113], v[152:155], v[204:207], v[110:113]
	v_mfma_f32_16x16x32_bf16 v[102:105], v[144:147], v[214:217], v[102:105]
	v_mfma_f32_16x16x32_bf16 v[94:97], v[152:155], v[214:217], v[94:97]
	v_mfma_f32_16x16x32_bf16 v[86:89], v[144:147], v[222:225], v[86:89]
	v_mfma_f32_16x16x32_bf16 v[78:81], v[152:155], v[222:225], v[78:81]
	s_setprio 0
	s_setprio 1
	v_mfma_f32_16x16x32_bf16 v[114:117], v[156:159], v[182:185], v[114:117]
	v_mfma_f32_16x16x32_bf16 v[106:109], v[174:177], v[182:185], v[106:109]
	v_mfma_f32_16x16x32_bf16 v[98:101], v[156:159], v[190:193], v[98:101]
	v_mfma_f32_16x16x32_bf16 v[90:93], v[174:177], v[190:193], v[90:93]
	v_mfma_f32_16x16x32_bf16 v[82:85], v[156:159], v[210:213], v[82:85]
	v_mfma_f32_16x16x32_bf16 v[74:77], v[174:177], v[210:213], v[74:77]
	v_mfma_f32_16x16x32_bf16 v[70:73], v[156:159], v[218:221], v[70:73]
	v_mfma_f32_16x16x32_bf16 v[66:69], v[174:177], v[218:221], v[66:69]
	v_mfma_f32_16x16x32_bf16 v[114:117], v[170:173], v[186:189], v[114:117]
	v_mfma_f32_16x16x32_bf16 v[106:109], v[178:181], v[186:189], v[106:109]
	v_mfma_f32_16x16x32_bf16 v[98:101], v[170:173], v[204:207], v[98:101]
	v_mfma_f32_16x16x32_bf16 v[90:93], v[178:181], v[204:207], v[90:93]
	v_mfma_f32_16x16x32_bf16 v[82:85], v[170:173], v[214:217], v[82:85]
	v_mfma_f32_16x16x32_bf16 v[74:77], v[178:181], v[214:217], v[74:77]
	v_mfma_f32_16x16x32_bf16 v[70:73], v[170:173], v[222:225], v[70:73]
	v_mfma_f32_16x16x32_bf16 v[66:69], v[178:181], v[222:225], v[66:69]
	s_setprio 0
	s_barrier
	s_add_i32 s29, s29, s12
	s_mov_b32 m0, s29
	ds_read_b128 v[182:185], v169 offset:16384
	ds_read_b128 v[186:189], v169 offset:17408
	ds_read_b128 v[190:193], v169 offset:18432
	ds_read_b128 v[204:207], v169 offset:19456
	ds_read_b128 v[210:213], v169 offset:20480
	ds_read_b128 v[214:217], v169 offset:21504
	ds_read_b128 v[218:221], v169 offset:22528
	ds_read_b128 v[222:225], v169 offset:23552
	global_load_lds_dwordx4 v0, s[20:21]
	s_add_i32 m0, s29, 0x2000
	s_add_u32 s48, s20, 0x40000
	s_addc_u32 s49, s21, 0
	s_add_i32 s29, s30, s12
	global_load_lds_dwordx4 v134, s[20:21]
	s_mov_b32 m0, s29
	s_nop 0
	global_load_lds_dwordx4 v0, s[48:49]
	s_add_i32 m0, s29, 0x2000
	s_nop 0
	global_load_lds_dwordx4 v134, s[48:49]
	s_mov_b32 m0, s34
	s_nop 0
	global_load_lds_dwordx4 v138, s[62:63]
	s_mov_b32 m0, s35
	s_nop 0
	global_load_lds_dwordx4 v136, s[62:63]
	s_waitcnt vmcnt(8)
	s_waitcnt lgkmcnt(0)
	s_barrier
	s_setprio 1
	s_waitcnt lgkmcnt(0)
	v_mfma_f32_16x16x32_bf16 v[62:65], v[130:133], v[182:185], v[62:65]
	v_mfma_f32_16x16x32_bf16 v[58:61], v[148:151], v[182:185], v[58:61]
	v_mfma_f32_16x16x32_bf16 v[54:57], v[130:133], v[190:193], v[54:57]
	v_mfma_f32_16x16x32_bf16 v[46:49], v[148:151], v[190:193], v[46:49]
	v_mfma_f32_16x16x32_bf16 v[38:41], v[130:133], v[210:213], v[38:41]
	v_mfma_f32_16x16x32_bf16 v[30:33], v[148:151], v[210:213], v[30:33]
	v_mfma_f32_16x16x32_bf16 v[22:25], v[130:133], v[218:221], v[22:25]
	v_mfma_f32_16x16x32_bf16 v[14:17], v[148:151], v[218:221], v[14:17]
	v_mfma_f32_16x16x32_bf16 v[62:65], v[144:147], v[186:189], v[62:65]
	v_mfma_f32_16x16x32_bf16 v[58:61], v[152:155], v[186:189], v[58:61]
	v_mfma_f32_16x16x32_bf16 v[54:57], v[144:147], v[204:207], v[54:57]
	v_mfma_f32_16x16x32_bf16 v[46:49], v[152:155], v[204:207], v[46:49]
	v_mfma_f32_16x16x32_bf16 v[38:41], v[144:147], v[214:217], v[38:41]
	v_mfma_f32_16x16x32_bf16 v[30:33], v[152:155], v[214:217], v[30:33]
	v_mfma_f32_16x16x32_bf16 v[22:25], v[144:147], v[222:225], v[22:25]
	v_mfma_f32_16x16x32_bf16 v[14:17], v[152:155], v[222:225], v[14:17]
	s_setprio 0
	s_setprio 1
	v_mfma_f32_16x16x32_bf16 v[50:53], v[156:159], v[182:185], v[50:53]
	v_mfma_f32_16x16x32_bf16 v[42:45], v[174:177], v[182:185], v[42:45]
	v_mfma_f32_16x16x32_bf16 v[34:37], v[156:159], v[190:193], v[34:37]
	v_mfma_f32_16x16x32_bf16 v[26:29], v[174:177], v[190:193], v[26:29]
	v_mfma_f32_16x16x32_bf16 v[18:21], v[156:159], v[210:213], v[18:21]
	v_mfma_f32_16x16x32_bf16 v[10:13], v[174:177], v[210:213], v[10:13]
	v_mfma_f32_16x16x32_bf16 v[6:9], v[156:159], v[218:221], v[6:9]
	v_mfma_f32_16x16x32_bf16 v[2:5], v[174:177], v[218:221], v[2:5]
	v_mfma_f32_16x16x32_bf16 v[50:53], v[170:173], v[186:189], v[50:53]
	v_mfma_f32_16x16x32_bf16 v[42:45], v[178:181], v[186:189], v[42:45]
	v_mfma_f32_16x16x32_bf16 v[34:37], v[170:173], v[204:207], v[34:37]
	v_mfma_f32_16x16x32_bf16 v[26:29], v[178:181], v[204:207], v[26:29]
	v_mfma_f32_16x16x32_bf16 v[18:21], v[170:173], v[214:217], v[18:21]
	v_mfma_f32_16x16x32_bf16 v[10:13], v[178:181], v[214:217], v[10:13]
	v_mfma_f32_16x16x32_bf16 v[6:9], v[170:173], v[222:225], v[6:9]
	v_mfma_f32_16x16x32_bf16 v[2:5], v[178:181], v[222:225], v[2:5]
	s_setprio 0
	s_barrier
; #define PG8_STAGE(bufoff, gbase, voff) do { _Pragma("unroll") for (int _i = 0; _i < 2; ++_i) \
;         __builtin_amdgcn_global_load_lds((const gunsigned*)((const gchar*)(gbase) + (voff)[_i]), (LAS unsigned*)(lds + (bufoff) + ldsw + _i * 8192), 16, 0, 0); } while (0)
; #define PG8_LDA(dst, b, h) do { _Pragma("unroll") for (int m = 0; m < 4; ++m) _Pragma("unroll") for (int k = 0; k < 2; ++k) dst[m][k] = *(const LAS bf16x8*)(lds + PG8_SA(b, h) + aoff + m * 2048 + k * 1024); } while (0)
; #define PG8_LDB(dst, b, h) do { _Pragma("unroll") for (int n = 0; n < 2; ++n) _Pragma("unroll") for (int k = 0; k < 2; ++k) dst[n][k] = *(const LAS bf16x8*)(lds + PG8_SB(b, h) + boff + n * 2048 + k * 1024); } while (0)
; #define PG8_MMA(ai, bj, At, Bt) do { __builtin_amdgcn_s_setprio(1); _Pragma("unroll") for (int m = 0; m < 4; ++m) _Pragma("unroll") for (int n = 0; n < 2; ++n) _Pragma("unroll") for (int k = 0; k < 2; ++k) \
;         acc[ai][bj][m][n] = __builtin_amdgcn_mfma_f32_16x16x32_bf16(Bt[n][k], At[m][k], acc[ai][bj][m][n], 0, 0, 0); __builtin_amdgcn_s_setprio(0); } while (0)
; #define PG8_WAIT_V(n) asm volatile("s_waitcnt vmcnt(" #n ")" ::: "memory")
; #define PG8_WAIT_L(n) asm volatile("s_waitcnt lgkmcnt(" #n ")" ::: "memory")
; #define PG8_BAR __builtin_amdgcn_s_barrier()
; #define PG8_SCHED __builtin_amdgcn_sched_barrier(0)
; template <class Epi, class Sched>
; __device__ __forceinline__ void gemm_phase(LAS unsigned char* lds, const int tid, const Gemm g, const Sched& S, const Epi& E) {
;     ...
;             PG8_LDB(B0, 1, 0); PG8_LDB(B1, 1, 1); PG8_SCHED; PG8_LDA(At, 1, 0); PG8_STAGE(PG8_SA(0, 1), a2 + hstep, voffA);
;             PG8_WAIT_V(8); PG8_WAIT_L(0); PG8_BAR; PG8_MMA(0, 0, At, B0); PG8_MMA(0, 1, At, B1); PG8_BAR; PG8_SCHED;
;             PG8_LDA(At, 1, 1); PG8_STAGE(PG8_SB(1, 0), b3, voffB); PG8_STAGE(PG8_SB(1, 1), b3 + hstep, voffB); PG8_STAGE(PG8_SA(1, 0), a3, voffA);
;             PG8_WAIT_V(8); PG8_WAIT_L(0); PG8_BAR; PG8_MMA(1, 0, At, B0); PG8_MMA(1, 1, At, B1); PG8_BAR; PG8_SCHED;
;         }
	s_add_i32 s29, 0, 0x18000
	s_add_i32 s30, 0, 0x1c000
	v_add_u32_e32 v152, s29, v165
	v_add_u32_e32 v162, s30, v165
	ds_read_b128 v[130:133], v152
	ds_read_b128 v[144:147], v152 offset:1024
	ds_read_b128 v[148:151], v152 offset:2048
	ds_read_b128 v[152:155], v152 offset:3072
	ds_read_b128 v[156:159], v162
	ds_read_b128 v[170:173], v162 offset:1024
	ds_read_b128 v[174:177], v162 offset:2048
	ds_read_b128 v[178:181], v162 offset:3072
	s_add_u32 s48, s62, 0x40000
	s_addc_u32 s49, s63, 0
	s_mov_b32 m0, s36
	ds_read_b128 v[182:185], v169 offset:32768
	ds_read_b128 v[186:189], v169 offset:33792
	ds_read_b128 v[190:193], v169 offset:34816
	ds_read_b128 v[204:207], v169 offset:35840
	ds_read_b128 v[210:213], v169 offset:36864
	ds_read_b128 v[214:217], v169 offset:37888
	ds_read_b128 v[218:221], v169 offset:38912
	ds_read_b128 v[222:225], v169 offset:39936
	global_load_lds_dwordx4 v138, s[48:49]
	s_mov_b32 m0, s37
	s_nop 0
	global_load_lds_dwordx4 v136, s[48:49]
	s_waitcnt vmcnt(8)
	s_waitcnt lgkmcnt(0)
	s_barrier
	s_setprio 1
	s_waitcnt lgkmcnt(0)
	v_mfma_f32_16x16x32_bf16 v[126:129], v[130:133], v[182:185], v[126:129]
	v_mfma_f32_16x16x32_bf16 v[122:125], v[148:151], v[182:185], v[122:125]
	v_mfma_f32_16x16x32_bf16 v[118:121], v[130:133], v[190:193], v[118:121]
	v_mfma_f32_16x16x32_bf16 v[110:113], v[148:151], v[190:193], v[110:113]
	v_mfma_f32_16x16x32_bf16 v[102:105], v[130:133], v[210:213], v[102:105]
	v_mfma_f32_16x16x32_bf16 v[94:97], v[148:151], v[210:213], v[94:97]
	v_mfma_f32_16x16x32_bf16 v[86:89], v[130:133], v[218:221], v[86:89]
	v_mfma_f32_16x16x32_bf16 v[78:81], v[148:151], v[218:221], v[78:81]
	v_mfma_f32_16x16x32_bf16 v[126:129], v[144:147], v[186:189], v[126:129]
	v_mfma_f32_16x16x32_bf16 v[122:125], v[152:155], v[186:189], v[122:125]
	v_mfma_f32_16x16x32_bf16 v[118:121], v[144:147], v[204:207], v[118:121]
	v_mfma_f32_16x16x32_bf16 v[110:113], v[152:155], v[204:207], v[110:113]
	v_mfma_f32_16x16x32_bf16 v[102:105], v[144:147], v[214:217], v[102:105]
	v_mfma_f32_16x16x32_bf16 v[94:97], v[152:155], v[214:217], v[94:97]
	v_mfma_f32_16x16x32_bf16 v[86:89], v[144:147], v[222:225], v[86:89]
	v_mfma_f32_16x16x32_bf16 v[78:81], v[152:155], v[222:225], v[78:81]
	s_setprio 0
	s_setprio 1
	v_mfma_f32_16x16x32_bf16 v[114:117], v[156:159], v[182:185], v[114:117]
	v_mfma_f32_16x16x32_bf16 v[106:109], v[174:177], v[182:185], v[106:109]
	v_mfma_f32_16x16x32_bf16 v[98:101], v[156:159], v[190:193], v[98:101]
	v_mfma_f32_16x16x32_bf16 v[90:93], v[174:177], v[190:193], v[90:93]
	v_mfma_f32_16x16x32_bf16 v[82:85], v[156:159], v[210:213], v[82:85]
	v_mfma_f32_16x16x32_bf16 v[74:77], v[174:177], v[210:213], v[74:77]
	v_mfma_f32_16x16x32_bf16 v[70:73], v[156:159], v[218:221], v[70:73]
	v_mfma_f32_16x16x32_bf16 v[66:69], v[174:177], v[218:221], v[66:69]
	v_mfma_f32_16x16x32_bf16 v[114:117], v[170:173], v[186:189], v[114:117]
	v_mfma_f32_16x16x32_bf16 v[106:109], v[178:181], v[186:189], v[106:109]
	v_mfma_f32_16x16x32_bf16 v[98:101], v[170:173], v[204:207], v[98:101]
	v_mfma_f32_16x16x32_bf16 v[90:93], v[178:181], v[204:207], v[90:93]
	v_mfma_f32_16x16x32_bf16 v[82:85], v[170:173], v[214:217], v[82:85]
	v_mfma_f32_16x16x32_bf16 v[74:77], v[178:181], v[214:217], v[74:77]
	v_mfma_f32_16x16x32_bf16 v[70:73], v[170:173], v[222:225], v[70:73]
	v_mfma_f32_16x16x32_bf16 v[66:69], v[178:181], v[222:225], v[66:69]
	s_setprio 0
	s_barrier
	s_add_i32 s29, s29, s12
	s_mov_b32 m0, s29
	ds_read_b128 v[182:185], v169 offset:49152
	ds_read_b128 v[186:189], v169 offset:50176
	ds_read_b128 v[190:193], v169 offset:51200
	ds_read_b128 v[204:207], v169 offset:52224
	ds_read_b128 v[210:213], v169 offset:53248
	ds_read_b128 v[214:217], v169 offset:54272
	ds_read_b128 v[218:221], v169 offset:55296
	ds_read_b128 v[222:225], v169 offset:56320
	global_load_lds_dwordx4 v161, s[20:21]
	s_add_i32 m0, s29, 0x2000
	s_add_i32 s29, s30, s12
	global_load_lds_dwordx4 v195, s[20:21]
	s_add_u32 s20, s20, 0x40080
	s_addc_u32 s21, s21, 0
	s_mov_b32 m0, s29
	s_nop 0
	global_load_lds_dwordx4 v0, s[20:21]
	s_add_i32 m0, s29, 0x2000
	s_nop 0
	global_load_lds_dwordx4 v134, s[20:21]
	s_mov_b32 m0, s38
	s_nop 0
	global_load_lds_dwordx4 v201, s[62:63]
	s_mov_b32 m0, s39
	s_nop 0
	global_load_lds_dwordx4 v227, s[62:63]
	s_waitcnt vmcnt(8)
	s_waitcnt lgkmcnt(0)
	s_barrier
	s_setprio 1
	s_waitcnt lgkmcnt(0)
	v_mfma_f32_16x16x32_bf16 v[62:65], v[130:133], v[182:185], v[62:65]
	v_mfma_f32_16x16x32_bf16 v[58:61], v[148:151], v[182:185], v[58:61]
	v_mfma_f32_16x16x32_bf16 v[54:57], v[130:133], v[190:193], v[54:57]
	v_mfma_f32_16x16x32_bf16 v[46:49], v[148:151], v[190:193], v[46:49]
	v_mfma_f32_16x16x32_bf16 v[38:41], v[130:133], v[210:213], v[38:41]
	v_mfma_f32_16x16x32_bf16 v[30:33], v[148:151], v[210:213], v[30:33]
	v_mfma_f32_16x16x32_bf16 v[22:25], v[130:133], v[218:221], v[22:25]
	v_mfma_f32_16x16x32_bf16 v[14:17], v[148:151], v[218:221], v[14:17]
	v_mfma_f32_16x16x32_bf16 v[62:65], v[144:147], v[186:189], v[62:65]
	v_mfma_f32_16x16x32_bf16 v[58:61], v[152:155], v[186:189], v[58:61]
	v_mfma_f32_16x16x32_bf16 v[54:57], v[144:147], v[204:207], v[54:57]
	v_mfma_f32_16x16x32_bf16 v[46:49], v[152:155], v[204:207], v[46:49]
	v_mfma_f32_16x16x32_bf16 v[38:41], v[144:147], v[214:217], v[38:41]
	v_mfma_f32_16x16x32_bf16 v[30:33], v[152:155], v[214:217], v[30:33]
	v_mfma_f32_16x16x32_bf16 v[22:25], v[144:147], v[222:225], v[22:25]
	v_mfma_f32_16x16x32_bf16 v[14:17], v[152:155], v[222:225], v[14:17]
	s_setprio 0
	s_setprio 1
	v_mfma_f32_16x16x32_bf16 v[50:53], v[156:159], v[182:185], v[50:53]
	v_mfma_f32_16x16x32_bf16 v[42:45], v[174:177], v[182:185], v[42:45]
	v_mfma_f32_16x16x32_bf16 v[34:37], v[156:159], v[190:193], v[34:37]
	v_mfma_f32_16x16x32_bf16 v[26:29], v[174:177], v[190:193], v[26:29]
	v_mfma_f32_16x16x32_bf16 v[18:21], v[156:159], v[210:213], v[18:21]
	v_mfma_f32_16x16x32_bf16 v[10:13], v[174:177], v[210:213], v[10:13]
	v_mfma_f32_16x16x32_bf16 v[6:9], v[156:159], v[218:221], v[6:9]
	v_mfma_f32_16x16x32_bf16 v[2:5], v[174:177], v[218:221], v[2:5]
	v_mfma_f32_16x16x32_bf16 v[50:53], v[170:173], v[186:189], v[50:53]
	v_mfma_f32_16x16x32_bf16 v[42:45], v[178:181], v[186:189], v[42:45]
	v_mfma_f32_16x16x32_bf16 v[34:37], v[170:173], v[204:207], v[34:37]
	v_mfma_f32_16x16x32_bf16 v[26:29], v[178:181], v[204:207], v[26:29]
	v_mfma_f32_16x16x32_bf16 v[18:21], v[170:173], v[214:217], v[18:21]
	v_mfma_f32_16x16x32_bf16 v[10:13], v[178:181], v[214:217], v[10:13]
	v_mfma_f32_16x16x32_bf16 v[6:9], v[170:173], v[222:225], v[6:9]
	v_mfma_f32_16x16x32_bf16 v[2:5], v[178:181], v[222:225], v[2:5]
	s_setprio 0
	s_barrier
	s_add_i32 s46, s46, 2
	s_add_u32 s44, s44, 0x100
	s_addc_u32 s45, s45, 0
	s_add_u32 s60, s60, 0x100
	s_addc_u32 s61, s61, 0
	s_cmp_gt_u32 s46, 13
	s_cbranch_scc0 .LBB0_559
	s_and_b64 vcc, exec, s[4:5]
	s_cbranch_vccz .LBB0_562
	s_barrier

; #define PG8_STAGE(bufoff, gbase, voff) do { _Pragma("unroll") for (int _i = 0; _i < 2; ++_i) \
;         __builtin_amdgcn_global_load_lds((const gunsigned*)((const gchar*)(gbase) + (voff)[_i]), (LAS unsigned*)(lds + (bufoff) + ldsw + _i * 8192), 16, 0, 0); } while (0)
; #define PG8_LDA(dst, b, h) do { _Pragma("unroll") for (int m = 0; m < 4; ++m) _Pragma("unroll") for (int k = 0; k < 2; ++k) dst[m][k] = *(const LAS bf16x8*)(lds + PG8_SA(b, h) + aoff + m * 2048 + k * 1024); } while (0)
; #define PG8_LDB(dst, b, h) do { _Pragma("unroll") for (int n = 0; n < 2; ++n) _Pragma("unroll") for (int k = 0; k < 2; ++k) dst[n][k] = *(const LAS bf16x8*)(lds + PG8_SB(b, h) + boff + n * 2048 + k * 1024); } while (0)
; #define PG8_MMA(ai, bj, At, Bt) do { __builtin_amdgcn_s_setprio(1); _Pragma("unroll") for (int m = 0; m < 4; ++m) _Pragma("unroll") for (int n = 0; n < 2; ++n) _Pragma("unroll") for (int k = 0; k < 2; ++k) \
;         acc[ai][bj][m][n] = __builtin_amdgcn_mfma_f32_16x16x32_bf16(Bt[n][k], At[m][k], acc[ai][bj][m][n], 0, 0, 0); __builtin_amdgcn_s_setprio(0); } while (0)
; #define PG8_WAIT_V(n) asm volatile("s_waitcnt vmcnt(" #n ")" ::: "memory")
; #define PG8_WAIT_L(n) asm volatile("s_waitcnt lgkmcnt(" #n ")" ::: "memory")
; #define PG8_BAR __builtin_amdgcn_s_barrier()
; template <class Epi, class Sched>
; __device__ __forceinline__ void gemm_phase(LAS unsigned char* lds, const int tid, const Gemm g, const Sched& S, const Epi& E) {
;     ...
;         for (int t = 0; t < nt; t += 2) {
;             const bool last = (t == nt - 2);
;             const gchar* a1 = cA + (size_t)(t + 1) * kstep;
;             const gchar* a2 = last ? nA : cA + (size_t)(t + 2) * kstep; const gchar* b2 = last ? nB : cB + (size_t)(t + 2) * kstep;
;             const gchar* a3 = a2 + kstep; const gchar* b3 = b2 + kstep;
;             PG8_LDB(B0, 0, 0); PG8_LDB(B1, 0, 1); PG8_SCHED; PG8_LDA(At, 0, 0); PG8_STAGE(PG8_SA(1, 1), a1 + hstep, voffA);
;             PG8_WAIT_V(8); PG8_WAIT_L(0); PG8_BAR; PG8_MMA(0, 0, At, B0); PG8_MMA(0, 1, At, B1); PG8_BAR; PG8_SCHED;
;     ...
; #pragma unroll
;         for (int a = 0; a < 2; ++a)
; #pragma unroll
;             for (int b = 0; b < 2; ++b)
; #pragma unroll
;                 for (int m = 0; m < 4; ++m)
; #pragma unroll
;                     for (int n = 0; n < 2; ++n) acc[a][b][m][n] = (f32x4){0.f, 0.f, 0.f, 0.f};
;         cur = nxt; cA = nA; cB = nB; ++ui;
.LBB0_597:
	s_add_u32 s31, s20, 0x100
	v_mov_b32_e32 v2, 0
	s_addc_u32 s44, s21, 0
	s_mov_b32 s45, -2
	s_waitcnt lgkmcnt(0)
	v_mov_b32_e32 v3, v2
	v_mov_b32_e32 v4, v2
	v_mov_b32_e32 v5, v2
	v_mov_b32_e32 v6, v2
	v_mov_b32_e32 v7, v2
	v_mov_b32_e32 v8, v2
	v_mov_b32_e32 v9, v2
	v_mov_b32_e32 v18, v2
	v_mov_b32_e32 v19, v2
	v_mov_b32_e32 v20, v2
	v_mov_b32_e32 v21, v2
	v_mov_b32_e32 v22, v2
	v_mov_b32_e32 v23, v2
	v_mov_b32_e32 v24, v2
	v_mov_b32_e32 v25, v2
	v_mov_b32_e32 v34, v2
	v_mov_b32_e32 v35, v2
	v_mov_b32_e32 v36, v2
	v_mov_b32_e32 v37, v2
	v_mov_b32_e32 v38, v2
	v_mov_b32_e32 v39, v2
	v_mov_b32_e32 v40, v2
	v_mov_b32_e32 v41, v2
	v_mov_b32_e32 v50, v2
	v_mov_b32_e32 v51, v2
	v_mov_b32_e32 v52, v2
	v_mov_b32_e32 v53, v2
	v_mov_b32_e32 v54, v2
	v_mov_b32_e32 v55, v2
	v_mov_b32_e32 v56, v2
	v_mov_b32_e32 v57, v2
	v_mov_b32_e32 v10, v2
	v_mov_b32_e32 v11, v2
	v_mov_b32_e32 v12, v2
	v_mov_b32_e32 v13, v2
	v_mov_b32_e32 v14, v2
	v_mov_b32_e32 v15, v2
	v_mov_b32_e32 v16, v2
	v_mov_b32_e32 v17, v2
	v_mov_b32_e32 v26, v2
	v_mov_b32_e32 v27, v2
	v_mov_b32_e32 v28, v2
	v_mov_b32_e32 v29, v2
	v_mov_b32_e32 v30, v2
	v_mov_b32_e32 v31, v2
	v_mov_b32_e32 v32, v2
	v_mov_b32_e32 v33, v2
	v_mov_b32_e32 v42, v2
	v_mov_b32_e32 v43, v2
	v_mov_b32_e32 v44, v2
	v_mov_b32_e32 v45, v2
	v_mov_b32_e32 v46, v2
	v_mov_b32_e32 v47, v2
	v_mov_b32_e32 v48, v2
	v_mov_b32_e32 v49, v2
	v_mov_b32_e32 v58, v2
	v_mov_b32_e32 v59, v2
	v_mov_b32_e32 v60, v2
	v_mov_b32_e32 v61, v2
	v_mov_b32_e32 v62, v2
	v_mov_b32_e32 v63, v2
	v_mov_b32_e32 v64, v2
	v_mov_b32_e32 v65, v2
	v_mov_b32_e32 v66, v2
	v_mov_b32_e32 v67, v2
	v_mov_b32_e32 v68, v2
	v_mov_b32_e32 v69, v2
	v_mov_b32_e32 v70, v2
	v_mov_b32_e32 v71, v2
	v_mov_b32_e32 v72, v2
	v_mov_b32_e32 v73, v2
	s_waitcnt vmcnt(0)
	v_mov_b32_e32 v82, v2
	v_mov_b32_e32 v83, v2
	v_mov_b32_e32 v84, v2
	v_mov_b32_e32 v85, v2
	v_mov_b32_e32 v86, v2
	v_mov_b32_e32 v87, v2
	v_mov_b32_e32 v88, v2
	v_mov_b32_e32 v89, v2
	v_mov_b32_e32 v98, v2
	v_mov_b32_e32 v99, v2
	v_mov_b32_e32 v100, v2
	v_mov_b32_e32 v101, v2
	v_mov_b32_e32 v102, v2
	v_mov_b32_e32 v103, v2
	v_mov_b32_e32 v104, v2
	v_mov_b32_e32 v105, v2
	v_mov_b32_e32 v114, v2
	v_mov_b32_e32 v115, v2
	v_mov_b32_e32 v116, v2
	v_mov_b32_e32 v117, v2
	v_mov_b32_e32 v118, v2
	v_mov_b32_e32 v119, v2
	v_mov_b32_e32 v120, v2
	v_mov_b32_e32 v121, v2
	v_mov_b32_e32 v74, v2
	v_mov_b32_e32 v75, v2
	v_mov_b32_e32 v76, v2
	v_mov_b32_e32 v77, v2
	v_mov_b32_e32 v78, v2
	v_mov_b32_e32 v79, v2
	v_mov_b32_e32 v80, v2
	v_mov_b32_e32 v81, v2
	v_mov_b32_e32 v90, v2
	v_mov_b32_e32 v91, v2
	v_mov_b32_e32 v92, v2
	v_mov_b32_e32 v93, v2
	v_mov_b32_e32 v94, v2
	v_mov_b32_e32 v95, v2
	v_mov_b32_e32 v96, v2
	v_mov_b32_e32 v97, v2
	v_mov_b32_e32 v106, v2
	v_mov_b32_e32 v107, v2
	v_mov_b32_e32 v108, v2
	v_mov_b32_e32 v109, v2
	v_mov_b32_e32 v110, v2
	v_mov_b32_e32 v111, v2
	v_mov_b32_e32 v112, v2
	v_mov_b32_e32 v113, v2
	v_mov_b32_e32 v122, v2
	v_mov_b32_e32 v123, v2
	v_mov_b32_e32 v124, v2
	v_mov_b32_e32 v125, v2
	v_mov_b32_e32 v126, v2
	v_mov_b32_e32 v127, v2
	v_mov_b32_e32 v128, v2
	v_mov_b32_e32 v129, v2
	v_add_u32_e32 v221, 0x80, v0
	v_add_u32_e32 v223, 0x80, v182
	v_add_u32_e32 v225, 0x80, v178
	v_add_u32_e32 v227, 0x80, v180
.LBB0_598:
	s_add_u32 s20, s62, 0x100
	s_addc_u32 s21, s63, 0
	s_add_i32 s29, 0, 0x10000
	s_cmp_eq_u32 s45, 40
	s_cselect_b32 s73, s9, s21
	s_cselect_b32 s72, s8, s20
	s_cselect_b32 s67, s61, s44
	s_cselect_b32 s66, s60, s31
	s_add_i32 s48, 0, 0x14000
	v_add_u32_e32 v142, s29, v210
	v_add_u32_e32 v158, s48, v210
	ds_read_b128 v[130:133], v142
	ds_read_b128 v[134:137], v142 offset:1024
	ds_read_b128 v[138:141], v142 offset:2048
	ds_read_b128 v[142:145], v142 offset:3072
	ds_read_b128 v[146:149], v158
	ds_read_b128 v[150:153], v158 offset:1024
	ds_read_b128 v[154:157], v158 offset:2048
	ds_read_b128 v[158:161], v158 offset:3072
	s_add_i32 m0, s34, 0xc000
	ds_read_b128 v[162:165], v214
	ds_read_b128 v[166:169], v214 offset:1024
	ds_read_b128 v[170:173], v214 offset:2048
	ds_read_b128 v[174:177], v214 offset:3072
	ds_read_b128 v[188:191], v214 offset:4096
	ds_read_b128 v[192:195], v214 offset:5120
	ds_read_b128 v[204:207], v214 offset:6144
	ds_read_b128 v[216:219], v214 offset:7168
	global_load_lds_dwordx4 v186, s[62:63]
	s_add_i32 m0, s34, 0xe000
	s_nop 0
	global_load_lds_dwordx4 v184, s[62:63]
	s_waitcnt vmcnt(8)
	s_waitcnt lgkmcnt(0)
	s_barrier
	s_setprio 1
	s_waitcnt lgkmcnt(0)
	v_mfma_f32_16x16x32_bf16 v[126:129], v[130:133], v[162:165], v[126:129]
	v_mfma_f32_16x16x32_bf16 v[122:125], v[138:141], v[162:165], v[122:125]
	v_mfma_f32_16x16x32_bf16 v[110:113], v[130:133], v[170:173], v[110:113]
	v_mfma_f32_16x16x32_bf16 v[106:109], v[138:141], v[170:173], v[106:109]
	v_mfma_f32_16x16x32_bf16 v[94:97], v[130:133], v[188:191], v[94:97]
	v_mfma_f32_16x16x32_bf16 v[90:93], v[138:141], v[188:191], v[90:93]
	v_mfma_f32_16x16x32_bf16 v[78:81], v[130:133], v[204:207], v[78:81]
	v_mfma_f32_16x16x32_bf16 v[74:77], v[138:141], v[204:207], v[74:77]
	v_mfma_f32_16x16x32_bf16 v[126:129], v[134:137], v[166:169], v[126:129]
	v_mfma_f32_16x16x32_bf16 v[122:125], v[142:145], v[166:169], v[122:125]
	v_mfma_f32_16x16x32_bf16 v[110:113], v[134:137], v[174:177], v[110:113]
	v_mfma_f32_16x16x32_bf16 v[106:109], v[142:145], v[174:177], v[106:109]
	v_mfma_f32_16x16x32_bf16 v[94:97], v[134:137], v[192:195], v[94:97]
	v_mfma_f32_16x16x32_bf16 v[90:93], v[142:145], v[192:195], v[90:93]
	v_mfma_f32_16x16x32_bf16 v[78:81], v[134:137], v[216:219], v[78:81]
	v_mfma_f32_16x16x32_bf16 v[74:77], v[142:145], v[216:219], v[74:77]
	s_setprio 0
	s_setprio 1
	v_mfma_f32_16x16x32_bf16 v[118:121], v[146:149], v[162:165], v[118:121]
	v_mfma_f32_16x16x32_bf16 v[114:117], v[154:157], v[162:165], v[114:117]
	v_mfma_f32_16x16x32_bf16 v[102:105], v[146:149], v[170:173], v[102:105]
	v_mfma_f32_16x16x32_bf16 v[98:101], v[154:157], v[170:173], v[98:101]
	v_mfma_f32_16x16x32_bf16 v[86:89], v[146:149], v[188:191], v[86:89]
	v_mfma_f32_16x16x32_bf16 v[82:85], v[154:157], v[188:191], v[82:85]
	v_mfma_f32_16x16x32_bf16 v[70:73], v[146:149], v[204:207], v[70:73]
	v_mfma_f32_16x16x32_bf16 v[66:69], v[154:157], v[204:207], v[66:69]
	v_mfma_f32_16x16x32_bf16 v[118:121], v[150:153], v[166:169], v[118:121]
	v_mfma_f32_16x16x32_bf16 v[114:117], v[158:161], v[166:169], v[114:117]
	v_mfma_f32_16x16x32_bf16 v[102:105], v[150:153], v[174:177], v[102:105]
	v_mfma_f32_16x16x32_bf16 v[98:101], v[158:161], v[174:177], v[98:101]
	v_mfma_f32_16x16x32_bf16 v[86:89], v[150:153], v[192:195], v[86:89]
	v_mfma_f32_16x16x32_bf16 v[82:85], v[158:161], v[192:195], v[82:85]
	v_mfma_f32_16x16x32_bf16 v[70:73], v[150:153], v[216:219], v[70:73]
	v_mfma_f32_16x16x32_bf16 v[66:69], v[158:161], v[216:219], v[66:69]
	s_setprio 0
	s_barrier
; #define PG8_STAGE(bufoff, gbase, voff) do { _Pragma("unroll") for (int _i = 0; _i < 2; ++_i) \
;         __builtin_amdgcn_global_load_lds((const gunsigned*)((const gchar*)(gbase) + (voff)[_i]), (LAS unsigned*)(lds + (bufoff) + ldsw + _i * 8192), 16, 0, 0); } while (0)
; #define PG8_LDA(dst, b, h) do { _Pragma("unroll") for (int m = 0; m < 4; ++m) _Pragma("unroll") for (int k = 0; k < 2; ++k) dst[m][k] = *(const LAS bf16x8*)(lds + PG8_SA(b, h) + aoff + m * 2048 + k * 1024); } while (0)
; #define PG8_LDB(dst, b, h) do { _Pragma("unroll") for (int n = 0; n < 2; ++n) _Pragma("unroll") for (int k = 0; k < 2; ++k) dst[n][k] = *(const LAS bf16x8*)(lds + PG8_SB(b, h) + boff + n * 2048 + k * 1024); } while (0)
; #define PG8_MMA(ai, bj, At, Bt) do { __builtin_amdgcn_s_setprio(1); _Pragma("unroll") for (int m = 0; m < 4; ++m) _Pragma("unroll") for (int n = 0; n < 2; ++n) _Pragma("unroll") for (int k = 0; k < 2; ++k) \
;         acc[ai][bj][m][n] = __builtin_amdgcn_mfma_f32_16x16x32_bf16(Bt[n][k], At[m][k], acc[ai][bj][m][n], 0, 0, 0); __builtin_amdgcn_s_setprio(0); } while (0)
; #define PG8_WAIT_V(n) asm volatile("s_waitcnt vmcnt(" #n ")" ::: "memory")
; #define PG8_WAIT_L(n) asm volatile("s_waitcnt lgkmcnt(" #n ")" ::: "memory")
; #define PG8_BAR __builtin_amdgcn_s_barrier()
; #define PG8_SCHED __builtin_amdgcn_sched_barrier(0)
; template <class Epi, class Sched>
; __device__ __forceinline__ void gemm_phase(LAS unsigned char* lds, const int tid, const Gemm g, const Sched& S, const Epi& E) {
;     ...
;             PG8_LDA(At, 0, 1); PG8_STAGE(PG8_SB(0, 0), b2, voffB); PG8_STAGE(PG8_SB(0, 1), b2 + hstep, voffB); PG8_STAGE(PG8_SA(0, 0), a2, voffA);
;             PG8_WAIT_V(8); PG8_WAIT_L(0); PG8_BAR; PG8_MMA(1, 0, At, B0); PG8_MMA(1, 1, At, B1); PG8_BAR; PG8_SCHED;
;             PG8_LDB(B0, 1, 0); PG8_LDB(B1, 1, 1); PG8_SCHED; PG8_LDA(At, 1, 0); PG8_STAGE(PG8_SA(0, 1), a2 + hstep, voffA);
;             PG8_WAIT_V(8); PG8_WAIT_L(0); PG8_BAR; PG8_MMA(0, 0, At, B0); PG8_MMA(0, 1, At, B1); PG8_BAR; PG8_SCHED;
;             PG8_LDA(At, 1, 1); PG8_STAGE(PG8_SB(1, 0), b3, voffB); PG8_STAGE(PG8_SB(1, 1), b3 + hstep, voffB); PG8_STAGE(PG8_SA(1, 0), a3, voffA);
	s_add_i32 s29, s29, s15
	s_mov_b32 m0, s29
	ds_read_b128 v[162:165], v214 offset:16384
	ds_read_b128 v[166:169], v214 offset:17408
	ds_read_b128 v[170:173], v214 offset:18432
	ds_read_b128 v[174:177], v214 offset:19456
	ds_read_b128 v[188:191], v214 offset:20480
	ds_read_b128 v[192:195], v214 offset:21504
	ds_read_b128 v[204:207], v214 offset:22528
	ds_read_b128 v[216:219], v214 offset:23552
	global_load_lds_dwordx4 v0, s[66:67]
	s_add_i32 m0, s29, 0x2000
	s_add_u32 s46, s66, 0xb0000
	s_addc_u32 s47, s67, 0
	s_add_i32 s29, s48, s15
	global_load_lds_dwordx4 v182, s[66:67]
	s_mov_b32 m0, s29
	s_nop 0
	global_load_lds_dwordx4 v0, s[46:47]
	s_add_i32 m0, s29, 0x2000
	s_nop 0
	global_load_lds_dwordx4 v182, s[46:47]
	s_mov_b32 m0, s34
	s_nop 0
	global_load_lds_dwordx4 v178, s[72:73]
	s_mov_b32 m0, s12
	s_nop 0
	global_load_lds_dwordx4 v180, s[72:73]
	s_waitcnt vmcnt(8)
	s_waitcnt lgkmcnt(0)
	s_barrier
	s_setprio 1
	s_waitcnt lgkmcnt(0)
	v_mfma_f32_16x16x32_bf16 v[62:65], v[130:133], v[162:165], v[62:65]
	v_mfma_f32_16x16x32_bf16 v[58:61], v[138:141], v[162:165], v[58:61]
	v_mfma_f32_16x16x32_bf16 v[46:49], v[130:133], v[170:173], v[46:49]
	v_mfma_f32_16x16x32_bf16 v[42:45], v[138:141], v[170:173], v[42:45]
	v_mfma_f32_16x16x32_bf16 v[30:33], v[130:133], v[188:191], v[30:33]
	v_mfma_f32_16x16x32_bf16 v[26:29], v[138:141], v[188:191], v[26:29]
	v_mfma_f32_16x16x32_bf16 v[14:17], v[130:133], v[204:207], v[14:17]
	v_mfma_f32_16x16x32_bf16 v[10:13], v[138:141], v[204:207], v[10:13]
	v_mfma_f32_16x16x32_bf16 v[62:65], v[134:137], v[166:169], v[62:65]
	v_mfma_f32_16x16x32_bf16 v[58:61], v[142:145], v[166:169], v[58:61]
	v_mfma_f32_16x16x32_bf16 v[46:49], v[134:137], v[174:177], v[46:49]
	v_mfma_f32_16x16x32_bf16 v[42:45], v[142:145], v[174:177], v[42:45]
	v_mfma_f32_16x16x32_bf16 v[30:33], v[134:137], v[192:195], v[30:33]
	v_mfma_f32_16x16x32_bf16 v[26:29], v[142:145], v[192:195], v[26:29]
	v_mfma_f32_16x16x32_bf16 v[14:17], v[134:137], v[216:219], v[14:17]
	v_mfma_f32_16x16x32_bf16 v[10:13], v[142:145], v[216:219], v[10:13]
	s_setprio 0
	s_setprio 1
	v_mfma_f32_16x16x32_bf16 v[54:57], v[146:149], v[162:165], v[54:57]
	v_mfma_f32_16x16x32_bf16 v[50:53], v[154:157], v[162:165], v[50:53]
	v_mfma_f32_16x16x32_bf16 v[38:41], v[146:149], v[170:173], v[38:41]
	v_mfma_f32_16x16x32_bf16 v[34:37], v[154:157], v[170:173], v[34:37]
	v_mfma_f32_16x16x32_bf16 v[22:25], v[146:149], v[188:191], v[22:25]
	v_mfma_f32_16x16x32_bf16 v[18:21], v[154:157], v[188:191], v[18:21]
	v_mfma_f32_16x16x32_bf16 v[6:9], v[146:149], v[204:207], v[6:9]
	v_mfma_f32_16x16x32_bf16 v[2:5], v[154:157], v[204:207], v[2:5]
	v_mfma_f32_16x16x32_bf16 v[54:57], v[150:153], v[166:169], v[54:57]
	v_mfma_f32_16x16x32_bf16 v[50:53], v[158:161], v[166:169], v[50:53]
	v_mfma_f32_16x16x32_bf16 v[38:41], v[150:153], v[174:177], v[38:41]
	v_mfma_f32_16x16x32_bf16 v[34:37], v[158:161], v[174:177], v[34:37]
	v_mfma_f32_16x16x32_bf16 v[22:25], v[150:153], v[192:195], v[22:25]
	v_mfma_f32_16x16x32_bf16 v[18:21], v[158:161], v[192:195], v[18:21]
	v_mfma_f32_16x16x32_bf16 v[6:9], v[150:153], v[216:219], v[6:9]
	v_mfma_f32_16x16x32_bf16 v[2:5], v[158:161], v[216:219], v[2:5]
	s_setprio 0
	s_barrier
	s_add_i32 s29, 0, 0x18000
	s_add_i32 s48, 0, 0x1c000
	v_add_u32_e32 v142, s29, v210
	v_add_u32_e32 v158, s48, v210
	ds_read_b128 v[130:133], v142
	ds_read_b128 v[134:137], v142 offset:1024
	ds_read_b128 v[138:141], v142 offset:2048
	ds_read_b128 v[142:145], v142 offset:3072
	ds_read_b128 v[146:149], v158
	ds_read_b128 v[150:153], v158 offset:1024
	ds_read_b128 v[154:157], v158 offset:2048
	ds_read_b128 v[158:161], v158 offset:3072
	s_add_u32 s46, s72, 0xb0000
	s_addc_u32 s47, s73, 0
	s_mov_b32 m0, s35
	ds_read_b128 v[162:165], v214 offset:32768
	ds_read_b128 v[166:169], v214 offset:33792
	ds_read_b128 v[170:173], v214 offset:34816
	ds_read_b128 v[174:177], v214 offset:35840
	ds_read_b128 v[188:191], v214 offset:36864
	ds_read_b128 v[192:195], v214 offset:37888
	ds_read_b128 v[204:207], v214 offset:38912
	ds_read_b128 v[216:219], v214 offset:39936
	global_load_lds_dwordx4 v178, s[46:47]
	s_mov_b32 m0, s36
	s_nop 0
	global_load_lds_dwordx4 v180, s[46:47]
	s_waitcnt vmcnt(8)
	s_waitcnt lgkmcnt(0)
	s_barrier
; #define PG8_STAGE(bufoff, gbase, voff) do { _Pragma("unroll") for (int _i = 0; _i < 2; ++_i) \
;         __builtin_amdgcn_global_load_lds((const gunsigned*)((const gchar*)(gbase) + (voff)[_i]), (LAS unsigned*)(lds + (bufoff) + ldsw + _i * 8192), 16, 0, 0); } while (0)
; #define PG8_LDA(dst, b, h) do { _Pragma("unroll") for (int m = 0; m < 4; ++m) _Pragma("unroll") for (int k = 0; k < 2; ++k) dst[m][k] = *(const LAS bf16x8*)(lds + PG8_SA(b, h) + aoff + m * 2048 + k * 1024); } while (0)
; #define PG8_MMA(ai, bj, At, Bt) do { __builtin_amdgcn_s_setprio(1); _Pragma("unroll") for (int m = 0; m < 4; ++m) _Pragma("unroll") for (int n = 0; n < 2; ++n) _Pragma("unroll") for (int k = 0; k < 2; ++k) \
;         acc[ai][bj][m][n] = __builtin_amdgcn_mfma_f32_16x16x32_bf16(Bt[n][k], At[m][k], acc[ai][bj][m][n], 0, 0, 0); __builtin_amdgcn_s_setprio(0); } while (0)
; #define PG8_WAIT_V(n) asm volatile("s_waitcnt vmcnt(" #n ")" ::: "memory")
; #define PG8_WAIT_L(n) asm volatile("s_waitcnt lgkmcnt(" #n ")" ::: "memory")
; #define PG8_BAR __builtin_amdgcn_s_barrier()
; #define PG8_SCHED __builtin_amdgcn_sched_barrier(0)
; template <class Epi, class Sched>
; __device__ __forceinline__ void gemm_phase(LAS unsigned char* lds, const int tid, const Gemm g, const Sched& S, const Epi& E) {
;     ...
;             PG8_WAIT_V(8); PG8_WAIT_L(0); PG8_BAR; PG8_MMA(0, 0, At, B0); PG8_MMA(0, 1, At, B1); PG8_BAR; PG8_SCHED;
;             PG8_LDA(At, 1, 1); PG8_STAGE(PG8_SB(1, 0), b3, voffB); PG8_STAGE(PG8_SB(1, 1), b3 + hstep, voffB); PG8_STAGE(PG8_SA(1, 0), a3, voffA);
;             PG8_WAIT_V(8); PG8_WAIT_L(0); PG8_BAR; PG8_MMA(1, 0, At, B0); PG8_MMA(1, 1, At, B1); PG8_BAR; PG8_SCHED;
;         }
	s_setprio 1
	s_waitcnt lgkmcnt(0)
	v_mfma_f32_16x16x32_bf16 v[126:129], v[130:133], v[162:165], v[126:129]
	v_mfma_f32_16x16x32_bf16 v[122:125], v[138:141], v[162:165], v[122:125]
	v_mfma_f32_16x16x32_bf16 v[110:113], v[130:133], v[170:173], v[110:113]
	v_mfma_f32_16x16x32_bf16 v[106:109], v[138:141], v[170:173], v[106:109]
	v_mfma_f32_16x16x32_bf16 v[94:97], v[130:133], v[188:191], v[94:97]
	v_mfma_f32_16x16x32_bf16 v[90:93], v[138:141], v[188:191], v[90:93]
	v_mfma_f32_16x16x32_bf16 v[78:81], v[130:133], v[204:207], v[78:81]
	v_mfma_f32_16x16x32_bf16 v[74:77], v[138:141], v[204:207], v[74:77]
	v_mfma_f32_16x16x32_bf16 v[126:129], v[134:137], v[166:169], v[126:129]
	v_mfma_f32_16x16x32_bf16 v[122:125], v[142:145], v[166:169], v[122:125]
	v_mfma_f32_16x16x32_bf16 v[110:113], v[134:137], v[174:177], v[110:113]
	v_mfma_f32_16x16x32_bf16 v[106:109], v[142:145], v[174:177], v[106:109]
	v_mfma_f32_16x16x32_bf16 v[94:97], v[134:137], v[192:195], v[94:97]
	v_mfma_f32_16x16x32_bf16 v[90:93], v[142:145], v[192:195], v[90:93]
	v_mfma_f32_16x16x32_bf16 v[78:81], v[134:137], v[216:219], v[78:81]
	v_mfma_f32_16x16x32_bf16 v[74:77], v[142:145], v[216:219], v[74:77]
	s_setprio 0
	s_setprio 1
	v_mfma_f32_16x16x32_bf16 v[118:121], v[146:149], v[162:165], v[118:121]
	v_mfma_f32_16x16x32_bf16 v[114:117], v[154:157], v[162:165], v[114:117]
	v_mfma_f32_16x16x32_bf16 v[102:105], v[146:149], v[170:173], v[102:105]
	v_mfma_f32_16x16x32_bf16 v[98:101], v[154:157], v[170:173], v[98:101]
	v_mfma_f32_16x16x32_bf16 v[86:89], v[146:149], v[188:191], v[86:89]
	v_mfma_f32_16x16x32_bf16 v[82:85], v[154:157], v[188:191], v[82:85]
	v_mfma_f32_16x16x32_bf16 v[70:73], v[146:149], v[204:207], v[70:73]
	v_mfma_f32_16x16x32_bf16 v[66:69], v[154:157], v[204:207], v[66:69]
	v_mfma_f32_16x16x32_bf16 v[118:121], v[150:153], v[166:169], v[118:121]
	v_mfma_f32_16x16x32_bf16 v[114:117], v[158:161], v[166:169], v[114:117]
	v_mfma_f32_16x16x32_bf16 v[102:105], v[150:153], v[174:177], v[102:105]
	v_mfma_f32_16x16x32_bf16 v[98:101], v[158:161], v[174:177], v[98:101]
	v_mfma_f32_16x16x32_bf16 v[86:89], v[150:153], v[192:195], v[86:89]
	v_mfma_f32_16x16x32_bf16 v[82:85], v[158:161], v[192:195], v[82:85]
	v_mfma_f32_16x16x32_bf16 v[70:73], v[150:153], v[216:219], v[70:73]
	v_mfma_f32_16x16x32_bf16 v[66:69], v[158:161], v[216:219], v[66:69]
	s_setprio 0
	s_barrier
	s_add_i32 s29, s29, s15
	s_mov_b32 m0, s29
	ds_read_b128 v[162:165], v214 offset:49152
	ds_read_b128 v[166:169], v214 offset:50176
	ds_read_b128 v[170:173], v214 offset:51200
	ds_read_b128 v[174:177], v214 offset:52224
	ds_read_b128 v[188:191], v214 offset:53248
	ds_read_b128 v[192:195], v214 offset:54272
	ds_read_b128 v[204:207], v214 offset:55296
	ds_read_b128 v[216:219], v214 offset:56320
	global_load_lds_dwordx4 v221, s[66:67]
	s_add_i32 m0, s29, 0x2000
	s_add_u32 s46, s66, 0xb0080
	s_addc_u32 s47, s67, 0
	s_add_i32 s29, s48, s15
	global_load_lds_dwordx4 v223, s[66:67]
	s_mov_b32 m0, s29
	s_nop 0
	global_load_lds_dwordx4 v0, s[46:47]
	s_add_i32 m0, s29, 0x2000
	s_nop 0
	global_load_lds_dwordx4 v182, s[46:47]
	s_mov_b32 m0, s37
	s_nop 0
	global_load_lds_dwordx4 v225, s[72:73]
	s_mov_b32 m0, s38
	s_nop 0
	global_load_lds_dwordx4 v227, s[72:73]
	s_waitcnt vmcnt(8)
	s_waitcnt lgkmcnt(0)
	s_barrier
	s_setprio 1
	s_waitcnt lgkmcnt(0)
	v_mfma_f32_16x16x32_bf16 v[62:65], v[130:133], v[162:165], v[62:65]
	v_mfma_f32_16x16x32_bf16 v[58:61], v[138:141], v[162:165], v[58:61]
	v_mfma_f32_16x16x32_bf16 v[46:49], v[130:133], v[170:173], v[46:49]
	v_mfma_f32_16x16x32_bf16 v[42:45], v[138:141], v[170:173], v[42:45]
	v_mfma_f32_16x16x32_bf16 v[30:33], v[130:133], v[188:191], v[30:33]
	v_mfma_f32_16x16x32_bf16 v[26:29], v[138:141], v[188:191], v[26:29]
	v_mfma_f32_16x16x32_bf16 v[14:17], v[130:133], v[204:207], v[14:17]
	v_mfma_f32_16x16x32_bf16 v[10:13], v[138:141], v[204:207], v[10:13]
	v_mfma_f32_16x16x32_bf16 v[62:65], v[134:137], v[166:169], v[62:65]
	v_mfma_f32_16x16x32_bf16 v[58:61], v[142:145], v[166:169], v[58:61]
	v_mfma_f32_16x16x32_bf16 v[46:49], v[134:137], v[174:177], v[46:49]
	v_mfma_f32_16x16x32_bf16 v[42:45], v[142:145], v[174:177], v[42:45]
	v_mfma_f32_16x16x32_bf16 v[30:33], v[134:137], v[192:195], v[30:33]
	v_mfma_f32_16x16x32_bf16 v[26:29], v[142:145], v[192:195], v[26:29]
	v_mfma_f32_16x16x32_bf16 v[14:17], v[134:137], v[216:219], v[14:17]
	v_mfma_f32_16x16x32_bf16 v[10:13], v[142:145], v[216:219], v[10:13]
	s_setprio 0
	s_setprio 1
	v_mfma_f32_16x16x32_bf16 v[54:57], v[146:149], v[162:165], v[54:57]
	v_mfma_f32_16x16x32_bf16 v[50:53], v[154:157], v[162:165], v[50:53]
	v_mfma_f32_16x16x32_bf16 v[38:41], v[146:149], v[170:173], v[38:41]
	v_mfma_f32_16x16x32_bf16 v[34:37], v[154:157], v[170:173], v[34:37]
	v_mfma_f32_16x16x32_bf16 v[22:25], v[146:149], v[188:191], v[22:25]
	v_mfma_f32_16x16x32_bf16 v[18:21], v[154:157], v[188:191], v[18:21]
	v_mfma_f32_16x16x32_bf16 v[6:9], v[146:149], v[204:207], v[6:9]
	v_mfma_f32_16x16x32_bf16 v[2:5], v[154:157], v[204:207], v[2:5]
	v_mfma_f32_16x16x32_bf16 v[54:57], v[150:153], v[166:169], v[54:57]
	v_mfma_f32_16x16x32_bf16 v[50:53], v[158:161], v[166:169], v[50:53]
	v_mfma_f32_16x16x32_bf16 v[38:41], v[150:153], v[174:177], v[38:41]
	v_mfma_f32_16x16x32_bf16 v[34:37], v[158:161], v[174:177], v[34:37]
	v_mfma_f32_16x16x32_bf16 v[22:25], v[150:153], v[192:195], v[22:25]
	v_mfma_f32_16x16x32_bf16 v[18:21], v[158:161], v[192:195], v[18:21]
	v_mfma_f32_16x16x32_bf16 v[6:9], v[150:153], v[216:219], v[6:9]
	v_mfma_f32_16x16x32_bf16 v[2:5], v[158:161], v[216:219], v[2:5]
	s_setprio 0
	s_barrier
	s_add_i32 s45, s45, 2
	s_add_u32 s31, s31, 0x100
	s_addc_u32 s44, s44, 0
	s_cmp_gt_u32 s45, 41
	s_mov_b64 s[62:63], s[20:21]
	s_cbranch_scc0 .LBB0_598
	s_and_b64 vcc, exec, s[58:59]
	s_cbranch_vccz .LBB0_601
	s_barrier

;     __device__ bool next(int i, Unit& u) const { if (!b.next(i / 3, u)) return false; u.pz = i % 3; return true; }
; #define PG8_STAGE(bufoff, gbase, voff) do { _Pragma("unroll") for (int _i = 0; _i < 2; ++_i) \
;         __builtin_amdgcn_global_load_lds((const gunsigned*)((const gchar*)(gbase) + (voff)[_i]), (LAS unsigned*)(lds + (bufoff) + ldsw + _i * 8192), 16, 0, 0); } while (0)
; #define PG8_LDA(dst, b, h) do { _Pragma("unroll") for (int m = 0; m < 4; ++m) _Pragma("unroll") for (int k = 0; k < 2; ++k) dst[m][k] = *(const LAS bf16x8*)(lds + PG8_SA(b, h) + aoff + m * 2048 + k * 1024); } while (0)
; #define PG8_LDB(dst, b, h) do { _Pragma("unroll") for (int n = 0; n < 2; ++n) _Pragma("unroll") for (int k = 0; k < 2; ++k) dst[n][k] = *(const LAS bf16x8*)(lds + PG8_SB(b, h) + boff + n * 2048 + k * 1024); } while (0)
; #define PG8_WAIT_V(n) asm volatile("s_waitcnt vmcnt(" #n ")" ::: "memory")
; #define PG8_WAIT_L(n) asm volatile("s_waitcnt lgkmcnt(" #n ")" ::: "memory")
; template <class Epi, class Sched>
; __device__ __forceinline__ void gemm_phase(LAS unsigned char* lds, const int tid, const Gemm g, const Sched& S, const Epi& E) {
;     ...
;         const bool has_next = S.next(ui + 1, nxt);
;         const gchar* nA = has_next ? (const gchar*)g.A + (size_t)nxt.pm * tstep + (size_t)nxt.pz * g.zA : cA;
;         const gchar* nB = has_next ? (const gchar*)g.Bt + (size_t)nxt.pn * tstep + (size_t)nxt.pz * g.zB : cB;
;         for (int t = 0; t < nt; t += 2) {
;             const bool last = (t == nt - 2);
;             const gchar* a1 = cA + (size_t)(t + 1) * kstep;
;             const gchar* a2 = last ? nA : cA + (size_t)(t + 2) * kstep; const gchar* b2 = last ? nB : cB + (size_t)(t + 2) * kstep;
;             const gchar* a3 = a2 + kstep; const gchar* b3 = b2 + kstep;
;             PG8_LDB(B0, 0, 0); PG8_LDB(B1, 0, 1); PG8_SCHED; PG8_LDA(At, 0, 0); PG8_STAGE(PG8_SA(1, 1), a1 + hstep, voffA);
;             PG8_WAIT_V(8); PG8_WAIT_L(0); PG8_BAR; PG8_MMA(0, 0, At, B0); PG8_MMA(0, 1, At, B1); PG8_BAR; PG8_SCHED;
;     ...
; #pragma unroll
;         for (int a = 0; a < 2; ++a)
; #pragma unroll
;             for (int b = 0; b < 2; ++b)
; #pragma unroll
;                 for (int m = 0; m < 4; ++m)
; #pragma unroll
;                     for (int n = 0; n < 2; ++n) acc[a][b][m][n] = (f32x4){0.f, 0.f, 0.f, 0.f};
;         cur = nxt; cA = nA; cB = nB; ++ui;
.LBB0_646:
	s_ashr_i32 s9, s8, 31
	s_lshl_b64 s[10:11], s[8:9], 19
	s_add_u32 s10, s86, s10
	s_addc_u32 s11, s87, s11
	s_and_b64 s[16:17], s[2:3], exec
	s_cselect_b32 s9, s11, s59
	s_cselect_b32 s37, s10, s58
	s_ashr_i32 s7, s6, 31
	s_lshl_b64 s[16:17], s[6:7], 19
	s_add_u32 s16, s84, s16
	s_addc_u32 s17, s85, s17
	s_and_b64 s[38:39], s[2:3], exec
	s_cselect_b32 s7, s17, s21
	s_cselect_b32 s38, s16, s20
	s_add_u32 s39, s20, 0x100
	s_addc_u32 s40, s21, 0
	s_add_u32 s58, s58, 0x40080
	v_mov_b32_e32 v2, 0
	s_addc_u32 s59, s59, 0
	s_mov_b32 s41, -2
	v_mov_b32_e32 v3, v2
	v_mov_b32_e32 v4, v2
	v_mov_b32_e32 v5, v2
	v_mov_b32_e32 v6, v2
	v_mov_b32_e32 v7, v2
	v_mov_b32_e32 v8, v2
	v_mov_b32_e32 v9, v2
	v_mov_b32_e32 v18, v2
	v_mov_b32_e32 v19, v2
	v_mov_b32_e32 v20, v2
	v_mov_b32_e32 v21, v2
	v_mov_b32_e32 v22, v2
	v_mov_b32_e32 v23, v2
	v_mov_b32_e32 v24, v2
	v_mov_b32_e32 v25, v2
	v_mov_b32_e32 v34, v2
	v_mov_b32_e32 v35, v2
	v_mov_b32_e32 v36, v2
	v_mov_b32_e32 v37, v2
	v_mov_b32_e32 v38, v2
	v_mov_b32_e32 v39, v2
	v_mov_b32_e32 v40, v2
	v_mov_b32_e32 v41, v2
	v_mov_b32_e32 v50, v2
	v_mov_b32_e32 v51, v2
	v_mov_b32_e32 v52, v2
	v_mov_b32_e32 v53, v2
	v_mov_b32_e32 v54, v2
	v_mov_b32_e32 v55, v2
	v_mov_b32_e32 v56, v2
	v_mov_b32_e32 v57, v2
	v_mov_b32_e32 v10, v2
	v_mov_b32_e32 v11, v2
	v_mov_b32_e32 v12, v2
	v_mov_b32_e32 v13, v2
	v_mov_b32_e32 v14, v2
	v_mov_b32_e32 v15, v2
	v_mov_b32_e32 v16, v2
	v_mov_b32_e32 v17, v2
	v_mov_b32_e32 v26, v2
	v_mov_b32_e32 v27, v2
	v_mov_b32_e32 v28, v2
	v_mov_b32_e32 v29, v2
	v_mov_b32_e32 v30, v2
	v_mov_b32_e32 v31, v2
	v_mov_b32_e32 v32, v2
	v_mov_b32_e32 v33, v2
	v_mov_b32_e32 v42, v2
	v_mov_b32_e32 v43, v2
	v_mov_b32_e32 v44, v2
	v_mov_b32_e32 v45, v2
	v_mov_b32_e32 v46, v2
	v_mov_b32_e32 v47, v2
	v_mov_b32_e32 v48, v2
	v_mov_b32_e32 v49, v2
	v_mov_b32_e32 v58, v2
	v_mov_b32_e32 v59, v2
	v_mov_b32_e32 v60, v2
	v_mov_b32_e32 v61, v2
	v_mov_b32_e32 v62, v2
	v_mov_b32_e32 v63, v2
	v_mov_b32_e32 v64, v2
	v_mov_b32_e32 v65, v2
	v_mov_b32_e32 v66, v2
	v_mov_b32_e32 v67, v2
	v_mov_b32_e32 v68, v2
	v_mov_b32_e32 v69, v2
	v_mov_b32_e32 v70, v2
	v_mov_b32_e32 v71, v2
	v_mov_b32_e32 v72, v2
	v_mov_b32_e32 v73, v2
	v_mov_b32_e32 v82, v2
	v_mov_b32_e32 v83, v2
	v_mov_b32_e32 v84, v2
	v_mov_b32_e32 v85, v2
	v_mov_b32_e32 v86, v2
	v_mov_b32_e32 v87, v2
	v_mov_b32_e32 v88, v2
	v_mov_b32_e32 v89, v2
	v_mov_b32_e32 v98, v2
	v_mov_b32_e32 v99, v2
	v_mov_b32_e32 v100, v2
	v_mov_b32_e32 v101, v2
	v_mov_b32_e32 v102, v2
	v_mov_b32_e32 v103, v2
	v_mov_b32_e32 v104, v2
	v_mov_b32_e32 v105, v2
	v_mov_b32_e32 v114, v2
	v_mov_b32_e32 v115, v2
	v_mov_b32_e32 v116, v2
	v_mov_b32_e32 v117, v2
	v_mov_b32_e32 v118, v2
	v_mov_b32_e32 v119, v2
	v_mov_b32_e32 v120, v2
	v_mov_b32_e32 v121, v2
	v_mov_b32_e32 v74, v2
	v_mov_b32_e32 v75, v2
	v_mov_b32_e32 v76, v2
	v_mov_b32_e32 v77, v2
	v_mov_b32_e32 v78, v2
	v_mov_b32_e32 v79, v2
	v_mov_b32_e32 v80, v2
	v_mov_b32_e32 v81, v2
	v_mov_b32_e32 v90, v2
	v_mov_b32_e32 v91, v2
	v_mov_b32_e32 v92, v2
	v_mov_b32_e32 v93, v2
	v_mov_b32_e32 v94, v2
	v_mov_b32_e32 v95, v2
	v_mov_b32_e32 v96, v2
	v_mov_b32_e32 v97, v2
	v_mov_b32_e32 v106, v2
	v_mov_b32_e32 v107, v2
	v_mov_b32_e32 v108, v2
	v_mov_b32_e32 v109, v2
	v_mov_b32_e32 v110, v2
	v_mov_b32_e32 v111, v2
	v_mov_b32_e32 v112, v2
	v_mov_b32_e32 v113, v2
	v_mov_b32_e32 v122, v2
	v_mov_b32_e32 v123, v2
	v_mov_b32_e32 v124, v2
	v_mov_b32_e32 v125, v2
	v_mov_b32_e32 v126, v2
	v_mov_b32_e32 v127, v2
	v_mov_b32_e32 v128, v2
	v_mov_b32_e32 v129, v2
	v_add_u32_e32 v141, 0x80, v0
	v_add_u32_e32 v195, 0x80, v130
	v_add_u32_e32 v221, 0x80, v134
	v_add_u32_e32 v223, 0x80, v132
.LBB0_647:
	s_add_u32 s20, s58, 0xfffc0080
	s_addc_u32 s21, s59, -1
	s_add_i32 s42, 0, 0x10000
	s_cmp_eq_u32 s41, 12
	s_cselect_b32 s61, s9, s21
	s_cselect_b32 s60, s37, s20
	v_add_u32_e32 v140, s42, v143
	s_cselect_b32 s21, s7, s40
	s_cselect_b32 s20, s38, s39
	s_add_i32 s44, 0, 0x14000
	ds_read_b128 v[146:149], v140
	ds_read_b128 v[150:153], v140 offset:1024
	ds_read_b128 v[154:157], v140 offset:2048
	ds_read_b128 v[158:161], v140 offset:3072
	v_add_u32_e32 v140, s44, v143
	ds_read_b128 v[162:165], v140
	ds_read_b128 v[166:169], v140 offset:1024
	ds_read_b128 v[170:173], v140 offset:2048
	ds_read_b128 v[174:177], v140 offset:3072
	s_add_i32 m0, s23, 0xc000
	ds_read_b128 v[178:181], v145
	ds_read_b128 v[182:185], v145 offset:1024
	ds_read_b128 v[186:189], v145 offset:2048
	ds_read_b128 v[190:193], v145 offset:3072
	ds_read_b128 v[204:207], v145 offset:4096
	ds_read_b128 v[208:211], v145 offset:5120
	ds_read_b128 v[212:215], v145 offset:6144
	ds_read_b128 v[216:219], v145 offset:7168
	global_load_lds_dwordx4 v138, s[58:59]
	s_add_i32 m0, s23, 0xe000
	s_nop 0
	global_load_lds_dwordx4 v136, s[58:59]
	s_waitcnt vmcnt(8)
	s_waitcnt lgkmcnt(0)
	s_barrier
; #define PG8_STAGE(bufoff, gbase, voff) do { _Pragma("unroll") for (int _i = 0; _i < 2; ++_i) \
;         __builtin_amdgcn_global_load_lds((const gunsigned*)((const gchar*)(gbase) + (voff)[_i]), (LAS unsigned*)(lds + (bufoff) + ldsw + _i * 8192), 16, 0, 0); } while (0)
; #define PG8_LDA(dst, b, h) do { _Pragma("unroll") for (int m = 0; m < 4; ++m) _Pragma("unroll") for (int k = 0; k < 2; ++k) dst[m][k] = *(const LAS bf16x8*)(lds + PG8_SA(b, h) + aoff + m * 2048 + k * 1024); } while (0)
; #define PG8_LDB(dst, b, h) do { _Pragma("unroll") for (int n = 0; n < 2; ++n) _Pragma("unroll") for (int k = 0; k < 2; ++k) dst[n][k] = *(const LAS bf16x8*)(lds + PG8_SB(b, h) + boff + n * 2048 + k * 1024); } while (0)
; #define PG8_MMA(ai, bj, At, Bt) do { __builtin_amdgcn_s_setprio(1); _Pragma("unroll") for (int m = 0; m < 4; ++m) _Pragma("unroll") for (int n = 0; n < 2; ++n) _Pragma("unroll") for (int k = 0; k < 2; ++k) \
;         acc[ai][bj][m][n] = __builtin_amdgcn_mfma_f32_16x16x32_bf16(Bt[n][k], At[m][k], acc[ai][bj][m][n], 0, 0, 0); __builtin_amdgcn_s_setprio(0); } while (0)
; #define PG8_WAIT_V(n) asm volatile("s_waitcnt vmcnt(" #n ")" ::: "memory")
; #define PG8_WAIT_L(n) asm volatile("s_waitcnt lgkmcnt(" #n ")" ::: "memory")
; #define PG8_BAR __builtin_amdgcn_s_barrier()
; #define PG8_SCHED __builtin_amdgcn_sched_barrier(0)
; template <class Epi, class Sched>
; __device__ __forceinline__ void gemm_phase(LAS unsigned char* lds, const int tid, const Gemm g, const Sched& S, const Epi& E) {
;     ...
;             PG8_WAIT_V(8); PG8_WAIT_L(0); PG8_BAR; PG8_MMA(0, 0, At, B0); PG8_MMA(0, 1, At, B1); PG8_BAR; PG8_SCHED;
;             PG8_LDA(At, 0, 1); PG8_STAGE(PG8_SB(0, 0), b2, voffB); PG8_STAGE(PG8_SB(0, 1), b2 + hstep, voffB); PG8_STAGE(PG8_SA(0, 0), a2, voffA);
;             PG8_WAIT_V(8); PG8_WAIT_L(0); PG8_BAR; PG8_MMA(1, 0, At, B0); PG8_MMA(1, 1, At, B1); PG8_BAR; PG8_SCHED;
;             PG8_LDB(B0, 1, 0); PG8_LDB(B1, 1, 1); PG8_SCHED; PG8_LDA(At, 1, 0); PG8_STAGE(PG8_SA(0, 1), a2 + hstep, voffA);
	s_setprio 1
	s_waitcnt lgkmcnt(0)
	v_mfma_f32_16x16x32_bf16 v[126:129], v[146:149], v[178:181], v[126:129]
	v_mfma_f32_16x16x32_bf16 v[122:125], v[154:157], v[178:181], v[122:125]
	v_mfma_f32_16x16x32_bf16 v[110:113], v[146:149], v[186:189], v[110:113]
	v_mfma_f32_16x16x32_bf16 v[106:109], v[154:157], v[186:189], v[106:109]
	v_mfma_f32_16x16x32_bf16 v[94:97], v[146:149], v[204:207], v[94:97]
	v_mfma_f32_16x16x32_bf16 v[90:93], v[154:157], v[204:207], v[90:93]
	v_mfma_f32_16x16x32_bf16 v[78:81], v[146:149], v[212:215], v[78:81]
	v_mfma_f32_16x16x32_bf16 v[74:77], v[154:157], v[212:215], v[74:77]
	v_mfma_f32_16x16x32_bf16 v[126:129], v[150:153], v[182:185], v[126:129]
	v_mfma_f32_16x16x32_bf16 v[122:125], v[158:161], v[182:185], v[122:125]
	v_mfma_f32_16x16x32_bf16 v[110:113], v[150:153], v[190:193], v[110:113]
	v_mfma_f32_16x16x32_bf16 v[106:109], v[158:161], v[190:193], v[106:109]
	v_mfma_f32_16x16x32_bf16 v[94:97], v[150:153], v[208:211], v[94:97]
	v_mfma_f32_16x16x32_bf16 v[90:93], v[158:161], v[208:211], v[90:93]
	v_mfma_f32_16x16x32_bf16 v[78:81], v[150:153], v[216:219], v[78:81]
	v_mfma_f32_16x16x32_bf16 v[74:77], v[158:161], v[216:219], v[74:77]
	s_setprio 0
	s_setprio 1
	v_mfma_f32_16x16x32_bf16 v[118:121], v[162:165], v[178:181], v[118:121]
	v_mfma_f32_16x16x32_bf16 v[114:117], v[170:173], v[178:181], v[114:117]
	v_mfma_f32_16x16x32_bf16 v[102:105], v[162:165], v[186:189], v[102:105]
	v_mfma_f32_16x16x32_bf16 v[98:101], v[170:173], v[186:189], v[98:101]
	v_mfma_f32_16x16x32_bf16 v[86:89], v[162:165], v[204:207], v[86:89]
	v_mfma_f32_16x16x32_bf16 v[82:85], v[170:173], v[204:207], v[82:85]
	v_mfma_f32_16x16x32_bf16 v[70:73], v[162:165], v[212:215], v[70:73]
	v_mfma_f32_16x16x32_bf16 v[66:69], v[170:173], v[212:215], v[66:69]
	v_mfma_f32_16x16x32_bf16 v[118:121], v[166:169], v[182:185], v[118:121]
	v_mfma_f32_16x16x32_bf16 v[114:117], v[174:177], v[182:185], v[114:117]
	v_mfma_f32_16x16x32_bf16 v[102:105], v[166:169], v[190:193], v[102:105]
	v_mfma_f32_16x16x32_bf16 v[98:101], v[174:177], v[190:193], v[98:101]
	v_mfma_f32_16x16x32_bf16 v[86:89], v[166:169], v[208:211], v[86:89]
	v_mfma_f32_16x16x32_bf16 v[82:85], v[174:177], v[208:211], v[82:85]
	v_mfma_f32_16x16x32_bf16 v[70:73], v[166:169], v[216:219], v[70:73]
	v_mfma_f32_16x16x32_bf16 v[66:69], v[174:177], v[216:219], v[66:69]
	s_setprio 0
	s_barrier
	s_add_i32 s42, s42, s12
	s_mov_b32 m0, s42
	ds_read_b128 v[178:181], v145 offset:16384
	ds_read_b128 v[182:185], v145 offset:17408
	ds_read_b128 v[186:189], v145 offset:18432
	ds_read_b128 v[190:193], v145 offset:19456
	ds_read_b128 v[204:207], v145 offset:20480
	ds_read_b128 v[208:211], v145 offset:21504
	ds_read_b128 v[212:215], v145 offset:22528
	ds_read_b128 v[216:219], v145 offset:23552
	global_load_lds_dwordx4 v0, s[20:21]
	s_add_i32 m0, s42, 0x2000
	s_add_u32 s42, s20, 0x40000
	s_addc_u32 s43, s21, 0
	s_add_i32 s44, s44, s12
	global_load_lds_dwordx4 v130, s[20:21]
	s_mov_b32 m0, s44
	s_nop 0
	global_load_lds_dwordx4 v0, s[42:43]
	s_add_i32 m0, s44, 0x2000
	s_nop 0
	global_load_lds_dwordx4 v130, s[42:43]
	s_mov_b32 m0, s23
	s_nop 0
	global_load_lds_dwordx4 v134, s[60:61]
	s_mov_b32 m0, s24
	s_nop 0
	global_load_lds_dwordx4 v132, s[60:61]
	s_waitcnt vmcnt(8)
	s_waitcnt lgkmcnt(0)
	s_barrier
	s_setprio 1
	s_waitcnt lgkmcnt(0)
	v_mfma_f32_16x16x32_bf16 v[62:65], v[146:149], v[178:181], v[62:65]
	v_mfma_f32_16x16x32_bf16 v[58:61], v[154:157], v[178:181], v[58:61]
	v_mfma_f32_16x16x32_bf16 v[46:49], v[146:149], v[186:189], v[46:49]
	v_mfma_f32_16x16x32_bf16 v[42:45], v[154:157], v[186:189], v[42:45]
	v_mfma_f32_16x16x32_bf16 v[30:33], v[146:149], v[204:207], v[30:33]
	v_mfma_f32_16x16x32_bf16 v[26:29], v[154:157], v[204:207], v[26:29]
	v_mfma_f32_16x16x32_bf16 v[14:17], v[146:149], v[212:215], v[14:17]
	v_mfma_f32_16x16x32_bf16 v[10:13], v[154:157], v[212:215], v[10:13]
	v_mfma_f32_16x16x32_bf16 v[62:65], v[150:153], v[182:185], v[62:65]
	v_mfma_f32_16x16x32_bf16 v[58:61], v[158:161], v[182:185], v[58:61]
	v_mfma_f32_16x16x32_bf16 v[46:49], v[150:153], v[190:193], v[46:49]
	v_mfma_f32_16x16x32_bf16 v[42:45], v[158:161], v[190:193], v[42:45]
	v_mfma_f32_16x16x32_bf16 v[30:33], v[150:153], v[208:211], v[30:33]
	v_mfma_f32_16x16x32_bf16 v[26:29], v[158:161], v[208:211], v[26:29]
	v_mfma_f32_16x16x32_bf16 v[14:17], v[150:153], v[216:219], v[14:17]
	v_mfma_f32_16x16x32_bf16 v[10:13], v[158:161], v[216:219], v[10:13]
	s_setprio 0
	s_setprio 1
	v_mfma_f32_16x16x32_bf16 v[54:57], v[162:165], v[178:181], v[54:57]
	v_mfma_f32_16x16x32_bf16 v[50:53], v[170:173], v[178:181], v[50:53]
	v_mfma_f32_16x16x32_bf16 v[38:41], v[162:165], v[186:189], v[38:41]
	v_mfma_f32_16x16x32_bf16 v[34:37], v[170:173], v[186:189], v[34:37]
	v_mfma_f32_16x16x32_bf16 v[22:25], v[162:165], v[204:207], v[22:25]
	v_mfma_f32_16x16x32_bf16 v[18:21], v[170:173], v[204:207], v[18:21]
	v_mfma_f32_16x16x32_bf16 v[6:9], v[162:165], v[212:215], v[6:9]
	v_mfma_f32_16x16x32_bf16 v[2:5], v[170:173], v[212:215], v[2:5]
	v_mfma_f32_16x16x32_bf16 v[54:57], v[166:169], v[182:185], v[54:57]
	v_mfma_f32_16x16x32_bf16 v[50:53], v[174:177], v[182:185], v[50:53]
	v_mfma_f32_16x16x32_bf16 v[38:41], v[166:169], v[190:193], v[38:41]
	v_mfma_f32_16x16x32_bf16 v[34:37], v[174:177], v[190:193], v[34:37]
	v_mfma_f32_16x16x32_bf16 v[22:25], v[166:169], v[208:211], v[22:25]
	v_mfma_f32_16x16x32_bf16 v[18:21], v[174:177], v[208:211], v[18:21]
	v_mfma_f32_16x16x32_bf16 v[6:9], v[166:169], v[216:219], v[6:9]
	v_mfma_f32_16x16x32_bf16 v[2:5], v[174:177], v[216:219], v[2:5]
	s_setprio 0
	s_barrier
; #define PG8_STAGE(bufoff, gbase, voff) do { _Pragma("unroll") for (int _i = 0; _i < 2; ++_i) \
;         __builtin_amdgcn_global_load_lds((const gunsigned*)((const gchar*)(gbase) + (voff)[_i]), (LAS unsigned*)(lds + (bufoff) + ldsw + _i * 8192), 16, 0, 0); } while (0)
; #define PG8_LDA(dst, b, h) do { _Pragma("unroll") for (int m = 0; m < 4; ++m) _Pragma("unroll") for (int k = 0; k < 2; ++k) dst[m][k] = *(const LAS bf16x8*)(lds + PG8_SA(b, h) + aoff + m * 2048 + k * 1024); } while (0)
; #define PG8_LDB(dst, b, h) do { _Pragma("unroll") for (int n = 0; n < 2; ++n) _Pragma("unroll") for (int k = 0; k < 2; ++k) dst[n][k] = *(const LAS bf16x8*)(lds + PG8_SB(b, h) + boff + n * 2048 + k * 1024); } while (0)
; #define PG8_WAIT_V(n) asm volatile("s_waitcnt vmcnt(" #n ")" ::: "memory")
; template <class Epi, class Sched>
; __device__ __forceinline__ void gemm_phase(LAS unsigned char* lds, const int tid, const Gemm g, const Sched& S, const Epi& E) {
;     ...
;         for (int t = 0; t < nt; t += 2) {
;             const bool last = (t == nt - 2);
;             const gchar* a1 = cA + (size_t)(t + 1) * kstep;
;             const gchar* a2 = last ? nA : cA + (size_t)(t + 2) * kstep; const gchar* b2 = last ? nB : cB + (size_t)(t + 2) * kstep;
;             const gchar* a3 = a2 + kstep; const gchar* b3 = b2 + kstep;
;             PG8_LDB(B0, 0, 0); PG8_LDB(B1, 0, 1); PG8_SCHED; PG8_LDA(At, 0, 0); PG8_STAGE(PG8_SA(1, 1), a1 + hstep, voffA);
;             PG8_WAIT_V(8); PG8_WAIT_L(0); PG8_BAR; PG8_MMA(0, 0, At, B0); PG8_MMA(0, 1, At, B1); PG8_BAR; PG8_SCHED;
;             PG8_LDA(At, 0, 1); PG8_STAGE(PG8_SB(0, 0), b2, voffB); PG8_STAGE(PG8_SB(0, 1), b2 + hstep, voffB); PG8_STAGE(PG8_SA(0, 0), a2, voffA);
;             PG8_WAIT_V(8); PG8_WAIT_L(0); PG8_BAR; PG8_MMA(1, 0, At, B0); PG8_MMA(1, 1, At, B1); PG8_BAR; PG8_SCHED;
;             PG8_LDB(B0, 1, 0); PG8_LDB(B1, 1, 1); PG8_SCHED; PG8_LDA(At, 1, 0); PG8_STAGE(PG8_SA(0, 1), a2 + hstep, voffA);
;             PG8_WAIT_V(8); PG8_WAIT_L(0); PG8_BAR; PG8_MMA(0, 0, At, B0); PG8_MMA(0, 1, At, B1); PG8_BAR; PG8_SCHED;
;             PG8_LDA(At, 1, 1); PG8_STAGE(PG8_SB(1, 0), b3, voffB); PG8_STAGE(PG8_SB(1, 1), b3 + hstep, voffB); PG8_STAGE(PG8_SA(1, 0), a3, voffA);
;             PG8_WAIT_V(8); PG8_WAIT_L(0); PG8_BAR; PG8_MMA(1, 0, At, B0); PG8_MMA(1, 1, At, B1); PG8_BAR; PG8_SCHED;
;         }
	s_add_i32 s44, 0, 0x18000
	s_add_i32 s45, 0, 0x1c000
	v_add_u32_e32 v158, s44, v143
	v_add_u32_e32 v174, s45, v143
	ds_read_b128 v[146:149], v158
	ds_read_b128 v[150:153], v158 offset:1024
	ds_read_b128 v[154:157], v158 offset:2048
	ds_read_b128 v[158:161], v158 offset:3072
	ds_read_b128 v[162:165], v174
	ds_read_b128 v[166:169], v174 offset:1024
	ds_read_b128 v[170:173], v174 offset:2048
	ds_read_b128 v[174:177], v174 offset:3072
	s_add_u32 s42, s60, 0x40000
	s_addc_u32 s43, s61, 0
	s_mov_b32 m0, s29
	ds_read_b128 v[178:181], v145 offset:32768
	ds_read_b128 v[182:185], v145 offset:33792
	ds_read_b128 v[186:189], v145 offset:34816
	ds_read_b128 v[190:193], v145 offset:35840
	ds_read_b128 v[204:207], v145 offset:36864
	ds_read_b128 v[208:211], v145 offset:37888
	ds_read_b128 v[212:215], v145 offset:38912
	ds_read_b128 v[216:219], v145 offset:39936
	global_load_lds_dwordx4 v134, s[42:43]
	s_mov_b32 m0, s30
	s_nop 0
	global_load_lds_dwordx4 v132, s[42:43]
	s_waitcnt vmcnt(8)
	s_waitcnt lgkmcnt(0)
	s_barrier
	s_setprio 1
	s_waitcnt lgkmcnt(0)
	v_mfma_f32_16x16x32_bf16 v[126:129], v[146:149], v[178:181], v[126:129]
	v_mfma_f32_16x16x32_bf16 v[122:125], v[154:157], v[178:181], v[122:125]
	v_mfma_f32_16x16x32_bf16 v[110:113], v[146:149], v[186:189], v[110:113]
	v_mfma_f32_16x16x32_bf16 v[106:109], v[154:157], v[186:189], v[106:109]
	v_mfma_f32_16x16x32_bf16 v[94:97], v[146:149], v[204:207], v[94:97]
	v_mfma_f32_16x16x32_bf16 v[90:93], v[154:157], v[204:207], v[90:93]
	v_mfma_f32_16x16x32_bf16 v[78:81], v[146:149], v[212:215], v[78:81]
	v_mfma_f32_16x16x32_bf16 v[74:77], v[154:157], v[212:215], v[74:77]
	v_mfma_f32_16x16x32_bf16 v[126:129], v[150:153], v[182:185], v[126:129]
	v_mfma_f32_16x16x32_bf16 v[122:125], v[158:161], v[182:185], v[122:125]
	v_mfma_f32_16x16x32_bf16 v[110:113], v[150:153], v[190:193], v[110:113]
	v_mfma_f32_16x16x32_bf16 v[106:109], v[158:161], v[190:193], v[106:109]
	v_mfma_f32_16x16x32_bf16 v[94:97], v[150:153], v[208:211], v[94:97]
	v_mfma_f32_16x16x32_bf16 v[90:93], v[158:161], v[208:211], v[90:93]
	v_mfma_f32_16x16x32_bf16 v[78:81], v[150:153], v[216:219], v[78:81]
	v_mfma_f32_16x16x32_bf16 v[74:77], v[158:161], v[216:219], v[74:77]
	s_setprio 0
	s_setprio 1
	v_mfma_f32_16x16x32_bf16 v[118:121], v[162:165], v[178:181], v[118:121]
	v_mfma_f32_16x16x32_bf16 v[114:117], v[170:173], v[178:181], v[114:117]
	v_mfma_f32_16x16x32_bf16 v[102:105], v[162:165], v[186:189], v[102:105]
	v_mfma_f32_16x16x32_bf16 v[98:101], v[170:173], v[186:189], v[98:101]
	v_mfma_f32_16x16x32_bf16 v[86:89], v[162:165], v[204:207], v[86:89]
	v_mfma_f32_16x16x32_bf16 v[82:85], v[170:173], v[204:207], v[82:85]
	v_mfma_f32_16x16x32_bf16 v[70:73], v[162:165], v[212:215], v[70:73]
	v_mfma_f32_16x16x32_bf16 v[66:69], v[170:173], v[212:215], v[66:69]
	v_mfma_f32_16x16x32_bf16 v[118:121], v[166:169], v[182:185], v[118:121]
	v_mfma_f32_16x16x32_bf16 v[114:117], v[174:177], v[182:185], v[114:117]
	v_mfma_f32_16x16x32_bf16 v[102:105], v[166:169], v[190:193], v[102:105]
	v_mfma_f32_16x16x32_bf16 v[98:101], v[174:177], v[190:193], v[98:101]
	v_mfma_f32_16x16x32_bf16 v[86:89], v[166:169], v[208:211], v[86:89]
	v_mfma_f32_16x16x32_bf16 v[82:85], v[174:177], v[208:211], v[82:85]
	v_mfma_f32_16x16x32_bf16 v[70:73], v[166:169], v[216:219], v[70:73]
	v_mfma_f32_16x16x32_bf16 v[66:69], v[174:177], v[216:219], v[66:69]
	s_setprio 0
	s_barrier
	s_add_i32 s42, s44, s12
	s_mov_b32 m0, s42
	ds_read_b128 v[178:181], v145 offset:49152
	ds_read_b128 v[182:185], v145 offset:50176
	ds_read_b128 v[186:189], v145 offset:51200
	ds_read_b128 v[190:193], v145 offset:52224
	ds_read_b128 v[204:207], v145 offset:53248
	ds_read_b128 v[208:211], v145 offset:54272
	ds_read_b128 v[212:215], v145 offset:55296
	ds_read_b128 v[216:219], v145 offset:56320
	global_load_lds_dwordx4 v141, s[20:21]
	s_add_i32 m0, s42, 0x2000
	s_add_i32 s42, s45, s12
	global_load_lds_dwordx4 v195, s[20:21]
	s_add_u32 s20, s20, 0x40080
	s_addc_u32 s21, s21, 0
	s_mov_b32 m0, s42
	s_nop 0
	global_load_lds_dwordx4 v0, s[20:21]
	s_add_i32 m0, s42, 0x2000
	s_nop 0
	global_load_lds_dwordx4 v130, s[20:21]
	s_mov_b32 m0, s31
	s_nop 0
	global_load_lds_dwordx4 v221, s[60:61]
	s_mov_b32 m0, s34
	s_nop 0
	global_load_lds_dwordx4 v223, s[60:61]
	s_waitcnt vmcnt(8)
	s_waitcnt lgkmcnt(0)
	s_barrier
	s_setprio 1
	s_waitcnt lgkmcnt(0)
	v_mfma_f32_16x16x32_bf16 v[62:65], v[146:149], v[178:181], v[62:65]
	v_mfma_f32_16x16x32_bf16 v[58:61], v[154:157], v[178:181], v[58:61]
	v_mfma_f32_16x16x32_bf16 v[46:49], v[146:149], v[186:189], v[46:49]
	v_mfma_f32_16x16x32_bf16 v[42:45], v[154:157], v[186:189], v[42:45]
	v_mfma_f32_16x16x32_bf16 v[30:33], v[146:149], v[204:207], v[30:33]
	v_mfma_f32_16x16x32_bf16 v[26:29], v[154:157], v[204:207], v[26:29]
	v_mfma_f32_16x16x32_bf16 v[14:17], v[146:149], v[212:215], v[14:17]
	v_mfma_f32_16x16x32_bf16 v[10:13], v[154:157], v[212:215], v[10:13]
	v_mfma_f32_16x16x32_bf16 v[62:65], v[150:153], v[182:185], v[62:65]
	v_mfma_f32_16x16x32_bf16 v[58:61], v[158:161], v[182:185], v[58:61]
	v_mfma_f32_16x16x32_bf16 v[46:49], v[150:153], v[190:193], v[46:49]
	v_mfma_f32_16x16x32_bf16 v[42:45], v[158:161], v[190:193], v[42:45]
	v_mfma_f32_16x16x32_bf16 v[30:33], v[150:153], v[208:211], v[30:33]
	v_mfma_f32_16x16x32_bf16 v[26:29], v[158:161], v[208:211], v[26:29]
	v_mfma_f32_16x16x32_bf16 v[14:17], v[150:153], v[216:219], v[14:17]
	v_mfma_f32_16x16x32_bf16 v[10:13], v[158:161], v[216:219], v[10:13]
	s_setprio 0
	s_setprio 1
	v_mfma_f32_16x16x32_bf16 v[54:57], v[162:165], v[178:181], v[54:57]
	v_mfma_f32_16x16x32_bf16 v[50:53], v[170:173], v[178:181], v[50:53]
	v_mfma_f32_16x16x32_bf16 v[38:41], v[162:165], v[186:189], v[38:41]
	v_mfma_f32_16x16x32_bf16 v[34:37], v[170:173], v[186:189], v[34:37]
	v_mfma_f32_16x16x32_bf16 v[22:25], v[162:165], v[204:207], v[22:25]
	v_mfma_f32_16x16x32_bf16 v[18:21], v[170:173], v[204:207], v[18:21]
	v_mfma_f32_16x16x32_bf16 v[6:9], v[162:165], v[212:215], v[6:9]
	v_mfma_f32_16x16x32_bf16 v[2:5], v[170:173], v[212:215], v[2:5]
	v_mfma_f32_16x16x32_bf16 v[54:57], v[166:169], v[182:185], v[54:57]
	v_mfma_f32_16x16x32_bf16 v[50:53], v[174:177], v[182:185], v[50:53]
	v_mfma_f32_16x16x32_bf16 v[38:41], v[166:169], v[190:193], v[38:41]
	v_mfma_f32_16x16x32_bf16 v[34:37], v[174:177], v[190:193], v[34:37]
	v_mfma_f32_16x16x32_bf16 v[22:25], v[166:169], v[208:211], v[22:25]
	v_mfma_f32_16x16x32_bf16 v[18:21], v[174:177], v[208:211], v[18:21]
	v_mfma_f32_16x16x32_bf16 v[6:9], v[166:169], v[216:219], v[6:9]
	v_mfma_f32_16x16x32_bf16 v[2:5], v[174:177], v[216:219], v[2:5]
	s_setprio 0
	s_barrier
	s_add_i32 s41, s41, 2
	s_add_u32 s39, s39, 0x100
	s_addc_u32 s40, s40, 0
	s_add_u32 s58, s58, 0x100
	s_addc_u32 s59, s59, 0
	s_cmp_gt_u32 s41, 13
	s_cbranch_scc0 .LBB0_647
	s_and_b64 vcc, exec, s[4:5]
	s_cbranch_vccz .LBB0_650
	s_barrier
